# batched out-proj epilogue (DPP row reductions) on top of v10
# speedup vs baseline: 1.0711x; 1.0020x over previous
; DI int fresh_tid() { int t = threadIdx.x; asm volatile("" : "+v"(t)); return t; }
; DI f32x16 zero16() { f32x16 z; for (int i = 0; i < 16; ++i) z[i] = 0.f; return z; }
; template <bool AT>
; DI void gemm_main(f32x16 (&acc)[2][4], const u16* __restrict__ R, int ldr, const u16* __restrict__ Cm, int ldc,
;                   const u16* __restrict__ RT, int ldrt, int K, char* smem, int tid) {
;   constexpr int STG = 2 * 256 * 72;
;   u16* S0 = (u16*)smem;
;   const int lane = tid & 63, wave = tid >> 6, wr = wave >> 1, wc = wave & 1;
;   const int li = lane & 31, g = lane >> 5;
;   u32x4 rr[4], cr[4];
; #pragma unroll
;   for (int a = 0; a < 2; ++a)
; #pragma unroll
;     for (int b = 0; b < 4; ++b) acc[a][b] = zero16();
;   const int nk = K / 64;
; #pragma unroll
;   for (int i = 0; i < 4; ++i) {
;     const int cid = tid + NT * i;
;     const int row = cid >> 3, kc = cid & 7;
;     if (AT) {
;       const int kr = cid >> 5, tc = cid & 31;
;       rr[i] = *(const u32x4*)(RT + (size_t)kr * ldrt + tc * 8);
;     } else {
;       rr[i] = *(const u32x4*)(R + (size_t)row * ldr + kc * 8);
;     }
;     cr[i] = *(const u32x4*)(Cm + (size_t)row * ldc + kc * 8);
;   }
;   for (int kt = -1; kt < nk; ++kt) {
;     if (kt + 1 < nk) {
;       const int ks1 = kt + 1;
;       u16* Rs = S0 + (ks1 & 1) * STG;
;       u16* Cs = Rs + 256 * 72;
; #pragma unroll
;       for (int i = 0; i < 4; ++i) {
;         const int cid = tid + NT * i;
;         const int row = cid >> 3, kc = cid & 7;
;         if (AT && ks1 < 8) {
;           const int kr = cid >> 5, tc = cid & 31;
;           *(u32x4*)(Rs + kr * 264 + tc * 8) = rr[i];
;         } else {
;           *(u32x4*)(Rs + row * 72 + kc * 8) = rr[i];
;         }
;         *(u32x4*)(Cs + row * 72 + kc * 8) = cr[i];
;       }
;     }
; DI void gemm_out_tile(const P& p, int l, int id, char* smem) {
;   const int bx = id & 255, xcd = bx & 7, s = bx >> 3;
;   const int mt = xcd * 8 + (s & 7), nt = s >> 3;
;   const int m0 = mt * 256, n0 = nt * 256;
;   const int tid = fresh_tid(), lane = tid & 63, wave = tid >> 6, wr = wave >> 1, wc = wave & 1;
;   const int li = lane & 31, g = lane >> 5;
;   f32x16 acc[2][4];
;   const u16* R = p.Ya + (size_t)m0 * 512 - 512;
;   const u16* Cm = p.WoutT + (size_t)l * 1024 * 1024 + (size_t)n0 * 1024;
;   const u16* RT = p.YhT + m0;
.LBB0_530:
	s_and_b32 s6, s22, 56
	s_bfe_u32 s7, s23, 0x30003
	s_or_b32 s28, s6, s7
	s_bfe_u32 s24, s23, 0x20006
	s_lshl_b32 s25, s28, 8
	s_lshl_b32 s6, s28, 18
	s_add_u32 s6, s12, s6
	s_addc_u32 s7, s13, 0
	s_lshl_b32 s26, s24, 19
	s_add_u32 s26, s8, s26
	v_mov_b32_e32 v148, v198
	s_addc_u32 s27, s9, 0
	s_lshl_b32 s28, s28, 9
	s_barrier
	s_add_u32 s28, s14, s28
	v_lshlrev_b32_e32 v6, 4, v148
	v_ashrrev_i32_e32 v138, 3, v148
	s_addc_u32 s29, s15, 0
	v_and_b32_e32 v188, 0x1f0, v6
	v_ashrrev_i32_e32 v139, 31, v138
	v_and_b32_e32 v136, 0x70, v6
	v_mov_b32_e32 v137, v189
	v_add_u32_e32 v8, 0x200, v148
	v_add_u32_e32 v16, 0x400, v148
	v_add_u32_e32 v24, 0x600, v148
	v_lshl_add_u64 v[146:147], s[28:29], 0, v[188:189]
	v_ashrrev_i32_e32 v169, 5, v148
	v_lshlrev_b64 v[4:5], 11, v[138:139]
	v_lshl_add_u64 v[28:29], s[26:27], 0, v[136:137]
	v_ashrrev_i32_e32 v140, 3, v8
	v_ashrrev_i32_e32 v142, 3, v16
	v_ashrrev_i32_e32 v144, 3, v24
	v_mad_i64_i32 v[0:1], s[28:29], v169, s67, v[146:147]
	v_lshl_add_u64 v[128:129], v[28:29], 0, v[4:5]
	v_ashrrev_i32_e32 v170, 5, v8
	v_ashrrev_i32_e32 v141, 31, v140
	v_ashrrev_i32_e32 v171, 5, v16
	v_ashrrev_i32_e32 v143, 31, v142
	v_ashrrev_i32_e32 v172, 5, v24
	v_ashrrev_i32_e32 v145, 31, v144
	global_load_dwordx4 v[0:3], v[0:1], off
	v_lshlrev_b64 v[12:13], 11, v[140:141]
	global_load_dwordx4 v[4:7], v[128:129], off
	v_lshlrev_b64 v[20:21], 11, v[142:143]
	v_lshlrev_b64 v[30:31], 11, v[144:145]
	v_add_u32_e32 v32, 64, v169
	v_add_u32_e32 v40, 64, v170
	v_add_u32_e32 v48, 64, v171
	v_add_u32_e32 v56, 64, v172
	v_mad_i64_i32 v[8:9], s[26:27], v170, s67, v[146:147]
	v_lshl_add_u64 v[130:131], v[28:29], 0, v[12:13]
	v_mad_i64_i32 v[16:17], s[26:27], v171, s67, v[146:147]
	v_lshl_add_u64 v[132:133], v[28:29], 0, v[20:21]
	v_mad_i64_i32 v[24:25], s[26:27], v172, s67, v[146:147]
	v_lshl_add_u64 v[134:135], v[28:29], 0, v[30:31]
	v_mad_i64_i32 v[32:33], s[26:27], v32, s67, v[146:147]
	v_mad_i64_i32 v[40:41], s[26:27], v40, s67, v[146:147]
	v_mad_i64_i32 v[48:49], s[26:27], v48, s67, v[146:147]
	v_mad_i64_i32 v[56:57], s[26:27], v56, s67, v[146:147]
	global_load_dwordx4 v[8:11], v[8:9], off
	v_and_b32_e32 v149, 31, v148
	global_load_dwordx4 v[12:15], v[130:131], off
	global_load_dwordx4 v[20:23], v[132:133], off
	global_load_dwordx4 v[28:31], v[134:135], off
	v_lshlrev_b32_e32 v64, 1, v148
	global_load_dwordx4 v[16:19], v[16:17], off
	v_and_or_b32 v168, v64, s40, v149
	global_load_dwordx4 v[24:27], v[24:25], off
	s_nop 0
	global_load_dwordx4 v[32:35], v[32:33], off
	s_nop 0
	global_load_dwordx4 v[36:39], v[128:129], off offset:128
	s_nop 0
	global_load_dwordx4 v[40:43], v[40:41], off
	s_nop 0
	global_load_dwordx4 v[44:47], v[130:131], off offset:128
	s_nop 0
	global_load_dwordx4 v[48:51], v[48:49], off
	s_nop 0
	global_load_dwordx4 v[52:55], v[132:133], off offset:128
	s_nop 0
	global_load_dwordx4 v[56:59], v[56:57], off
	s_nop 0
	global_load_dwordx4 v[60:63], v[134:135], off offset:128
	v_add_u32_e32 v64, 0, v136
	v_add_u32_e32 v65, 0, v188
	v_mul_lo_u32 v66, v169, s39
	v_mul_lo_u32 v162, v138, s94
	v_add_u32_e32 v177, v65, v66
	v_add_u32_e32 v156, v64, v162
	s_add_i32 s26, 0, 0x12000
	v_bfe_u32 v150, v148, 5, 1
	v_and_b32_e32 v160, 0xffffff80, v148
	v_mul_lo_u32 v163, v140, s94
	v_mul_lo_u32 v164, v142, s94
	v_mul_lo_u32 v165, v144, s94
	v_add_u32_e32 v157, v64, v163
	v_add_u32_e32 v158, v64, v164
	v_add_u32_e32 v159, v64, v165
	v_mul_u32_u24_e32 v181, 0x1080, v150
	v_lshlrev_b32_e32 v161, 4, v150
	v_add_u32_e32 v166, 0, v161
	v_mad_u32_u24 v151, v168, s94, v166
	v_add_u32_e32 v240, 0x80, v172
	v_mad_i64_i32 v[244:245], s[28:29], v240, s67, v[146:147]
	v_lshlrev_b64 v[138:139], 10, v[138:139]
	v_lshlrev_b64 v[142:143], 10, v[142:143]
	v_lshlrev_b64 v[140:141], 10, v[140:141]
	v_lshlrev_b64 v[144:145], 10, v[144:145]
	s_waitcnt vmcnt(15)
	ds_write_b128 v177, v[0:3]
	v_mul_lo_u32 v0, v170, s39
	s_waitcnt vmcnt(14)
	ds_write_b128 v156, v[4:7] offset:36864
	v_mul_lo_u32 v1, v171, s39
	v_mul_lo_u32 v2, v172, s39
	v_add_u32_e32 v3, s90, v136
	v_add_u32_e32 v4, s26, v188
	v_add_u32_e32 v178, v65, v0
	v_add_u32_e32 v179, v65, v1
	v_add_u32_e32 v180, v65, v2
	v_add_u32_e32 v173, v4, v66
	v_add_u32_e32 v152, v3, v162
	v_add_u32_e32 v174, v4, v0
	v_add_u32_e32 v153, v3, v163
	v_add_u32_e32 v175, v4, v1
	v_add_u32_e32 v154, v3, v164
	v_add_u32_e32 v176, v4, v2
	v_add_u32_e32 v155, v3, v165
	v_add_u32_e32 v0, 0, v160
	v_lshlrev_b32_e32 v188, 1, v149
	v_add3_u32 v167, v0, v188, v181
	v_add_u32_e32 v160, s26, v160
	s_waitcnt vmcnt(13)
	ds_write_b128 v178, v[8:11]
	s_waitcnt vmcnt(12)
	ds_write_b128 v157, v[12:15] offset:36864
	s_waitcnt vmcnt(9)
	ds_write_b128 v179, v[16:19]
	ds_write_b128 v158, v[20:23] offset:36864
	s_waitcnt vmcnt(8)
	ds_write_b128 v180, v[24:27]
	ds_write_b128 v159, v[28:31] offset:36864
	s_waitcnt lgkmcnt(0)
	s_barrier
; template <bool AT>
; DI void gemm_main(f32x16 (&acc)[2][4], const u16* __restrict__ R, int ldr, const u16* __restrict__ Cm, int ldc,
;                   const u16* __restrict__ RT, int ldrt, int K, char* smem, int tid) {
;     ...
;     if (kt + 1 < nk) {
;       const int ks1 = kt + 1;
;       u16* Rs = S0 + (ks1 & 1) * STG;
;       u16* Cs = Rs + 256 * 72;
; #pragma unroll
;       for (int i = 0; i < 4; ++i) {
;         const int cid = tid + NT * i;
;         const int row = cid >> 3, kc = cid & 7;
;         if (AT && ks1 < 8) {
;           const int kr = cid >> 5, tc = cid & 31;
;           *(u32x4*)(Rs + kr * 264 + tc * 8) = rr[i];
;         } else {
;           *(u32x4*)(Rs + row * 72 + kc * 8) = rr[i];
;         }
;         *(u32x4*)(Cs + row * 72 + kc * 8) = cr[i];
;       }
;     }
;     if (kt + 2 < nk) {
;       const int kn = kt + 2;
; #pragma unroll
;       for (int i = 0; i < 4; ++i) {
;         const int cid = tid + NT * i;
;         const int row = cid >> 3, kc = cid & 7;
;         if (AT && kn < 8) {
;           const int kr = cid >> 5, tc = cid & 31;
;           rr[i] = *(const u32x4*)(RT + (size_t)(kn * 64 + kr) * ldrt + tc * 8);
;         } else {
;           rr[i] = *(const u32x4*)(R + (size_t)row * ldr + kn * 64 + kc * 8);
;         }
;         cr[i] = *(const u32x4*)(Cm + (size_t)row * ldc + kn * 64 + kc * 8);
;       }
;     }
;     __builtin_amdgcn_sched_barrier(0x38F);
;     if (kt >= 0) {
;       const u16* Rs = S0 + (kt & 1) * STG;
;       const u16* Cs = Rs + 256 * 72;
;       const u16* RTs = Rs;
; #pragma unroll
;       for (int ks = 0; ks < 4; ++ks) {
;         bf16x8 rf[2];
; #pragma unroll
;         for (int rb = 0; rb < 2; ++rb) {
;           if (AT && kt < 8) {
;             const u16* src = RTs + (16 * ks + 8 * g) * 264 + 64 * wr + 32 * rb + li;
;             bf16x8 t;
; #pragma unroll
;             for (int j = 0; j < 8; ++j) t[j] = (short)src[j * 264];
;             rf[rb] = t;
;           } else {
;             rf[rb] = *(const bf16x8*)(Rs + (64 * wr + 32 * rb + li) * 72 + 16 * ks + 8 * g);
;           }
;         }
; #pragma unroll
;         for (int cb = 0; cb < 4; ++cb) {
;           const bf16x8 cfv = *(const bf16x8*)(Cs + (128 * wc + 32 * cb + li) * 72 + 16 * ks + 8 * g);
; #pragma unroll
;           for (int rb = 0; rb < 2; ++rb) acc[rb][cb] = MFMA(rf[rb], cfv, acc[rb][cb]);
;         }
;       }
;     }
	s_waitcnt vmcnt(7)
	ds_write_b128 v173, v[32:35]
	s_waitcnt vmcnt(6)
	ds_write_b128 v152, v[36:39]
	s_waitcnt vmcnt(5)
	ds_write_b128 v174, v[40:43]
	s_waitcnt vmcnt(4)
	ds_write_b128 v153, v[44:47]
	s_waitcnt vmcnt(3)
	ds_write_b128 v175, v[48:51]
	s_waitcnt vmcnt(2)
	ds_write_b128 v154, v[52:55]
	s_waitcnt vmcnt(1)
	ds_write_b128 v176, v[56:59]
	s_waitcnt vmcnt(0)
	ds_write_b128 v155, v[60:63]
	ds_read_u16 v0, v167
	ds_read_u16 v1, v167 offset:528
	ds_read_u16 v2, v167 offset:1056
	ds_read_u16 v3, v167 offset:1584
	ds_read_u16 v4, v167 offset:1648
	ds_read_u16 v5, v167 offset:1120
	ds_read_u16 v6, v167 offset:592
	ds_read_u16 v7, v167 offset:64
	ds_read_u16 v8, v167 offset:2112
	ds_read_u16 v9, v167 offset:2640
	ds_read_u16 v10, v167 offset:3168
	ds_read_u16 v11, v167 offset:3696
	ds_read_u16 v12, v167 offset:3760
	ds_read_u16 v13, v167 offset:3232
	ds_read_u16 v14, v167 offset:2704
	ds_read_u16 v15, v167 offset:2176
	s_waitcnt lgkmcnt(4)
	v_perm_b32 v19, v11, v10, s19
	v_perm_b32 v18, v9, v8, s19
	v_perm_b32 v17, v3, v2, s19
	v_perm_b32 v16, v1, v0, s19
	s_waitcnt lgkmcnt(2)
	v_perm_b32 v23, v12, v13, s19
	s_waitcnt lgkmcnt(0)
	v_perm_b32 v22, v14, v15, s19
	v_perm_b32 v21, v4, v5, s19
	v_perm_b32 v20, v6, v7, s19
	ds_read_b128 v[0:3], v151 offset:36864
	ds_read_b128 v[182:185], v151 offset:36896
	ds_read_b128 v[24:27], v151 offset:41472
	ds_read_b128 v[190:193], v151 offset:41504
	s_waitcnt lgkmcnt(1)
	v_mfma_f32_32x32x16_bf16 v[96:111], v[16:19], v[24:27], 0
	v_mfma_f32_32x32x16_bf16 v[32:47], v[20:23], v[24:27], 0
	ds_read_b128 v[24:27], v151 offset:46080
	ds_read_b128 v[194:197], v151 offset:46112
	s_waitcnt lgkmcnt(1)
	v_mfma_f32_32x32x16_bf16 v[112:127], v[16:19], v[24:27], 0
	v_mfma_f32_32x32x16_bf16 v[48:63], v[20:23], v[24:27], 0
	ds_read_b128 v[24:27], v151 offset:50688
	ds_read_b128 v[220:223], v151 offset:50720
	ds_read_u16 v186, v167 offset:8448
	ds_read_u16 v187, v167 offset:8976
	ds_read_u16 v224, v167 offset:9504
	ds_read_u16 v225, v167 offset:10032
	ds_read_u16 v228, v167 offset:10096
	ds_read_u16 v229, v167 offset:9568
	ds_read_u16 v232, v167 offset:9040
	ds_read_u16 v233, v167 offset:8512
	ds_read_u16 v226, v167 offset:10560
	ds_read_u16 v230, v167 offset:11088
	ds_read_u16 v227, v167 offset:11616
	ds_read_u16 v231, v167 offset:12144
	ds_read_u16 v234, v167 offset:12208
	ds_read_u16 v235, v167 offset:11680
	ds_read_u16 v236, v167 offset:11152
	ds_read_u16 v237, v167 offset:10624
	s_waitcnt lgkmcnt(4)
	v_perm_b32 v227, v231, v227, s19
	v_perm_b32 v226, v230, v226, s19
	v_perm_b32 v225, v225, v224, s19
	v_perm_b32 v224, v187, v186, s19
	s_waitcnt lgkmcnt(2)
	v_perm_b32 v231, v234, v235, s19
	v_mfma_f32_32x32x16_bf16 v[64:79], v[16:19], v[0:3], 0
	s_waitcnt lgkmcnt(0)
	v_perm_b32 v230, v236, v237, s19
	v_perm_b32 v229, v228, v229, s19
	v_perm_b32 v228, v232, v233, s19
	v_mfma_f32_32x32x16_bf16 v[0:15], v[20:23], v[0:3], 0
	v_mfma_f32_32x32x16_bf16 v[80:95], v[16:19], v[24:27], 0
	v_mfma_f32_32x32x16_bf16 v[16:31], v[20:23], v[24:27], 0
	v_mfma_f32_32x32x16_bf16 v[64:79], v[224:227], v[182:185], v[64:79]
	v_mfma_f32_32x32x16_bf16 v[0:15], v[228:231], v[182:185], v[0:15]
	v_mfma_f32_32x32x16_bf16 v[96:111], v[224:227], v[190:193], v[96:111]
	v_mfma_f32_32x32x16_bf16 v[32:47], v[228:231], v[190:193], v[32:47]
	v_mfma_f32_32x32x16_bf16 v[112:127], v[224:227], v[194:197], v[112:127]
	v_mfma_f32_32x32x16_bf16 v[80:95], v[224:227], v[220:223], v[80:95]
	v_mfma_f32_32x32x16_bf16 v[16:31], v[228:231], v[220:223], v[16:31]
	ds_read_u16 v182, v167 offset:16896
	ds_read_u16 v186, v167 offset:17424
	ds_read_u16 v183, v167 offset:17952
	ds_read_u16 v187, v167 offset:18480
	ds_read_u16 v220, v167 offset:18544
	ds_read_u16 v221, v167 offset:18016
	ds_read_u16 v224, v167 offset:17488
	ds_read_u16 v225, v167 offset:16960
	ds_read_u16 v184, v167 offset:19008
	ds_read_u16 v190, v167 offset:19536
	ds_read_u16 v185, v167 offset:20064
	ds_read_u16 v191, v167 offset:20592
	ds_read_u16 v222, v167 offset:20656
	ds_read_u16 v223, v167 offset:20128
	ds_read_u16 v226, v167 offset:19600
	ds_read_u16 v227, v167 offset:19072
	s_waitcnt lgkmcnt(4)
	v_perm_b32 v185, v191, v185, s19
	v_perm_b32 v184, v190, v184, s19
	v_perm_b32 v183, v187, v183, s19
	v_perm_b32 v182, v186, v182, s19
	s_waitcnt lgkmcnt(2)
	v_perm_b32 v223, v222, v223, s19
	s_waitcnt lgkmcnt(0)
	v_perm_b32 v222, v226, v227, s19
	v_perm_b32 v221, v220, v221, s19
	v_perm_b32 v220, v224, v225, s19
	v_mfma_f32_32x32x16_bf16 v[48:63], v[228:231], v[194:197], v[48:63]
	ds_read_b128 v[190:193], v151 offset:36928
	ds_read_b128 v[194:197], v151 offset:36960
	s_waitcnt lgkmcnt(1)
	v_mfma_f32_32x32x16_bf16 v[64:79], v[182:185], v[190:193], v[64:79]
	v_mfma_f32_32x32x16_bf16 v[0:15], v[220:223], v[190:193], v[0:15]
	ds_read_b128 v[190:193], v151 offset:41536
	ds_read_b128 v[224:227], v151 offset:41568
	s_waitcnt lgkmcnt(1)
	v_mfma_f32_32x32x16_bf16 v[96:111], v[182:185], v[190:193], v[96:111]
	v_mfma_f32_32x32x16_bf16 v[32:47], v[220:223], v[190:193], v[32:47]
	ds_read_b128 v[190:193], v151 offset:46144
	ds_read_b128 v[228:231], v151 offset:46176
	s_waitcnt lgkmcnt(1)
	v_mfma_f32_32x32x16_bf16 v[112:127], v[182:185], v[190:193], v[112:127]
	v_mfma_f32_32x32x16_bf16 v[48:63], v[220:223], v[190:193], v[48:63]
	ds_read_b128 v[190:193], v151 offset:50752
	ds_read_b128 v[232:235], v151 offset:50784
	s_waitcnt lgkmcnt(1)
; template <bool AT>
; DI void gemm_main(f32x16 (&acc)[2][4], const u16* __restrict__ R, int ldr, const u16* __restrict__ Cm, int ldc,
;                   const u16* __restrict__ RT, int ldrt, int K, char* smem, int tid) {
;     ...
;     if (kt + 1 < nk) {
;       const int ks1 = kt + 1;
;       u16* Rs = S0 + (ks1 & 1) * STG;
;       u16* Cs = Rs + 256 * 72;
; #pragma unroll
;       for (int i = 0; i < 4; ++i) {
;         const int cid = tid + NT * i;
;         const int row = cid >> 3, kc = cid & 7;
;         if (AT && ks1 < 8) {
;           const int kr = cid >> 5, tc = cid & 31;
;           *(u32x4*)(Rs + kr * 264 + tc * 8) = rr[i];
;         } else {
;           *(u32x4*)(Rs + row * 72 + kc * 8) = rr[i];
;         }
;         *(u32x4*)(Cs + row * 72 + kc * 8) = cr[i];
;       }
;     }
;     if (kt + 2 < nk) {
;       const int kn = kt + 2;
; #pragma unroll
;       for (int i = 0; i < 4; ++i) {
;         const int cid = tid + NT * i;
;         const int row = cid >> 3, kc = cid & 7;
;         if (AT && kn < 8) {
;           const int kr = cid >> 5, tc = cid & 31;
;           rr[i] = *(const u32x4*)(RT + (size_t)(kn * 64 + kr) * ldrt + tc * 8);
;         } else {
;           rr[i] = *(const u32x4*)(R + (size_t)row * ldr + kn * 64 + kc * 8);
;         }
;         cr[i] = *(const u32x4*)(Cm + (size_t)row * ldc + kn * 64 + kc * 8);
;       }
;     }
;     __builtin_amdgcn_sched_barrier(0x38F);
;     if (kt >= 0) {
;       const u16* Rs = S0 + (kt & 1) * STG;
;       const u16* Cs = Rs + 256 * 72;
;       const u16* RTs = Rs;
; #pragma unroll
;       for (int ks = 0; ks < 4; ++ks) {
;         bf16x8 rf[2];
; #pragma unroll
;         for (int rb = 0; rb < 2; ++rb) {
;           if (AT && kt < 8) {
;             const u16* src = RTs + (16 * ks + 8 * g) * 264 + 64 * wr + 32 * rb + li;
;             bf16x8 t;
; #pragma unroll
;             for (int j = 0; j < 8; ++j) t[j] = (short)src[j * 264];
;             rf[rb] = t;
;           } else {
;             rf[rb] = *(const bf16x8*)(Rs + (64 * wr + 32 * rb + li) * 72 + 16 * ks + 8 * g);
;           }
;         }
; #pragma unroll
;         for (int cb = 0; cb < 4; ++cb) {
;           const bf16x8 cfv = *(const bf16x8*)(Cs + (128 * wc + 32 * cb + li) * 72 + 16 * ks + 8 * g);
; #pragma unroll
;           for (int rb = 0; rb < 2; ++rb) acc[rb][cb] = MFMA(rf[rb], cfv, acc[rb][cb]);
;         }
;       }
;     }
	v_mfma_f32_32x32x16_bf16 v[80:95], v[182:185], v[190:193], v[80:95]
	v_mfma_f32_32x32x16_bf16 v[16:31], v[220:223], v[190:193], v[16:31]
	ds_read_u16 v182, v167 offset:25344
	ds_read_u16 v186, v167 offset:25872
	ds_read_u16 v183, v167 offset:26400
	ds_read_u16 v187, v167 offset:26928
	ds_read_u16 v190, v167 offset:26992
	ds_read_u16 v191, v167 offset:26464
	ds_read_u16 v220, v167 offset:25936
	ds_read_u16 v221, v167 offset:25408
	ds_read_u16 v184, v167 offset:27456
	ds_read_u16 v192, v167 offset:27984
	ds_read_u16 v185, v167 offset:28512
	ds_read_u16 v193, v167 offset:29040
	ds_read_u16 v222, v167 offset:29104
	ds_read_u16 v223, v167 offset:28576
	ds_read_u16 v236, v167 offset:28048
	ds_read_u16 v237, v167 offset:27520
	s_waitcnt lgkmcnt(4)
	v_perm_b32 v185, v193, v185, s19
	v_perm_b32 v184, v192, v184, s19
	v_perm_b32 v183, v187, v183, s19
	v_perm_b32 v182, v186, v182, s19
	s_waitcnt lgkmcnt(2)
	v_perm_b32 v193, v222, v223, s19
	s_waitcnt lgkmcnt(0)
	v_perm_b32 v192, v236, v237, s19
	v_perm_b32 v191, v190, v191, s19
	v_perm_b32 v190, v220, v221, s19
	v_mfma_f32_32x32x16_bf16 v[64:79], v[182:185], v[194:197], v[64:79]
	v_add_u32_e32 v186, 0x80, v169
	v_mad_i64_i32 v[186:187], s[28:29], v186, s67, v[146:147]
	v_mfma_f32_32x32x16_bf16 v[0:15], v[190:193], v[194:197], v[0:15]
	v_add_u32_e32 v194, 0x80, v170
	v_mad_i64_i32 v[220:221], s[28:29], v194, s67, v[146:147]
	v_mfma_f32_32x32x16_bf16 v[96:111], v[182:185], v[224:227], v[96:111]
	v_mfma_f32_32x32x16_bf16 v[32:47], v[190:193], v[224:227], v[32:47]
	global_load_dwordx4 v[194:197], v[186:187], off
	s_nop 0
	global_load_dwordx4 v[220:223], v[220:221], off
	s_nop 0
	global_load_dwordx4 v[224:227], v[128:129], off offset:256
	global_load_dwordx4 v[236:239], v[130:131], off offset:256
	v_add_u32_e32 v186, 0x80, v171
	v_mad_i64_i32 v[186:187], s[28:29], v186, s67, v[146:147]
	v_mfma_f32_32x32x16_bf16 v[112:127], v[182:185], v[228:231], v[112:127]
	v_mfma_f32_32x32x16_bf16 v[48:63], v[190:193], v[228:231], v[48:63]
	global_load_dwordx4 v[228:231], v[132:133], off offset:256
	global_load_dwordx4 v[240:243], v[186:187], off
	s_nop 0
	global_load_dwordx4 v[244:247], v[244:245], off
	v_mul_u32_u24_e32 v186, 0x90, v168
	v_add3_u32 v168, v160, v188, v181
	v_mfma_f32_32x32x16_bf16 v[80:95], v[182:185], v[232:235], v[80:95]
	global_load_dwordx4 v[182:185], v[134:135], off offset:256
	s_barrier
	s_waitcnt vmcnt(7)
	ds_write_b128 v177, v[194:197]
	s_waitcnt vmcnt(5)
	ds_write_b128 v156, v[224:227] offset:36864
	ds_write_b128 v178, v[220:223]
	s_waitcnt vmcnt(4)
	ds_write_b128 v157, v[236:239] offset:36864
	s_waitcnt vmcnt(2)
	ds_write_b128 v179, v[240:243]
	ds_write_b128 v158, v[228:231] offset:36864
	s_waitcnt vmcnt(1)
	ds_write_b128 v180, v[244:247]
	s_waitcnt vmcnt(0)
	ds_write_b128 v159, v[182:185] offset:36864
	v_mfma_f32_32x32x16_bf16 v[16:31], v[190:193], v[232:235], v[16:31]
	ds_read_u16 v160, v168
	ds_read_u16 v181, v168 offset:528
	ds_read_u16 v182, v168 offset:1056
	ds_read_u16 v183, v168 offset:1584
	ds_read_u16 v187, v168 offset:1648
	ds_read_u16 v188, v168 offset:1120
	ds_read_u16 v220, v168 offset:592
	ds_read_u16 v224, v168 offset:64
	ds_read_u16 v184, v168 offset:2112
	ds_read_u16 v190, v168 offset:2640
	ds_read_u16 v185, v168 offset:3168
	ds_read_u16 v191, v168 offset:3696
	ds_read_u16 v221, v168 offset:3760
	ds_read_u16 v222, v168 offset:3232
	ds_read_u16 v225, v168 offset:2704
	ds_read_u16 v226, v168 offset:2176
	s_waitcnt lgkmcnt(4)
	v_perm_b32 v185, v191, v185, s19
	v_perm_b32 v184, v190, v184, s19
	v_perm_b32 v183, v183, v182, s19
	v_perm_b32 v182, v181, v160, s19
	v_add3_u32 v160, s90, v161, v186
	s_waitcnt lgkmcnt(2)
	v_perm_b32 v223, v221, v222, s19
	s_waitcnt lgkmcnt(0)
	v_perm_b32 v222, v225, v226, s19
	v_perm_b32 v221, v187, v188, s19
	v_perm_b32 v220, v220, v224, s19
	ds_read_b128 v[190:193], v160
	ds_read_b128 v[194:197], v160 offset:32
	s_waitcnt lgkmcnt(1)
	v_mfma_f32_32x32x16_bf16 v[64:79], v[182:185], v[190:193], v[64:79]
	v_mfma_f32_32x32x16_bf16 v[0:15], v[220:223], v[190:193], v[0:15]
	ds_read_b128 v[190:193], v160 offset:4608
	ds_read_b128 v[224:227], v160 offset:4640
	s_waitcnt lgkmcnt(1)
	v_mfma_f32_32x32x16_bf16 v[96:111], v[182:185], v[190:193], v[96:111]
	v_mfma_f32_32x32x16_bf16 v[32:47], v[220:223], v[190:193], v[32:47]
	ds_read_b128 v[190:193], v160 offset:9216
	ds_read_b128 v[228:231], v160 offset:9248
	s_waitcnt lgkmcnt(1)
	v_mfma_f32_32x32x16_bf16 v[112:127], v[182:185], v[190:193], v[112:127]
	v_mfma_f32_32x32x16_bf16 v[48:63], v[220:223], v[190:193], v[48:63]
	ds_read_b128 v[190:193], v160 offset:13824
	ds_read_b128 v[232:235], v160 offset:13856
	s_waitcnt lgkmcnt(1)
	v_mfma_f32_32x32x16_bf16 v[80:95], v[182:185], v[190:193], v[80:95]
	v_mfma_f32_32x32x16_bf16 v[16:31], v[220:223], v[190:193], v[16:31]
	ds_read_u16 v181, v168 offset:8448
	ds_read_u16 v182, v168 offset:8976
	ds_read_u16 v183, v168 offset:9504
	ds_read_u16 v186, v168 offset:10032
	ds_read_u16 v187, v168 offset:10096
	ds_read_u16 v188, v168 offset:9568
	ds_read_u16 v190, v168 offset:9040
	ds_read_u16 v220, v168 offset:8512
	ds_read_u16 v184, v168 offset:10560
	ds_read_u16 v191, v168 offset:11088
	ds_read_u16 v185, v168 offset:11616
	ds_read_u16 v192, v168 offset:12144
	ds_read_u16 v193, v168 offset:12208
	ds_read_u16 v221, v168 offset:11680
	ds_read_u16 v222, v168 offset:11152
	ds_read_u16 v223, v168 offset:10624
	s_waitcnt lgkmcnt(4)
	v_perm_b32 v185, v192, v185, s19
	v_perm_b32 v184, v191, v184, s19
	v_perm_b32 v183, v186, v183, s19
	v_perm_b32 v182, v182, v181, s19
	s_waitcnt lgkmcnt(2)
	v_perm_b32 v193, v193, v221, s19
	s_waitcnt lgkmcnt(0)
; template <bool AT>
; DI void gemm_main(f32x16 (&acc)[2][4], const u16* __restrict__ R, int ldr, const u16* __restrict__ Cm, int ldc,
;                   const u16* __restrict__ RT, int ldrt, int K, char* smem, int tid) {
;     ...
;     if (kt + 1 < nk) {
;       const int ks1 = kt + 1;
;       u16* Rs = S0 + (ks1 & 1) * STG;
;       u16* Cs = Rs + 256 * 72;
; #pragma unroll
;       for (int i = 0; i < 4; ++i) {
;         const int cid = tid + NT * i;
;         const int row = cid >> 3, kc = cid & 7;
;         if (AT && ks1 < 8) {
;           const int kr = cid >> 5, tc = cid & 31;
;           *(u32x4*)(Rs + kr * 264 + tc * 8) = rr[i];
;         } else {
;           *(u32x4*)(Rs + row * 72 + kc * 8) = rr[i];
;         }
;         *(u32x4*)(Cs + row * 72 + kc * 8) = cr[i];
;       }
;     }
;     if (kt + 2 < nk) {
;       const int kn = kt + 2;
; #pragma unroll
;       for (int i = 0; i < 4; ++i) {
;         const int cid = tid + NT * i;
;         const int row = cid >> 3, kc = cid & 7;
;         if (AT && kn < 8) {
;           const int kr = cid >> 5, tc = cid & 31;
;           rr[i] = *(const u32x4*)(RT + (size_t)(kn * 64 + kr) * ldrt + tc * 8);
;         } else {
;           rr[i] = *(const u32x4*)(R + (size_t)row * ldr + kn * 64 + kc * 8);
;         }
;         cr[i] = *(const u32x4*)(Cm + (size_t)row * ldc + kn * 64 + kc * 8);
;       }
;     }
;     __builtin_amdgcn_sched_barrier(0x38F);
;     if (kt >= 0) {
;       const u16* Rs = S0 + (kt & 1) * STG;
;       const u16* Cs = Rs + 256 * 72;
;       const u16* RTs = Rs;
; #pragma unroll
;       for (int ks = 0; ks < 4; ++ks) {
;         bf16x8 rf[2];
; #pragma unroll
;         for (int rb = 0; rb < 2; ++rb) {
;           if (AT && kt < 8) {
;             const u16* src = RTs + (16 * ks + 8 * g) * 264 + 64 * wr + 32 * rb + li;
;             bf16x8 t;
; #pragma unroll
;             for (int j = 0; j < 8; ++j) t[j] = (short)src[j * 264];
;             rf[rb] = t;
;           } else {
;             rf[rb] = *(const bf16x8*)(Rs + (64 * wr + 32 * rb + li) * 72 + 16 * ks + 8 * g);
;           }
;         }
; #pragma unroll
;         for (int cb = 0; cb < 4; ++cb) {
;           const bf16x8 cfv = *(const bf16x8*)(Cs + (128 * wc + 32 * cb + li) * 72 + 16 * ks + 8 * g);
; #pragma unroll
;           for (int rb = 0; rb < 2; ++rb) acc[rb][cb] = MFMA(rf[rb], cfv, acc[rb][cb]);
;         }
;       }
;     }
	v_perm_b32 v192, v222, v223, s19
	v_perm_b32 v191, v187, v188, s19
	v_perm_b32 v190, v190, v220, s19
	v_mfma_f32_32x32x16_bf16 v[64:79], v[182:185], v[194:197], v[64:79]
	s_nop 0
	v_mfma_f32_32x32x16_bf16 v[0:15], v[190:193], v[194:197], v[0:15]
	v_mfma_f32_32x32x16_bf16 v[96:111], v[182:185], v[224:227], v[96:111]
	v_mfma_f32_32x32x16_bf16 v[32:47], v[190:193], v[224:227], v[32:47]
	v_mfma_f32_32x32x16_bf16 v[112:127], v[182:185], v[228:231], v[112:127]
	v_mfma_f32_32x32x16_bf16 v[48:63], v[190:193], v[228:231], v[48:63]
	v_mfma_f32_32x32x16_bf16 v[80:95], v[182:185], v[232:235], v[80:95]
	v_mfma_f32_32x32x16_bf16 v[16:31], v[190:193], v[232:235], v[16:31]
	ds_read_u16 v181, v168 offset:16896
	ds_read_u16 v182, v168 offset:17424
	ds_read_u16 v183, v168 offset:17952
	ds_read_u16 v186, v168 offset:18480
	ds_read_u16 v187, v168 offset:18544
	ds_read_u16 v188, v168 offset:18016
	ds_read_u16 v220, v168 offset:17488
	ds_read_u16 v224, v168 offset:16960
	ds_read_u16 v184, v168 offset:19008
	ds_read_u16 v190, v168 offset:19536
	ds_read_u16 v185, v168 offset:20064
	ds_read_u16 v191, v168 offset:20592
	ds_read_u16 v221, v168 offset:20656
	ds_read_u16 v222, v168 offset:20128
	ds_read_u16 v225, v168 offset:19600
	ds_read_u16 v226, v168 offset:19072
	s_waitcnt lgkmcnt(4)
	v_perm_b32 v185, v191, v185, s19
	v_perm_b32 v184, v190, v184, s19
	v_perm_b32 v183, v186, v183, s19
	v_perm_b32 v182, v182, v181, s19
	s_waitcnt lgkmcnt(2)
	v_perm_b32 v223, v221, v222, s19
	s_waitcnt lgkmcnt(0)
	v_perm_b32 v222, v225, v226, s19
	v_perm_b32 v221, v187, v188, s19
	v_perm_b32 v220, v220, v224, s19
	ds_read_b128 v[190:193], v160 offset:64
	ds_read_b128 v[194:197], v160 offset:96
	s_waitcnt lgkmcnt(1)
	v_mfma_f32_32x32x16_bf16 v[64:79], v[182:185], v[190:193], v[64:79]
	v_mfma_f32_32x32x16_bf16 v[0:15], v[220:223], v[190:193], v[0:15]
	ds_read_b128 v[190:193], v160 offset:4672
	ds_read_b128 v[224:227], v160 offset:4704
	s_waitcnt lgkmcnt(1)
	v_mfma_f32_32x32x16_bf16 v[96:111], v[182:185], v[190:193], v[96:111]
	v_mfma_f32_32x32x16_bf16 v[32:47], v[220:223], v[190:193], v[32:47]
	ds_read_b128 v[190:193], v160 offset:9280
	ds_read_b128 v[228:231], v160 offset:9312
	s_waitcnt lgkmcnt(1)
	v_mfma_f32_32x32x16_bf16 v[112:127], v[182:185], v[190:193], v[112:127]
	v_mfma_f32_32x32x16_bf16 v[48:63], v[220:223], v[190:193], v[48:63]
	ds_read_b128 v[190:193], v160 offset:13888
	ds_read_b128 v[232:235], v160 offset:13920
	s_waitcnt lgkmcnt(1)
	v_mfma_f32_32x32x16_bf16 v[80:95], v[182:185], v[190:193], v[80:95]
	v_mfma_f32_32x32x16_bf16 v[16:31], v[220:223], v[190:193], v[16:31]
	ds_read_u16 v181, v168 offset:25344
	ds_read_u16 v182, v168 offset:25872
	ds_read_u16 v183, v168 offset:26400
	ds_read_u16 v186, v168 offset:26928
	ds_read_u16 v187, v168 offset:26992
	ds_read_u16 v188, v168 offset:26464
	ds_read_u16 v190, v168 offset:25936
	ds_read_u16 v220, v168 offset:25408
	ds_read_u16 v184, v168 offset:27456
	ds_read_u16 v191, v168 offset:27984
	ds_read_u16 v185, v168 offset:28512
	ds_read_u16 v192, v168 offset:29040
	ds_read_u16 v193, v168 offset:29104
	ds_read_u16 v221, v168 offset:28576
	ds_read_u16 v222, v168 offset:28048
	ds_read_u16 v223, v168 offset:27520
	s_waitcnt lgkmcnt(4)
	v_perm_b32 v185, v192, v185, s19
	v_perm_b32 v184, v191, v184, s19
	v_perm_b32 v183, v186, v183, s19
	v_perm_b32 v182, v182, v181, s19
	s_waitcnt lgkmcnt(2)
	v_perm_b32 v193, v193, v221, s19
	s_waitcnt lgkmcnt(0)
	v_perm_b32 v192, v222, v223, s19
	v_perm_b32 v191, v187, v188, s19
	v_perm_b32 v190, v190, v220, s19
	v_add_u32_e32 v181, 0xc0, v169
	v_mad_i64_i32 v[186:187], s[28:29], v181, s67, v[146:147]
	v_add_u32_e32 v181, 0xc0, v170
	v_mad_i64_i32 v[220:221], s[28:29], v181, s67, v[146:147]
	v_add_u32_e32 v181, 0xc0, v171
	v_mfma_f32_32x32x16_bf16 v[64:79], v[182:185], v[194:197], v[64:79]
	v_mfma_f32_32x32x16_bf16 v[0:15], v[190:193], v[194:197], v[0:15]
	v_mfma_f32_32x32x16_bf16 v[96:111], v[182:185], v[224:227], v[96:111]
	v_mfma_f32_32x32x16_bf16 v[32:47], v[190:193], v[224:227], v[32:47]
	global_load_dwordx4 v[194:197], v[186:187], off
	s_nop 0
	global_load_dwordx4 v[220:223], v[220:221], off
	s_nop 0
	global_load_dwordx4 v[224:227], v[128:129], off offset:384
	global_load_dwordx4 v[236:239], v[130:131], off offset:384
	v_mad_i64_i32 v[186:187], s[28:29], v181, s67, v[146:147]
	v_add_u32_e32 v181, 0xc0, v172
	v_mad_i64_i32 v[244:245], s[28:29], v181, s67, v[146:147]
	v_mfma_f32_32x32x16_bf16 v[112:127], v[182:185], v[228:231], v[112:127]
	v_mfma_f32_32x32x16_bf16 v[48:63], v[190:193], v[228:231], v[48:63]
	global_load_dwordx4 v[228:231], v[132:133], off offset:384
	global_load_dwordx4 v[240:243], v[186:187], off
	s_nop 0
	global_load_dwordx4 v[244:247], v[244:245], off
	v_mfma_f32_32x32x16_bf16 v[80:95], v[182:185], v[232:235], v[80:95]
	global_load_dwordx4 v[182:185], v[134:135], off offset:384
	s_barrier
; template <bool AT>
; DI void gemm_main(f32x16 (&acc)[2][4], const u16* __restrict__ R, int ldr, const u16* __restrict__ Cm, int ldc,
;                   const u16* __restrict__ RT, int ldrt, int K, char* smem, int tid) {
;     ...
;     if (kt + 1 < nk) {
;       const int ks1 = kt + 1;
;       u16* Rs = S0 + (ks1 & 1) * STG;
;       u16* Cs = Rs + 256 * 72;
; #pragma unroll
;       for (int i = 0; i < 4; ++i) {
;         const int cid = tid + NT * i;
;         const int row = cid >> 3, kc = cid & 7;
;         if (AT && ks1 < 8) {
;           const int kr = cid >> 5, tc = cid & 31;
;           *(u32x4*)(Rs + kr * 264 + tc * 8) = rr[i];
;         } else {
;           *(u32x4*)(Rs + row * 72 + kc * 8) = rr[i];
;         }
;         *(u32x4*)(Cs + row * 72 + kc * 8) = cr[i];
;       }
;     }
;     if (kt + 2 < nk) {
;       const int kn = kt + 2;
; #pragma unroll
;       for (int i = 0; i < 4; ++i) {
;         const int cid = tid + NT * i;
;         const int row = cid >> 3, kc = cid & 7;
;         if (AT && kn < 8) {
;           const int kr = cid >> 5, tc = cid & 31;
;           rr[i] = *(const u32x4*)(RT + (size_t)(kn * 64 + kr) * ldrt + tc * 8);
;         } else {
;           rr[i] = *(const u32x4*)(R + (size_t)row * ldr + kn * 64 + kc * 8);
;         }
;         cr[i] = *(const u32x4*)(Cm + (size_t)row * ldc + kn * 64 + kc * 8);
;       }
;     }
;     __builtin_amdgcn_sched_barrier(0x38F);
;     if (kt >= 0) {
;       const u16* Rs = S0 + (kt & 1) * STG;
;       const u16* Cs = Rs + 256 * 72;
;       const u16* RTs = Rs;
; #pragma unroll
;       for (int ks = 0; ks < 4; ++ks) {
;         bf16x8 rf[2];
; #pragma unroll
;         for (int rb = 0; rb < 2; ++rb) {
;           if (AT && kt < 8) {
;             const u16* src = RTs + (16 * ks + 8 * g) * 264 + 64 * wr + 32 * rb + li;
;             bf16x8 t;
; #pragma unroll
;             for (int j = 0; j < 8; ++j) t[j] = (short)src[j * 264];
;             rf[rb] = t;
;           } else {
;             rf[rb] = *(const bf16x8*)(Rs + (64 * wr + 32 * rb + li) * 72 + 16 * ks + 8 * g);
;           }
;         }
; #pragma unroll
;         for (int cb = 0; cb < 4; ++cb) {
;           const bf16x8 cfv = *(const bf16x8*)(Cs + (128 * wc + 32 * cb + li) * 72 + 16 * ks + 8 * g);
; #pragma unroll
;           for (int rb = 0; rb < 2; ++rb) acc[rb][cb] = MFMA(rf[rb], cfv, acc[rb][cb]);
;         }
;       }
;     }
	s_waitcnt vmcnt(7)
	ds_write_b128 v173, v[194:197]
	s_waitcnt vmcnt(5)
	ds_write_b128 v152, v[224:227]
	ds_write_b128 v174, v[220:223]
	s_waitcnt vmcnt(4)
	ds_write_b128 v153, v[236:239]
	s_waitcnt vmcnt(2)
	ds_write_b128 v175, v[240:243]
	ds_write_b128 v154, v[228:231]
	s_waitcnt vmcnt(1)
	ds_write_b128 v176, v[244:247]
	s_waitcnt vmcnt(0)
	ds_write_b128 v155, v[182:185]
	v_mfma_f32_32x32x16_bf16 v[16:31], v[190:193], v[232:235], v[16:31]
	ds_read_u16 v181, v167
	ds_read_u16 v182, v167 offset:528
	ds_read_u16 v183, v167 offset:1056
	ds_read_u16 v186, v167 offset:1584
	ds_read_u16 v187, v167 offset:1648
	ds_read_u16 v188, v167 offset:1120
	ds_read_u16 v220, v167 offset:592
	ds_read_u16 v224, v167 offset:64
	ds_read_u16 v184, v167 offset:2112
	ds_read_u16 v190, v167 offset:2640
	ds_read_u16 v185, v167 offset:3168
	ds_read_u16 v191, v167 offset:3696
	ds_read_u16 v221, v167 offset:3760
	ds_read_u16 v222, v167 offset:3232
	ds_read_u16 v225, v167 offset:2704
	ds_read_u16 v226, v167 offset:2176
	s_waitcnt lgkmcnt(4)
	v_perm_b32 v185, v191, v185, s19
	v_perm_b32 v184, v190, v184, s19
	v_perm_b32 v183, v186, v183, s19
	v_perm_b32 v182, v182, v181, s19
	s_waitcnt lgkmcnt(2)
	v_perm_b32 v223, v221, v222, s19
	s_waitcnt lgkmcnt(0)
	v_perm_b32 v222, v225, v226, s19
	v_perm_b32 v221, v187, v188, s19
	v_perm_b32 v220, v220, v224, s19
	ds_read_b128 v[190:193], v151 offset:36864
	ds_read_b128 v[194:197], v151 offset:36896
	s_waitcnt lgkmcnt(1)
	v_mfma_f32_32x32x16_bf16 v[64:79], v[182:185], v[190:193], v[64:79]
	v_mfma_f32_32x32x16_bf16 v[0:15], v[220:223], v[190:193], v[0:15]
	ds_read_b128 v[190:193], v151 offset:41472
	ds_read_b128 v[224:227], v151 offset:41504
	s_waitcnt lgkmcnt(1)
	v_mfma_f32_32x32x16_bf16 v[96:111], v[182:185], v[190:193], v[96:111]
	v_mfma_f32_32x32x16_bf16 v[32:47], v[220:223], v[190:193], v[32:47]
	ds_read_b128 v[190:193], v151 offset:46080
	ds_read_b128 v[228:231], v151 offset:46112
	s_waitcnt lgkmcnt(1)
	v_mfma_f32_32x32x16_bf16 v[112:127], v[182:185], v[190:193], v[112:127]
	v_mfma_f32_32x32x16_bf16 v[48:63], v[220:223], v[190:193], v[48:63]
	ds_read_b128 v[190:193], v151 offset:50688
	ds_read_b128 v[232:235], v151 offset:50720
	s_waitcnt lgkmcnt(1)
	v_mfma_f32_32x32x16_bf16 v[80:95], v[182:185], v[190:193], v[80:95]
	v_mfma_f32_32x32x16_bf16 v[16:31], v[220:223], v[190:193], v[16:31]
	ds_read_u16 v181, v167 offset:8448
	ds_read_u16 v182, v167 offset:8976
	ds_read_u16 v183, v167 offset:9504
	ds_read_u16 v186, v167 offset:10032
	ds_read_u16 v187, v167 offset:10096
	ds_read_u16 v188, v167 offset:9568
	ds_read_u16 v190, v167 offset:9040
	ds_read_u16 v220, v167 offset:8512
	ds_read_u16 v184, v167 offset:10560
	ds_read_u16 v191, v167 offset:11088
	ds_read_u16 v185, v167 offset:11616
	ds_read_u16 v192, v167 offset:12144
	ds_read_u16 v193, v167 offset:12208
	ds_read_u16 v221, v167 offset:11680
	ds_read_u16 v222, v167 offset:11152
	ds_read_u16 v223, v167 offset:10624
	s_waitcnt lgkmcnt(4)
	v_perm_b32 v185, v192, v185, s19
	v_perm_b32 v184, v191, v184, s19
	v_perm_b32 v183, v186, v183, s19
	v_perm_b32 v182, v182, v181, s19
	s_waitcnt lgkmcnt(2)
	v_perm_b32 v193, v193, v221, s19
	s_waitcnt lgkmcnt(0)
	v_perm_b32 v192, v222, v223, s19
	v_perm_b32 v191, v187, v188, s19
	v_perm_b32 v190, v190, v220, s19
	v_mfma_f32_32x32x16_bf16 v[64:79], v[182:185], v[194:197], v[64:79]
	s_nop 0
	v_mfma_f32_32x32x16_bf16 v[0:15], v[190:193], v[194:197], v[0:15]
	v_mfma_f32_32x32x16_bf16 v[96:111], v[182:185], v[224:227], v[96:111]
	v_mfma_f32_32x32x16_bf16 v[32:47], v[190:193], v[224:227], v[32:47]
	v_mfma_f32_32x32x16_bf16 v[112:127], v[182:185], v[228:231], v[112:127]
	v_mfma_f32_32x32x16_bf16 v[48:63], v[190:193], v[228:231], v[48:63]
	v_mfma_f32_32x32x16_bf16 v[80:95], v[182:185], v[232:235], v[80:95]
	v_mfma_f32_32x32x16_bf16 v[16:31], v[190:193], v[232:235], v[16:31]
	ds_read_u16 v181, v167 offset:16896
	ds_read_u16 v182, v167 offset:17424
	ds_read_u16 v183, v167 offset:17952
	ds_read_u16 v186, v167 offset:18480
	ds_read_u16 v187, v167 offset:18544
	ds_read_u16 v188, v167 offset:18016
	ds_read_u16 v220, v167 offset:17488
	ds_read_u16 v224, v167 offset:16960
	ds_read_u16 v184, v167 offset:19008
	ds_read_u16 v190, v167 offset:19536
	ds_read_u16 v185, v167 offset:20064
	ds_read_u16 v191, v167 offset:20592
	ds_read_u16 v221, v167 offset:20656
	ds_read_u16 v222, v167 offset:20128
	ds_read_u16 v225, v167 offset:19600
	ds_read_u16 v226, v167 offset:19072
	s_waitcnt lgkmcnt(4)
	v_perm_b32 v185, v191, v185, s19
	v_perm_b32 v184, v190, v184, s19
	v_perm_b32 v183, v186, v183, s19
	v_perm_b32 v182, v182, v181, s19
	s_waitcnt lgkmcnt(2)
	v_perm_b32 v223, v221, v222, s19
	s_waitcnt lgkmcnt(0)
	v_perm_b32 v222, v225, v226, s19
	v_perm_b32 v221, v187, v188, s19
	v_perm_b32 v220, v220, v224, s19
	ds_read_b128 v[190:193], v151 offset:36928
	ds_read_b128 v[194:197], v151 offset:36960
	s_waitcnt lgkmcnt(1)
	v_mfma_f32_32x32x16_bf16 v[64:79], v[182:185], v[190:193], v[64:79]
	v_mfma_f32_32x32x16_bf16 v[0:15], v[220:223], v[190:193], v[0:15]
	ds_read_b128 v[190:193], v151 offset:41536
	ds_read_b128 v[224:227], v151 offset:41568
	s_waitcnt lgkmcnt(1)
	v_mfma_f32_32x32x16_bf16 v[96:111], v[182:185], v[190:193], v[96:111]
	v_mfma_f32_32x32x16_bf16 v[32:47], v[220:223], v[190:193], v[32:47]
	ds_read_b128 v[190:193], v151 offset:46144
	ds_read_b128 v[228:231], v151 offset:46176
	s_waitcnt lgkmcnt(1)
	v_mfma_f32_32x32x16_bf16 v[112:127], v[182:185], v[190:193], v[112:127]
	v_mfma_f32_32x32x16_bf16 v[48:63], v[220:223], v[190:193], v[48:63]
	ds_read_b128 v[190:193], v151 offset:50752
	ds_read_b128 v[232:235], v151 offset:50784
	s_waitcnt lgkmcnt(1)
; template <bool AT>
; DI void gemm_main(f32x16 (&acc)[2][4], const u16* __restrict__ R, int ldr, const u16* __restrict__ Cm, int ldc,
;                   const u16* __restrict__ RT, int ldrt, int K, char* smem, int tid) {
;     ...
;     if (kt + 1 < nk) {
;       const int ks1 = kt + 1;
;       u16* Rs = S0 + (ks1 & 1) * STG;
;       u16* Cs = Rs + 256 * 72;
; #pragma unroll
;       for (int i = 0; i < 4; ++i) {
;         const int cid = tid + NT * i;
;         const int row = cid >> 3, kc = cid & 7;
;         if (AT && ks1 < 8) {
;           const int kr = cid >> 5, tc = cid & 31;
;           *(u32x4*)(Rs + kr * 264 + tc * 8) = rr[i];
;         } else {
;           *(u32x4*)(Rs + row * 72 + kc * 8) = rr[i];
;         }
;         *(u32x4*)(Cs + row * 72 + kc * 8) = cr[i];
;       }
;     }
;     if (kt + 2 < nk) {
;       const int kn = kt + 2;
; #pragma unroll
;       for (int i = 0; i < 4; ++i) {
;         const int cid = tid + NT * i;
;         const int row = cid >> 3, kc = cid & 7;
;         if (AT && kn < 8) {
;           const int kr = cid >> 5, tc = cid & 31;
;           rr[i] = *(const u32x4*)(RT + (size_t)(kn * 64 + kr) * ldrt + tc * 8);
;         } else {
;           rr[i] = *(const u32x4*)(R + (size_t)row * ldr + kn * 64 + kc * 8);
;         }
;         cr[i] = *(const u32x4*)(Cm + (size_t)row * ldc + kn * 64 + kc * 8);
;       }
;     }
;     __builtin_amdgcn_sched_barrier(0x38F);
;     if (kt >= 0) {
;       const u16* Rs = S0 + (kt & 1) * STG;
;       const u16* Cs = Rs + 256 * 72;
;       const u16* RTs = Rs;
; #pragma unroll
;       for (int ks = 0; ks < 4; ++ks) {
;         bf16x8 rf[2];
; #pragma unroll
;         for (int rb = 0; rb < 2; ++rb) {
;           if (AT && kt < 8) {
;             const u16* src = RTs + (16 * ks + 8 * g) * 264 + 64 * wr + 32 * rb + li;
;             bf16x8 t;
; #pragma unroll
;             for (int j = 0; j < 8; ++j) t[j] = (short)src[j * 264];
;             rf[rb] = t;
;           } else {
;             rf[rb] = *(const bf16x8*)(Rs + (64 * wr + 32 * rb + li) * 72 + 16 * ks + 8 * g);
;           }
;         }
; #pragma unroll
;         for (int cb = 0; cb < 4; ++cb) {
;           const bf16x8 cfv = *(const bf16x8*)(Cs + (128 * wc + 32 * cb + li) * 72 + 16 * ks + 8 * g);
; #pragma unroll
;           for (int rb = 0; rb < 2; ++rb) acc[rb][cb] = MFMA(rf[rb], cfv, acc[rb][cb]);
;         }
;       }
;     }
	v_mfma_f32_32x32x16_bf16 v[80:95], v[182:185], v[190:193], v[80:95]
	v_mfma_f32_32x32x16_bf16 v[16:31], v[220:223], v[190:193], v[16:31]
	ds_read_u16 v181, v167 offset:25344
	ds_read_u16 v182, v167 offset:25872
	ds_read_u16 v183, v167 offset:26400
	ds_read_u16 v186, v167 offset:26928
	ds_read_u16 v187, v167 offset:26992
	ds_read_u16 v188, v167 offset:26464
	ds_read_u16 v190, v167 offset:25936
	ds_read_u16 v220, v167 offset:25408
	ds_read_u16 v184, v167 offset:27456
	ds_read_u16 v191, v167 offset:27984
	ds_read_u16 v185, v167 offset:28512
	ds_read_u16 v192, v167 offset:29040
	ds_read_u16 v193, v167 offset:29104
	ds_read_u16 v221, v167 offset:28576
	ds_read_u16 v222, v167 offset:28048
	ds_read_u16 v223, v167 offset:27520
	s_waitcnt lgkmcnt(4)
	v_perm_b32 v185, v192, v185, s19
	v_perm_b32 v184, v191, v184, s19
	v_perm_b32 v183, v186, v183, s19
	v_perm_b32 v182, v182, v181, s19
	s_waitcnt lgkmcnt(2)
	v_perm_b32 v193, v193, v221, s19
	s_waitcnt lgkmcnt(0)
	v_perm_b32 v192, v222, v223, s19
	v_perm_b32 v191, v187, v188, s19
	v_perm_b32 v190, v190, v220, s19
	v_add_u32_e32 v181, 0x100, v169
	v_mad_i64_i32 v[186:187], s[28:29], v181, s67, v[146:147]
	v_add_u32_e32 v181, 0x100, v170
	v_mad_i64_i32 v[220:221], s[28:29], v181, s67, v[146:147]
	v_add_u32_e32 v181, 0x100, v171
	v_mfma_f32_32x32x16_bf16 v[64:79], v[182:185], v[194:197], v[64:79]
	v_mfma_f32_32x32x16_bf16 v[0:15], v[190:193], v[194:197], v[0:15]
	v_mfma_f32_32x32x16_bf16 v[96:111], v[182:185], v[224:227], v[96:111]
	v_mfma_f32_32x32x16_bf16 v[32:47], v[190:193], v[224:227], v[32:47]
	global_load_dwordx4 v[194:197], v[186:187], off
	s_nop 0
	global_load_dwordx4 v[220:223], v[220:221], off
	s_nop 0
	global_load_dwordx4 v[224:227], v[128:129], off offset:512
	global_load_dwordx4 v[236:239], v[130:131], off offset:512
	v_mad_i64_i32 v[186:187], s[28:29], v181, s67, v[146:147]
	v_add_u32_e32 v181, 0x100, v172
	v_mad_i64_i32 v[244:245], s[28:29], v181, s67, v[146:147]
	v_mfma_f32_32x32x16_bf16 v[112:127], v[182:185], v[228:231], v[112:127]
	v_mfma_f32_32x32x16_bf16 v[48:63], v[190:193], v[228:231], v[48:63]
	global_load_dwordx4 v[228:231], v[132:133], off offset:512
	global_load_dwordx4 v[240:243], v[186:187], off
	s_nop 0
	global_load_dwordx4 v[244:247], v[244:245], off
	v_mfma_f32_32x32x16_bf16 v[80:95], v[182:185], v[232:235], v[80:95]
	global_load_dwordx4 v[182:185], v[134:135], off offset:512
	s_barrier
	s_waitcnt vmcnt(7)
	ds_write_b128 v177, v[194:197]
	s_waitcnt vmcnt(5)
	ds_write_b128 v156, v[224:227] offset:36864
	ds_write_b128 v178, v[220:223]
	s_waitcnt vmcnt(4)
	ds_write_b128 v157, v[236:239] offset:36864
	s_waitcnt vmcnt(2)
	ds_write_b128 v179, v[240:243]
	ds_write_b128 v158, v[228:231] offset:36864
	s_waitcnt vmcnt(1)
	ds_write_b128 v180, v[244:247]
	s_waitcnt vmcnt(0)
	ds_write_b128 v159, v[182:185] offset:36864
	v_mfma_f32_32x32x16_bf16 v[16:31], v[190:193], v[232:235], v[16:31]
	ds_read_u16 v181, v168
	ds_read_u16 v182, v168 offset:528
	ds_read_u16 v183, v168 offset:1056
	ds_read_u16 v186, v168 offset:1584
	ds_read_u16 v187, v168 offset:1648
	ds_read_u16 v188, v168 offset:1120
	ds_read_u16 v220, v168 offset:592
	ds_read_u16 v224, v168 offset:64
	ds_read_u16 v184, v168 offset:2112
	ds_read_u16 v190, v168 offset:2640
	ds_read_u16 v185, v168 offset:3168
	ds_read_u16 v191, v168 offset:3696
	ds_read_u16 v221, v168 offset:3760
	ds_read_u16 v222, v168 offset:3232
	ds_read_u16 v225, v168 offset:2704
	ds_read_u16 v226, v168 offset:2176
	s_waitcnt lgkmcnt(4)
	v_perm_b32 v185, v191, v185, s19
	v_perm_b32 v184, v190, v184, s19
	v_perm_b32 v183, v186, v183, s19
	v_perm_b32 v182, v182, v181, s19
	s_waitcnt lgkmcnt(2)
	v_perm_b32 v223, v221, v222, s19
	s_waitcnt lgkmcnt(0)
	v_perm_b32 v222, v225, v226, s19
	v_perm_b32 v221, v187, v188, s19
	v_perm_b32 v220, v220, v224, s19
	ds_read_b128 v[190:193], v160
	ds_read_b128 v[194:197], v160 offset:32
	s_waitcnt lgkmcnt(1)
	v_mfma_f32_32x32x16_bf16 v[64:79], v[182:185], v[190:193], v[64:79]
	v_mfma_f32_32x32x16_bf16 v[0:15], v[220:223], v[190:193], v[0:15]
	ds_read_b128 v[190:193], v160 offset:4608
	ds_read_b128 v[224:227], v160 offset:4640
	s_waitcnt lgkmcnt(1)
	v_mfma_f32_32x32x16_bf16 v[96:111], v[182:185], v[190:193], v[96:111]
	v_mfma_f32_32x32x16_bf16 v[32:47], v[220:223], v[190:193], v[32:47]
	ds_read_b128 v[190:193], v160 offset:9216
	ds_read_b128 v[228:231], v160 offset:9248
	s_waitcnt lgkmcnt(1)
	v_mfma_f32_32x32x16_bf16 v[112:127], v[182:185], v[190:193], v[112:127]
	v_mfma_f32_32x32x16_bf16 v[48:63], v[220:223], v[190:193], v[48:63]
	ds_read_b128 v[190:193], v160 offset:13824
	ds_read_b128 v[232:235], v160 offset:13856
	s_waitcnt lgkmcnt(1)
	v_mfma_f32_32x32x16_bf16 v[80:95], v[182:185], v[190:193], v[80:95]
	v_mfma_f32_32x32x16_bf16 v[16:31], v[220:223], v[190:193], v[16:31]
	ds_read_u16 v181, v168 offset:8448
	ds_read_u16 v182, v168 offset:8976
	ds_read_u16 v183, v168 offset:9504
	ds_read_u16 v186, v168 offset:10032
	ds_read_u16 v187, v168 offset:10096
	ds_read_u16 v188, v168 offset:9568
	ds_read_u16 v190, v168 offset:9040
	ds_read_u16 v220, v168 offset:8512
	ds_read_u16 v184, v168 offset:10560
	ds_read_u16 v191, v168 offset:11088
	ds_read_u16 v185, v168 offset:11616
	ds_read_u16 v192, v168 offset:12144
	ds_read_u16 v193, v168 offset:12208
	ds_read_u16 v221, v168 offset:11680
	ds_read_u16 v222, v168 offset:11152
	ds_read_u16 v223, v168 offset:10624
	s_waitcnt lgkmcnt(4)
	v_perm_b32 v185, v192, v185, s19
	v_perm_b32 v184, v191, v184, s19
	v_perm_b32 v183, v186, v183, s19
	v_perm_b32 v182, v182, v181, s19
	s_waitcnt lgkmcnt(2)
	v_perm_b32 v193, v193, v221, s19
	s_waitcnt lgkmcnt(0)
; template <bool AT>
; DI void gemm_main(f32x16 (&acc)[2][4], const u16* __restrict__ R, int ldr, const u16* __restrict__ Cm, int ldc,
;                   const u16* __restrict__ RT, int ldrt, int K, char* smem, int tid) {
;     ...
;     if (kt + 1 < nk) {
;       const int ks1 = kt + 1;
;       u16* Rs = S0 + (ks1 & 1) * STG;
;       u16* Cs = Rs + 256 * 72;
; #pragma unroll
;       for (int i = 0; i < 4; ++i) {
;         const int cid = tid + NT * i;
;         const int row = cid >> 3, kc = cid & 7;
;         if (AT && ks1 < 8) {
;           const int kr = cid >> 5, tc = cid & 31;
;           *(u32x4*)(Rs + kr * 264 + tc * 8) = rr[i];
;         } else {
;           *(u32x4*)(Rs + row * 72 + kc * 8) = rr[i];
;         }
;         *(u32x4*)(Cs + row * 72 + kc * 8) = cr[i];
;       }
;     }
;     if (kt + 2 < nk) {
;       const int kn = kt + 2;
; #pragma unroll
;       for (int i = 0; i < 4; ++i) {
;         const int cid = tid + NT * i;
;         const int row = cid >> 3, kc = cid & 7;
;         if (AT && kn < 8) {
;           const int kr = cid >> 5, tc = cid & 31;
;           rr[i] = *(const u32x4*)(RT + (size_t)(kn * 64 + kr) * ldrt + tc * 8);
;         } else {
;           rr[i] = *(const u32x4*)(R + (size_t)row * ldr + kn * 64 + kc * 8);
;         }
;         cr[i] = *(const u32x4*)(Cm + (size_t)row * ldc + kn * 64 + kc * 8);
;       }
;     }
;     __builtin_amdgcn_sched_barrier(0x38F);
;     if (kt >= 0) {
;       const u16* Rs = S0 + (kt & 1) * STG;
;       const u16* Cs = Rs + 256 * 72;
;       const u16* RTs = Rs;
; #pragma unroll
;       for (int ks = 0; ks < 4; ++ks) {
;         bf16x8 rf[2];
; #pragma unroll
;         for (int rb = 0; rb < 2; ++rb) {
;           if (AT && kt < 8) {
;             const u16* src = RTs + (16 * ks + 8 * g) * 264 + 64 * wr + 32 * rb + li;
;             bf16x8 t;
; #pragma unroll
;             for (int j = 0; j < 8; ++j) t[j] = (short)src[j * 264];
;             rf[rb] = t;
;           } else {
;             rf[rb] = *(const bf16x8*)(Rs + (64 * wr + 32 * rb + li) * 72 + 16 * ks + 8 * g);
;           }
;         }
; #pragma unroll
;         for (int cb = 0; cb < 4; ++cb) {
;           const bf16x8 cfv = *(const bf16x8*)(Cs + (128 * wc + 32 * cb + li) * 72 + 16 * ks + 8 * g);
; #pragma unroll
;           for (int rb = 0; rb < 2; ++rb) acc[rb][cb] = MFMA(rf[rb], cfv, acc[rb][cb]);
;         }
;       }
;     }
	v_perm_b32 v192, v222, v223, s19
	v_perm_b32 v191, v187, v188, s19
	v_perm_b32 v190, v190, v220, s19
	v_mfma_f32_32x32x16_bf16 v[64:79], v[182:185], v[194:197], v[64:79]
	s_nop 0
	v_mfma_f32_32x32x16_bf16 v[0:15], v[190:193], v[194:197], v[0:15]
	v_mfma_f32_32x32x16_bf16 v[96:111], v[182:185], v[224:227], v[96:111]
	v_mfma_f32_32x32x16_bf16 v[32:47], v[190:193], v[224:227], v[32:47]
	v_mfma_f32_32x32x16_bf16 v[112:127], v[182:185], v[228:231], v[112:127]
	v_mfma_f32_32x32x16_bf16 v[48:63], v[190:193], v[228:231], v[48:63]
	v_mfma_f32_32x32x16_bf16 v[80:95], v[182:185], v[232:235], v[80:95]
	v_mfma_f32_32x32x16_bf16 v[16:31], v[190:193], v[232:235], v[16:31]
	ds_read_u16 v181, v168 offset:16896
	ds_read_u16 v182, v168 offset:17424
	ds_read_u16 v183, v168 offset:17952
	ds_read_u16 v186, v168 offset:18480
	ds_read_u16 v187, v168 offset:18544
	ds_read_u16 v188, v168 offset:18016
	ds_read_u16 v220, v168 offset:17488
	ds_read_u16 v224, v168 offset:16960
	ds_read_u16 v184, v168 offset:19008
	ds_read_u16 v190, v168 offset:19536
	ds_read_u16 v185, v168 offset:20064
	ds_read_u16 v191, v168 offset:20592
	ds_read_u16 v221, v168 offset:20656
	ds_read_u16 v222, v168 offset:20128
	ds_read_u16 v225, v168 offset:19600
	ds_read_u16 v226, v168 offset:19072
	s_waitcnt lgkmcnt(4)
	v_perm_b32 v185, v191, v185, s19
	v_perm_b32 v184, v190, v184, s19
	v_perm_b32 v183, v186, v183, s19
	v_perm_b32 v182, v182, v181, s19
	s_waitcnt lgkmcnt(2)
	v_perm_b32 v223, v221, v222, s19
	s_waitcnt lgkmcnt(0)
	v_perm_b32 v222, v225, v226, s19
	v_perm_b32 v221, v187, v188, s19
	v_perm_b32 v220, v220, v224, s19
	ds_read_b128 v[190:193], v160 offset:64
	ds_read_b128 v[194:197], v160 offset:96
	s_waitcnt lgkmcnt(1)
	v_mfma_f32_32x32x16_bf16 v[64:79], v[182:185], v[190:193], v[64:79]
	v_mfma_f32_32x32x16_bf16 v[0:15], v[220:223], v[190:193], v[0:15]
	ds_read_b128 v[190:193], v160 offset:4672
	ds_read_b128 v[224:227], v160 offset:4704
	s_waitcnt lgkmcnt(1)
	v_mfma_f32_32x32x16_bf16 v[96:111], v[182:185], v[190:193], v[96:111]
	v_mfma_f32_32x32x16_bf16 v[32:47], v[220:223], v[190:193], v[32:47]
	ds_read_b128 v[190:193], v160 offset:9280
	ds_read_b128 v[228:231], v160 offset:9312
	s_waitcnt lgkmcnt(1)
	v_mfma_f32_32x32x16_bf16 v[112:127], v[182:185], v[190:193], v[112:127]
	v_mfma_f32_32x32x16_bf16 v[48:63], v[220:223], v[190:193], v[48:63]
	ds_read_b128 v[190:193], v160 offset:13888
	ds_read_b128 v[232:235], v160 offset:13920
	s_waitcnt lgkmcnt(1)
	v_mfma_f32_32x32x16_bf16 v[80:95], v[182:185], v[190:193], v[80:95]
	v_mfma_f32_32x32x16_bf16 v[16:31], v[220:223], v[190:193], v[16:31]
	ds_read_u16 v181, v168 offset:25344
	ds_read_u16 v182, v168 offset:25872
	ds_read_u16 v183, v168 offset:26400
	ds_read_u16 v186, v168 offset:26928
	ds_read_u16 v187, v168 offset:26992
	ds_read_u16 v188, v168 offset:26464
	ds_read_u16 v190, v168 offset:25936
	ds_read_u16 v220, v168 offset:25408
	ds_read_u16 v184, v168 offset:27456
	ds_read_u16 v191, v168 offset:27984
	ds_read_u16 v185, v168 offset:28512
	ds_read_u16 v192, v168 offset:29040
	ds_read_u16 v193, v168 offset:29104
	ds_read_u16 v221, v168 offset:28576
	ds_read_u16 v222, v168 offset:28048
	ds_read_u16 v223, v168 offset:27520
	s_waitcnt lgkmcnt(4)
	v_perm_b32 v185, v192, v185, s19
	v_perm_b32 v184, v191, v184, s19
	v_perm_b32 v183, v186, v183, s19
	v_perm_b32 v182, v182, v181, s19
	s_waitcnt lgkmcnt(2)
	v_perm_b32 v193, v193, v221, s19
	s_waitcnt lgkmcnt(0)
	v_perm_b32 v192, v222, v223, s19
	v_perm_b32 v191, v187, v188, s19
	v_perm_b32 v190, v190, v220, s19
	v_add_u32_e32 v181, 0x140, v169
	v_mad_i64_i32 v[186:187], s[28:29], v181, s67, v[146:147]
	v_add_u32_e32 v181, 0x140, v170
	v_mad_i64_i32 v[220:221], s[28:29], v181, s67, v[146:147]
	v_add_u32_e32 v181, 0x140, v171
	v_mfma_f32_32x32x16_bf16 v[64:79], v[182:185], v[194:197], v[64:79]
	v_mfma_f32_32x32x16_bf16 v[0:15], v[190:193], v[194:197], v[0:15]
	v_mfma_f32_32x32x16_bf16 v[96:111], v[182:185], v[224:227], v[96:111]
	v_mfma_f32_32x32x16_bf16 v[32:47], v[190:193], v[224:227], v[32:47]
	global_load_dwordx4 v[194:197], v[186:187], off
	s_nop 0
	global_load_dwordx4 v[220:223], v[220:221], off
	s_nop 0
	global_load_dwordx4 v[224:227], v[128:129], off offset:640
	global_load_dwordx4 v[236:239], v[130:131], off offset:640
	v_mad_i64_i32 v[186:187], s[28:29], v181, s67, v[146:147]
	v_add_u32_e32 v181, 0x140, v172
	v_mad_i64_i32 v[244:245], s[28:29], v181, s67, v[146:147]
	v_mfma_f32_32x32x16_bf16 v[112:127], v[182:185], v[228:231], v[112:127]
	v_mfma_f32_32x32x16_bf16 v[48:63], v[190:193], v[228:231], v[48:63]
	global_load_dwordx4 v[228:231], v[132:133], off offset:640
	global_load_dwordx4 v[240:243], v[186:187], off
	s_nop 0
	global_load_dwordx4 v[244:247], v[244:245], off
	v_mfma_f32_32x32x16_bf16 v[80:95], v[182:185], v[232:235], v[80:95]
	global_load_dwordx4 v[182:185], v[134:135], off offset:640
	s_barrier
; template <bool AT>
; DI void gemm_main(f32x16 (&acc)[2][4], const u16* __restrict__ R, int ldr, const u16* __restrict__ Cm, int ldc,
;                   const u16* __restrict__ RT, int ldrt, int K, char* smem, int tid) {
;     ...
;     if (kt + 1 < nk) {
;       const int ks1 = kt + 1;
;       u16* Rs = S0 + (ks1 & 1) * STG;
;       u16* Cs = Rs + 256 * 72;
; #pragma unroll
;       for (int i = 0; i < 4; ++i) {
;         const int cid = tid + NT * i;
;         const int row = cid >> 3, kc = cid & 7;
;         if (AT && ks1 < 8) {
;           const int kr = cid >> 5, tc = cid & 31;
;           *(u32x4*)(Rs + kr * 264 + tc * 8) = rr[i];
;         } else {
;           *(u32x4*)(Rs + row * 72 + kc * 8) = rr[i];
;         }
;         *(u32x4*)(Cs + row * 72 + kc * 8) = cr[i];
;       }
;     }
;     if (kt + 2 < nk) {
;       const int kn = kt + 2;
; #pragma unroll
;       for (int i = 0; i < 4; ++i) {
;         const int cid = tid + NT * i;
;         const int row = cid >> 3, kc = cid & 7;
;         if (AT && kn < 8) {
;           const int kr = cid >> 5, tc = cid & 31;
;           rr[i] = *(const u32x4*)(RT + (size_t)(kn * 64 + kr) * ldrt + tc * 8);
;         } else {
;           rr[i] = *(const u32x4*)(R + (size_t)row * ldr + kn * 64 + kc * 8);
;         }
;         cr[i] = *(const u32x4*)(Cm + (size_t)row * ldc + kn * 64 + kc * 8);
;       }
;     }
;     __builtin_amdgcn_sched_barrier(0x38F);
;     if (kt >= 0) {
;       const u16* Rs = S0 + (kt & 1) * STG;
;       const u16* Cs = Rs + 256 * 72;
;       const u16* RTs = Rs;
; #pragma unroll
;       for (int ks = 0; ks < 4; ++ks) {
;         bf16x8 rf[2];
; #pragma unroll
;         for (int rb = 0; rb < 2; ++rb) {
;           if (AT && kt < 8) {
;             const u16* src = RTs + (16 * ks + 8 * g) * 264 + 64 * wr + 32 * rb + li;
;             bf16x8 t;
; #pragma unroll
;             for (int j = 0; j < 8; ++j) t[j] = (short)src[j * 264];
;             rf[rb] = t;
;           } else {
;             rf[rb] = *(const bf16x8*)(Rs + (64 * wr + 32 * rb + li) * 72 + 16 * ks + 8 * g);
;           }
;         }
; #pragma unroll
;         for (int cb = 0; cb < 4; ++cb) {
;           const bf16x8 cfv = *(const bf16x8*)(Cs + (128 * wc + 32 * cb + li) * 72 + 16 * ks + 8 * g);
; #pragma unroll
;           for (int rb = 0; rb < 2; ++rb) acc[rb][cb] = MFMA(rf[rb], cfv, acc[rb][cb]);
;         }
;       }
;     }
	s_waitcnt vmcnt(7)
	ds_write_b128 v173, v[194:197]
	s_waitcnt vmcnt(5)
	ds_write_b128 v152, v[224:227]
	ds_write_b128 v174, v[220:223]
	s_waitcnt vmcnt(4)
	ds_write_b128 v153, v[236:239]
	s_waitcnt vmcnt(2)
	ds_write_b128 v175, v[240:243]
	ds_write_b128 v154, v[228:231]
	s_waitcnt vmcnt(1)
	ds_write_b128 v176, v[244:247]
	s_waitcnt vmcnt(0)
	ds_write_b128 v155, v[182:185]
	v_mfma_f32_32x32x16_bf16 v[16:31], v[190:193], v[232:235], v[16:31]
	ds_read_u16 v181, v167
	ds_read_u16 v182, v167 offset:528
	ds_read_u16 v183, v167 offset:1056
	ds_read_u16 v186, v167 offset:1584
	ds_read_u16 v187, v167 offset:1648
	ds_read_u16 v188, v167 offset:1120
	ds_read_u16 v220, v167 offset:592
	ds_read_u16 v224, v167 offset:64
	ds_read_u16 v184, v167 offset:2112
	ds_read_u16 v190, v167 offset:2640
	ds_read_u16 v185, v167 offset:3168
	ds_read_u16 v191, v167 offset:3696
	ds_read_u16 v221, v167 offset:3760
	ds_read_u16 v222, v167 offset:3232
	ds_read_u16 v225, v167 offset:2704
	ds_read_u16 v226, v167 offset:2176
	s_waitcnt lgkmcnt(4)
	v_perm_b32 v185, v191, v185, s19
	v_perm_b32 v184, v190, v184, s19
	v_perm_b32 v183, v186, v183, s19
	v_perm_b32 v182, v182, v181, s19
	s_waitcnt lgkmcnt(2)
	v_perm_b32 v223, v221, v222, s19
	s_waitcnt lgkmcnt(0)
	v_perm_b32 v222, v225, v226, s19
	v_perm_b32 v221, v187, v188, s19
	v_perm_b32 v220, v220, v224, s19
	ds_read_b128 v[190:193], v151 offset:36864
	ds_read_b128 v[194:197], v151 offset:36896
	s_waitcnt lgkmcnt(1)
	v_mfma_f32_32x32x16_bf16 v[64:79], v[182:185], v[190:193], v[64:79]
	v_mfma_f32_32x32x16_bf16 v[0:15], v[220:223], v[190:193], v[0:15]
	ds_read_b128 v[190:193], v151 offset:41472
	ds_read_b128 v[224:227], v151 offset:41504
	s_waitcnt lgkmcnt(1)
	v_mfma_f32_32x32x16_bf16 v[96:111], v[182:185], v[190:193], v[96:111]
	v_mfma_f32_32x32x16_bf16 v[32:47], v[220:223], v[190:193], v[32:47]
	ds_read_b128 v[190:193], v151 offset:46080
	ds_read_b128 v[228:231], v151 offset:46112
	s_waitcnt lgkmcnt(1)
	v_mfma_f32_32x32x16_bf16 v[112:127], v[182:185], v[190:193], v[112:127]
	v_mfma_f32_32x32x16_bf16 v[48:63], v[220:223], v[190:193], v[48:63]
	ds_read_b128 v[190:193], v151 offset:50688
	ds_read_b128 v[232:235], v151 offset:50720
	s_waitcnt lgkmcnt(1)
	v_mfma_f32_32x32x16_bf16 v[80:95], v[182:185], v[190:193], v[80:95]
	v_mfma_f32_32x32x16_bf16 v[16:31], v[220:223], v[190:193], v[16:31]
	ds_read_u16 v181, v167 offset:8448
	ds_read_u16 v182, v167 offset:8976
	ds_read_u16 v183, v167 offset:9504
	ds_read_u16 v186, v167 offset:10032
	ds_read_u16 v187, v167 offset:10096
	ds_read_u16 v188, v167 offset:9568
	ds_read_u16 v190, v167 offset:9040
	ds_read_u16 v220, v167 offset:8512
	ds_read_u16 v184, v167 offset:10560
	ds_read_u16 v191, v167 offset:11088
	ds_read_u16 v185, v167 offset:11616
	ds_read_u16 v192, v167 offset:12144
	ds_read_u16 v193, v167 offset:12208
	ds_read_u16 v221, v167 offset:11680
	ds_read_u16 v222, v167 offset:11152
	ds_read_u16 v223, v167 offset:10624
	s_waitcnt lgkmcnt(4)
	v_perm_b32 v185, v192, v185, s19
	v_perm_b32 v184, v191, v184, s19
	v_perm_b32 v183, v186, v183, s19
	v_perm_b32 v182, v182, v181, s19
	s_waitcnt lgkmcnt(2)
	v_perm_b32 v193, v193, v221, s19
	s_waitcnt lgkmcnt(0)
	v_perm_b32 v192, v222, v223, s19
	v_perm_b32 v191, v187, v188, s19
	v_perm_b32 v190, v190, v220, s19
	v_mfma_f32_32x32x16_bf16 v[64:79], v[182:185], v[194:197], v[64:79]
	s_nop 0
	v_mfma_f32_32x32x16_bf16 v[0:15], v[190:193], v[194:197], v[0:15]
	v_mfma_f32_32x32x16_bf16 v[96:111], v[182:185], v[224:227], v[96:111]
	v_mfma_f32_32x32x16_bf16 v[32:47], v[190:193], v[224:227], v[32:47]
	v_mfma_f32_32x32x16_bf16 v[112:127], v[182:185], v[228:231], v[112:127]
	v_mfma_f32_32x32x16_bf16 v[48:63], v[190:193], v[228:231], v[48:63]
	v_mfma_f32_32x32x16_bf16 v[80:95], v[182:185], v[232:235], v[80:95]
	v_mfma_f32_32x32x16_bf16 v[16:31], v[190:193], v[232:235], v[16:31]
	ds_read_u16 v181, v167 offset:16896
	ds_read_u16 v182, v167 offset:17424
	ds_read_u16 v183, v167 offset:17952
	ds_read_u16 v186, v167 offset:18480
	ds_read_u16 v187, v167 offset:18544
	ds_read_u16 v188, v167 offset:18016
	ds_read_u16 v220, v167 offset:17488
	ds_read_u16 v224, v167 offset:16960
	ds_read_u16 v184, v167 offset:19008
	ds_read_u16 v190, v167 offset:19536
	ds_read_u16 v185, v167 offset:20064
	ds_read_u16 v191, v167 offset:20592
	ds_read_u16 v221, v167 offset:20656
	ds_read_u16 v222, v167 offset:20128
	ds_read_u16 v225, v167 offset:19600
	ds_read_u16 v226, v167 offset:19072
	s_waitcnt lgkmcnt(4)
	v_perm_b32 v185, v191, v185, s19
	v_perm_b32 v184, v190, v184, s19
	v_perm_b32 v183, v186, v183, s19
	v_perm_b32 v182, v182, v181, s19
	s_waitcnt lgkmcnt(2)
	v_perm_b32 v223, v221, v222, s19
	s_waitcnt lgkmcnt(0)
	v_perm_b32 v222, v225, v226, s19
	v_perm_b32 v221, v187, v188, s19
	v_perm_b32 v220, v220, v224, s19
	ds_read_b128 v[190:193], v151 offset:36928
	ds_read_b128 v[194:197], v151 offset:36960
	s_waitcnt lgkmcnt(1)
	v_mfma_f32_32x32x16_bf16 v[64:79], v[182:185], v[190:193], v[64:79]
	v_mfma_f32_32x32x16_bf16 v[0:15], v[220:223], v[190:193], v[0:15]
	ds_read_b128 v[190:193], v151 offset:41536
	ds_read_b128 v[224:227], v151 offset:41568
	s_waitcnt lgkmcnt(1)
	v_mfma_f32_32x32x16_bf16 v[96:111], v[182:185], v[190:193], v[96:111]
	v_mfma_f32_32x32x16_bf16 v[32:47], v[220:223], v[190:193], v[32:47]
	ds_read_b128 v[190:193], v151 offset:46144
	ds_read_b128 v[228:231], v151 offset:46176
	s_waitcnt lgkmcnt(1)
	v_mfma_f32_32x32x16_bf16 v[112:127], v[182:185], v[190:193], v[112:127]
	v_mfma_f32_32x32x16_bf16 v[48:63], v[220:223], v[190:193], v[48:63]
	ds_read_b128 v[190:193], v151 offset:50752
	ds_read_b128 v[232:235], v151 offset:50784
	s_waitcnt lgkmcnt(1)
; template <bool AT>
; DI void gemm_main(f32x16 (&acc)[2][4], const u16* __restrict__ R, int ldr, const u16* __restrict__ Cm, int ldc,
;                   const u16* __restrict__ RT, int ldrt, int K, char* smem, int tid) {
;     ...
;     if (kt + 1 < nk) {
;       const int ks1 = kt + 1;
;       u16* Rs = S0 + (ks1 & 1) * STG;
;       u16* Cs = Rs + 256 * 72;
; #pragma unroll
;       for (int i = 0; i < 4; ++i) {
;         const int cid = tid + NT * i;
;         const int row = cid >> 3, kc = cid & 7;
;         if (AT && ks1 < 8) {
;           const int kr = cid >> 5, tc = cid & 31;
;           *(u32x4*)(Rs + kr * 264 + tc * 8) = rr[i];
;         } else {
;           *(u32x4*)(Rs + row * 72 + kc * 8) = rr[i];
;         }
;         *(u32x4*)(Cs + row * 72 + kc * 8) = cr[i];
;       }
;     }
;     if (kt + 2 < nk) {
;       const int kn = kt + 2;
; #pragma unroll
;       for (int i = 0; i < 4; ++i) {
;         const int cid = tid + NT * i;
;         const int row = cid >> 3, kc = cid & 7;
;         if (AT && kn < 8) {
;           const int kr = cid >> 5, tc = cid & 31;
;           rr[i] = *(const u32x4*)(RT + (size_t)(kn * 64 + kr) * ldrt + tc * 8);
;         } else {
;           rr[i] = *(const u32x4*)(R + (size_t)row * ldr + kn * 64 + kc * 8);
;         }
;         cr[i] = *(const u32x4*)(Cm + (size_t)row * ldc + kn * 64 + kc * 8);
;       }
;     }
;     __builtin_amdgcn_sched_barrier(0x38F);
;     if (kt >= 0) {
;       const u16* Rs = S0 + (kt & 1) * STG;
;       const u16* Cs = Rs + 256 * 72;
;       const u16* RTs = Rs;
; #pragma unroll
;       for (int ks = 0; ks < 4; ++ks) {
;         bf16x8 rf[2];
; #pragma unroll
;         for (int rb = 0; rb < 2; ++rb) {
;           if (AT && kt < 8) {
;             const u16* src = RTs + (16 * ks + 8 * g) * 264 + 64 * wr + 32 * rb + li;
;             bf16x8 t;
; #pragma unroll
;             for (int j = 0; j < 8; ++j) t[j] = (short)src[j * 264];
;             rf[rb] = t;
;           } else {
;             rf[rb] = *(const bf16x8*)(Rs + (64 * wr + 32 * rb + li) * 72 + 16 * ks + 8 * g);
;           }
;         }
; #pragma unroll
;         for (int cb = 0; cb < 4; ++cb) {
;           const bf16x8 cfv = *(const bf16x8*)(Cs + (128 * wc + 32 * cb + li) * 72 + 16 * ks + 8 * g);
; #pragma unroll
;           for (int rb = 0; rb < 2; ++rb) acc[rb][cb] = MFMA(rf[rb], cfv, acc[rb][cb]);
;         }
;       }
;     }
	v_mfma_f32_32x32x16_bf16 v[80:95], v[182:185], v[190:193], v[80:95]
	v_mfma_f32_32x32x16_bf16 v[16:31], v[220:223], v[190:193], v[16:31]
	ds_read_u16 v181, v167 offset:25344
	ds_read_u16 v182, v167 offset:25872
	ds_read_u16 v183, v167 offset:26400
	ds_read_u16 v186, v167 offset:26928
	ds_read_u16 v187, v167 offset:26992
	ds_read_u16 v188, v167 offset:26464
	ds_read_u16 v190, v167 offset:25936
	ds_read_u16 v220, v167 offset:25408
	ds_read_u16 v184, v167 offset:27456
	ds_read_u16 v191, v167 offset:27984
	ds_read_u16 v185, v167 offset:28512
	ds_read_u16 v192, v167 offset:29040
	ds_read_u16 v193, v167 offset:29104
	ds_read_u16 v221, v167 offset:28576
	ds_read_u16 v222, v167 offset:28048
	ds_read_u16 v223, v167 offset:27520
	s_waitcnt lgkmcnt(4)
	v_perm_b32 v185, v192, v185, s19
	v_perm_b32 v184, v191, v184, s19
	v_perm_b32 v183, v186, v183, s19
	v_perm_b32 v182, v182, v181, s19
	s_waitcnt lgkmcnt(2)
	v_perm_b32 v193, v193, v221, s19
	s_waitcnt lgkmcnt(0)
	v_perm_b32 v192, v222, v223, s19
	v_perm_b32 v191, v187, v188, s19
	v_perm_b32 v190, v190, v220, s19
	v_add_u32_e32 v181, 0x180, v169
	v_mad_i64_i32 v[186:187], s[28:29], v181, s67, v[146:147]
	v_add_u32_e32 v181, 0x180, v170
	v_mad_i64_i32 v[220:221], s[28:29], v181, s67, v[146:147]
	v_add_u32_e32 v181, 0x180, v171
	v_mfma_f32_32x32x16_bf16 v[64:79], v[182:185], v[194:197], v[64:79]
	v_add_u32_e32 v169, 0x1c0, v169
	v_mfma_f32_32x32x16_bf16 v[0:15], v[190:193], v[194:197], v[0:15]
	v_mfma_f32_32x32x16_bf16 v[96:111], v[182:185], v[224:227], v[96:111]
	v_mfma_f32_32x32x16_bf16 v[32:47], v[190:193], v[224:227], v[32:47]
	global_load_dwordx4 v[194:197], v[186:187], off
	s_nop 0
	global_load_dwordx4 v[220:223], v[220:221], off
	s_nop 0
	global_load_dwordx4 v[224:227], v[128:129], off offset:768
	global_load_dwordx4 v[236:239], v[130:131], off offset:768
	v_mad_i64_i32 v[186:187], s[28:29], v181, s67, v[146:147]
	v_add_u32_e32 v181, 0x180, v172
	v_mad_i64_i32 v[244:245], s[28:29], v181, s67, v[146:147]
	v_mfma_f32_32x32x16_bf16 v[112:127], v[182:185], v[228:231], v[112:127]
	v_mfma_f32_32x32x16_bf16 v[48:63], v[190:193], v[228:231], v[48:63]
	global_load_dwordx4 v[228:231], v[132:133], off offset:768
	global_load_dwordx4 v[240:243], v[186:187], off
	s_nop 0
	global_load_dwordx4 v[244:247], v[244:245], off
	v_mfma_f32_32x32x16_bf16 v[80:95], v[182:185], v[232:235], v[80:95]
	global_load_dwordx4 v[182:185], v[134:135], off offset:768
	s_barrier
	s_waitcnt vmcnt(7)
	ds_write_b128 v177, v[194:197]
	s_waitcnt vmcnt(5)
	ds_write_b128 v156, v[224:227] offset:36864
	ds_write_b128 v178, v[220:223]
	s_waitcnt vmcnt(4)
	ds_write_b128 v157, v[236:239] offset:36864
	s_waitcnt vmcnt(2)
	ds_write_b128 v179, v[240:243]
	ds_write_b128 v158, v[228:231] offset:36864
	s_waitcnt vmcnt(1)
	ds_write_b128 v180, v[244:247]
	s_waitcnt vmcnt(0)
	ds_write_b128 v159, v[182:185] offset:36864
	ds_read_u16 v177, v168
	ds_read_u16 v178, v168 offset:528
	ds_read_u16 v179, v168 offset:1056
	ds_read_u16 v182, v168 offset:1584
	ds_read_u16 v186, v168 offset:1648
	ds_read_u16 v187, v168 offset:1120
	ds_read_u16 v188, v168 offset:592
	ds_read_u16 v194, v168 offset:64
	ds_read_u16 v180, v168 offset:2112
	ds_read_u16 v183, v168 offset:2640
	ds_read_u16 v181, v168 offset:3168
	ds_read_u16 v184, v168 offset:3696
	ds_read_u16 v195, v168 offset:3760
	ds_read_u16 v196, v168 offset:3232
	ds_read_u16 v220, v168 offset:2704
	ds_read_u16 v221, v168 offset:2176
	s_waitcnt lgkmcnt(4)
	v_perm_b32 v181, v184, v181, s19
	v_perm_b32 v180, v183, v180, s19
	v_perm_b32 v179, v182, v179, s19
	v_perm_b32 v178, v178, v177, s19
	s_waitcnt lgkmcnt(2)
	v_perm_b32 v197, v195, v196, s19
	s_waitcnt lgkmcnt(0)
	v_perm_b32 v196, v220, v221, s19
	v_perm_b32 v195, v186, v187, s19
	v_perm_b32 v194, v188, v194, s19
	v_mfma_f32_32x32x16_bf16 v[16:31], v[190:193], v[232:235], v[16:31]
	ds_read_b128 v[182:185], v160
	ds_read_b128 v[190:193], v160 offset:32
	s_waitcnt lgkmcnt(1)
	v_mfma_f32_32x32x16_bf16 v[64:79], v[178:181], v[182:185], v[64:79]
	v_mfma_f32_32x32x16_bf16 v[0:15], v[194:197], v[182:185], v[0:15]
	ds_read_b128 v[182:185], v160 offset:4608
	ds_read_b128 v[220:223], v160 offset:4640
	s_waitcnt lgkmcnt(1)
	v_mfma_f32_32x32x16_bf16 v[96:111], v[178:181], v[182:185], v[96:111]
	v_mfma_f32_32x32x16_bf16 v[32:47], v[194:197], v[182:185], v[32:47]
	ds_read_b128 v[182:185], v160 offset:9216
	ds_read_b128 v[224:227], v160 offset:9248
	s_waitcnt lgkmcnt(1)
	v_mfma_f32_32x32x16_bf16 v[112:127], v[178:181], v[182:185], v[112:127]
	v_mfma_f32_32x32x16_bf16 v[48:63], v[194:197], v[182:185], v[48:63]
	ds_read_b128 v[182:185], v160 offset:13824
	ds_read_b128 v[228:231], v160 offset:13856
	s_waitcnt lgkmcnt(1)
	v_mfma_f32_32x32x16_bf16 v[80:95], v[178:181], v[182:185], v[80:95]
	v_mfma_f32_32x32x16_bf16 v[16:31], v[194:197], v[182:185], v[16:31]
	ds_read_u16 v177, v168 offset:8448
	ds_read_u16 v178, v168 offset:8976
	ds_read_u16 v179, v168 offset:9504
	ds_read_u16 v182, v168 offset:10032
	ds_read_u16 v183, v168 offset:10096
	ds_read_u16 v186, v168 offset:9568
	ds_read_u16 v187, v168 offset:9040
	ds_read_u16 v188, v168 offset:8512
	ds_read_u16 v180, v168 offset:10560
	ds_read_u16 v184, v168 offset:11088
	ds_read_u16 v181, v168 offset:11616
	ds_read_u16 v185, v168 offset:12144
	ds_read_u16 v194, v168 offset:12208
	ds_read_u16 v195, v168 offset:11680
	ds_read_u16 v196, v168 offset:11152
	ds_read_u16 v197, v168 offset:10624
	s_waitcnt lgkmcnt(4)
	v_perm_b32 v181, v185, v181, s19
	v_perm_b32 v180, v184, v180, s19
	v_perm_b32 v179, v182, v179, s19
	v_perm_b32 v178, v178, v177, s19
	s_waitcnt lgkmcnt(2)
	v_perm_b32 v185, v194, v195, s19
	s_waitcnt lgkmcnt(0)
; template <bool AT>
; DI void gemm_main(f32x16 (&acc)[2][4], const u16* __restrict__ R, int ldr, const u16* __restrict__ Cm, int ldc,
;                   const u16* __restrict__ RT, int ldrt, int K, char* smem, int tid) {
;     ...
;     if (kt + 1 < nk) {
;       const int ks1 = kt + 1;
;       u16* Rs = S0 + (ks1 & 1) * STG;
;       u16* Cs = Rs + 256 * 72;
; #pragma unroll
;       for (int i = 0; i < 4; ++i) {
;         const int cid = tid + NT * i;
;         const int row = cid >> 3, kc = cid & 7;
;         if (AT && ks1 < 8) {
;           const int kr = cid >> 5, tc = cid & 31;
;           *(u32x4*)(Rs + kr * 264 + tc * 8) = rr[i];
;         } else {
;           *(u32x4*)(Rs + row * 72 + kc * 8) = rr[i];
;         }
;         *(u32x4*)(Cs + row * 72 + kc * 8) = cr[i];
;       }
;     }
;     if (kt + 2 < nk) {
;       const int kn = kt + 2;
; #pragma unroll
;       for (int i = 0; i < 4; ++i) {
;         const int cid = tid + NT * i;
;         const int row = cid >> 3, kc = cid & 7;
;         if (AT && kn < 8) {
;           const int kr = cid >> 5, tc = cid & 31;
;           rr[i] = *(const u32x4*)(RT + (size_t)(kn * 64 + kr) * ldrt + tc * 8);
;         } else {
;           rr[i] = *(const u32x4*)(R + (size_t)row * ldr + kn * 64 + kc * 8);
;         }
;         cr[i] = *(const u32x4*)(Cm + (size_t)row * ldc + kn * 64 + kc * 8);
;       }
;     }
;     __builtin_amdgcn_sched_barrier(0x38F);
;     if (kt >= 0) {
;       const u16* Rs = S0 + (kt & 1) * STG;
;       const u16* Cs = Rs + 256 * 72;
;       const u16* RTs = Rs;
; #pragma unroll
;       for (int ks = 0; ks < 4; ++ks) {
;         bf16x8 rf[2];
; #pragma unroll
;         for (int rb = 0; rb < 2; ++rb) {
;           if (AT && kt < 8) {
;             const u16* src = RTs + (16 * ks + 8 * g) * 264 + 64 * wr + 32 * rb + li;
;             bf16x8 t;
; #pragma unroll
;             for (int j = 0; j < 8; ++j) t[j] = (short)src[j * 264];
;             rf[rb] = t;
;           } else {
;             rf[rb] = *(const bf16x8*)(Rs + (64 * wr + 32 * rb + li) * 72 + 16 * ks + 8 * g);
;           }
;         }
; #pragma unroll
;         for (int cb = 0; cb < 4; ++cb) {
;           const bf16x8 cfv = *(const bf16x8*)(Cs + (128 * wc + 32 * cb + li) * 72 + 16 * ks + 8 * g);
; #pragma unroll
;           for (int rb = 0; rb < 2; ++rb) acc[rb][cb] = MFMA(rf[rb], cfv, acc[rb][cb]);
;         }
;       }
;     }
	v_perm_b32 v184, v196, v197, s19
	v_perm_b32 v183, v183, v186, s19
	v_perm_b32 v182, v187, v188, s19
	v_mfma_f32_32x32x16_bf16 v[64:79], v[178:181], v[190:193], v[64:79]
	s_nop 0
	v_mfma_f32_32x32x16_bf16 v[0:15], v[182:185], v[190:193], v[0:15]
	v_mfma_f32_32x32x16_bf16 v[96:111], v[178:181], v[220:223], v[96:111]
	v_mfma_f32_32x32x16_bf16 v[32:47], v[182:185], v[220:223], v[32:47]
	v_mfma_f32_32x32x16_bf16 v[112:127], v[178:181], v[224:227], v[112:127]
	v_mfma_f32_32x32x16_bf16 v[48:63], v[182:185], v[224:227], v[48:63]
	v_mfma_f32_32x32x16_bf16 v[80:95], v[178:181], v[228:231], v[80:95]
	v_mfma_f32_32x32x16_bf16 v[16:31], v[182:185], v[228:231], v[16:31]
	ds_read_u16 v177, v168 offset:16896
	ds_read_u16 v178, v168 offset:17424
	ds_read_u16 v179, v168 offset:17952
	ds_read_u16 v182, v168 offset:18480
	ds_read_u16 v186, v168 offset:18544
	ds_read_u16 v187, v168 offset:18016
	ds_read_u16 v188, v168 offset:17488
	ds_read_u16 v194, v168 offset:16960
	ds_read_u16 v180, v168 offset:19008
	ds_read_u16 v183, v168 offset:19536
	ds_read_u16 v181, v168 offset:20064
	ds_read_u16 v184, v168 offset:20592
	ds_read_u16 v195, v168 offset:20656
	ds_read_u16 v196, v168 offset:20128
	ds_read_u16 v220, v168 offset:19600
	ds_read_u16 v221, v168 offset:19072
	s_waitcnt lgkmcnt(4)
	v_perm_b32 v181, v184, v181, s19
	v_perm_b32 v180, v183, v180, s19
	v_perm_b32 v179, v182, v179, s19
	v_perm_b32 v178, v178, v177, s19
	s_waitcnt lgkmcnt(2)
	v_perm_b32 v197, v195, v196, s19
	s_waitcnt lgkmcnt(0)
	v_perm_b32 v196, v220, v221, s19
	v_perm_b32 v195, v186, v187, s19
	v_perm_b32 v194, v188, v194, s19
	ds_read_b128 v[182:185], v160 offset:64
	ds_read_b128 v[190:193], v160 offset:96
	s_waitcnt lgkmcnt(1)
	v_mfma_f32_32x32x16_bf16 v[64:79], v[178:181], v[182:185], v[64:79]
	v_mfma_f32_32x32x16_bf16 v[0:15], v[194:197], v[182:185], v[0:15]
	ds_read_b128 v[182:185], v160 offset:4672
	ds_read_b128 v[220:223], v160 offset:4704
	s_waitcnt lgkmcnt(1)
	v_mfma_f32_32x32x16_bf16 v[96:111], v[178:181], v[182:185], v[96:111]
	v_mfma_f32_32x32x16_bf16 v[32:47], v[194:197], v[182:185], v[32:47]
	ds_read_b128 v[182:185], v160 offset:9280
	ds_read_b128 v[224:227], v160 offset:9312
	s_waitcnt lgkmcnt(1)
	v_mfma_f32_32x32x16_bf16 v[112:127], v[178:181], v[182:185], v[112:127]
	v_mfma_f32_32x32x16_bf16 v[48:63], v[194:197], v[182:185], v[48:63]
	ds_read_b128 v[182:185], v160 offset:13888
	ds_read_b128 v[228:231], v160 offset:13920
	s_waitcnt lgkmcnt(1)
	v_mfma_f32_32x32x16_bf16 v[80:95], v[178:181], v[182:185], v[80:95]
	v_mfma_f32_32x32x16_bf16 v[16:31], v[194:197], v[182:185], v[16:31]
	ds_read_u16 v177, v168 offset:25344
	ds_read_u16 v178, v168 offset:25872
	ds_read_u16 v179, v168 offset:26400
	ds_read_u16 v182, v168 offset:26928
	ds_read_u16 v183, v168 offset:26992
	ds_read_u16 v186, v168 offset:26464
	ds_read_u16 v187, v168 offset:25936
	ds_read_u16 v188, v168 offset:25408
	ds_read_u16 v180, v168 offset:27456
	ds_read_u16 v184, v168 offset:27984
	ds_read_u16 v181, v168 offset:28512
	ds_read_u16 v185, v168 offset:29040
	ds_read_u16 v194, v168 offset:29104
	ds_read_u16 v195, v168 offset:28576
	ds_read_u16 v196, v168 offset:28048
	ds_read_u16 v197, v168 offset:27520
	s_waitcnt lgkmcnt(4)
	v_perm_b32 v181, v185, v181, s19
	v_perm_b32 v180, v184, v180, s19
	v_perm_b32 v179, v182, v179, s19
	v_perm_b32 v178, v178, v177, s19
	s_waitcnt lgkmcnt(2)
	v_perm_b32 v185, v194, v195, s19
	s_waitcnt lgkmcnt(0)
	v_perm_b32 v184, v196, v197, s19
	v_perm_b32 v183, v183, v186, s19
	v_perm_b32 v182, v187, v188, s19
	v_mad_i64_i32 v[186:187], s[28:29], v169, s67, v[146:147]
	v_add_u32_e32 v169, 0x1c0, v170
	v_mad_i64_i32 v[194:195], s[28:29], v169, s67, v[146:147]
	v_add_u32_e32 v169, 0x1c0, v171
	v_mad_i64_i32 v[170:171], s[28:29], v169, s67, v[146:147]
	v_add_u32_e32 v169, 0x1c0, v172
	v_mfma_f32_32x32x16_bf16 v[64:79], v[178:181], v[190:193], v[64:79]
	v_mad_i64_i32 v[146:147], s[28:29], v169, s67, v[146:147]
	v_mfma_f32_32x32x16_bf16 v[0:15], v[182:185], v[190:193], v[0:15]
	v_mfma_f32_32x32x16_bf16 v[96:111], v[178:181], v[220:223], v[96:111]
	v_mfma_f32_32x32x16_bf16 v[32:47], v[182:185], v[220:223], v[32:47]
	global_load_dwordx4 v[190:193], v[186:187], off
	s_nop 0
	global_load_dwordx4 v[194:197], v[194:195], off
	s_nop 0
	global_load_dwordx4 v[220:223], v[128:129], off offset:896
	global_load_dwordx4 v[232:235], v[130:131], off offset:896
	v_mfma_f32_32x32x16_bf16 v[112:127], v[178:181], v[224:227], v[112:127]
	v_mfma_f32_32x32x16_bf16 v[48:63], v[182:185], v[224:227], v[48:63]
	global_load_dwordx4 v[224:227], v[132:133], off offset:896
	global_load_dwordx4 v[236:239], v[170:171], off
	global_load_dwordx4 v[240:243], v[146:147], off
	v_mfma_f32_32x32x16_bf16 v[80:95], v[178:181], v[228:231], v[80:95]
	global_load_dwordx4 v[178:181], v[134:135], off offset:896
	s_barrier
; template <bool AT>
; DI void gemm_main(f32x16 (&acc)[2][4], const u16* __restrict__ R, int ldr, const u16* __restrict__ Cm, int ldc,
;                   const u16* __restrict__ RT, int ldrt, int K, char* smem, int tid) {
;     ...
;   for (int kt = -1; kt < nk; ++kt) {
;     if (kt + 1 < nk) {
;       const int ks1 = kt + 1;
;       u16* Rs = S0 + (ks1 & 1) * STG;
;       u16* Cs = Rs + 256 * 72;
; #pragma unroll
;       for (int i = 0; i < 4; ++i) {
;         const int cid = tid + NT * i;
;         const int row = cid >> 3, kc = cid & 7;
;         if (AT && ks1 < 8) {
;           const int kr = cid >> 5, tc = cid & 31;
;           *(u32x4*)(Rs + kr * 264 + tc * 8) = rr[i];
;         } else {
;           *(u32x4*)(Rs + row * 72 + kc * 8) = rr[i];
;         }
;         *(u32x4*)(Cs + row * 72 + kc * 8) = cr[i];
;       }
;     }
;     if (kt + 2 < nk) {
;       const int kn = kt + 2;
; #pragma unroll
;       for (int i = 0; i < 4; ++i) {
;         const int cid = tid + NT * i;
;         const int row = cid >> 3, kc = cid & 7;
;         if (AT && kn < 8) {
;           const int kr = cid >> 5, tc = cid & 31;
;           rr[i] = *(const u32x4*)(RT + (size_t)(kn * 64 + kr) * ldrt + tc * 8);
;         } else {
;           rr[i] = *(const u32x4*)(R + (size_t)row * ldr + kn * 64 + kc * 8);
;         }
;         cr[i] = *(const u32x4*)(Cm + (size_t)row * ldc + kn * 64 + kc * 8);
;       }
;     }
;     __builtin_amdgcn_sched_barrier(0x38F);
;     if (kt >= 0) {
;       const u16* Rs = S0 + (kt & 1) * STG;
;       const u16* Cs = Rs + 256 * 72;
;       const u16* RTs = Rs;
; #pragma unroll
;       for (int ks = 0; ks < 4; ++ks) {
;         bf16x8 rf[2];
; #pragma unroll
;         for (int rb = 0; rb < 2; ++rb) {
;           if (AT && kt < 8) {
;             const u16* src = RTs + (16 * ks + 8 * g) * 264 + 64 * wr + 32 * rb + li;
;             bf16x8 t;
; #pragma unroll
;             for (int j = 0; j < 8; ++j) t[j] = (short)src[j * 264];
;             rf[rb] = t;
;           } else {
;             rf[rb] = *(const bf16x8*)(Rs + (64 * wr + 32 * rb + li) * 72 + 16 * ks + 8 * g);
;           }
;         }
; #pragma unroll
;         for (int cb = 0; cb < 4; ++cb) {
;           const bf16x8 cfv = *(const bf16x8*)(Cs + (128 * wc + 32 * cb + li) * 72 + 16 * ks + 8 * g);
; #pragma unroll
;           for (int rb = 0; rb < 2; ++rb) acc[rb][cb] = MFMA(rf[rb], cfv, acc[rb][cb]);
	s_waitcnt vmcnt(7)
	ds_write_b128 v173, v[190:193]
	s_waitcnt vmcnt(5)
	ds_write_b128 v152, v[220:223]
	ds_write_b128 v174, v[194:197]
	s_waitcnt vmcnt(4)
	ds_write_b128 v153, v[232:235]
	s_waitcnt vmcnt(2)
	ds_write_b128 v175, v[236:239]
	ds_write_b128 v154, v[224:227]
	s_waitcnt vmcnt(1)
	ds_write_b128 v176, v[240:243]
	s_waitcnt vmcnt(0)
	ds_write_b128 v155, v[178:181]
	v_mfma_f32_32x32x16_bf16 v[16:31], v[182:185], v[228:231], v[16:31]
	ds_read_u16 v146, v167
	ds_read_u16 v147, v167 offset:528
	ds_read_u16 v169, v167 offset:1056
	ds_read_u16 v170, v167 offset:1584
	ds_read_u16 v182, v167 offset:1648
	ds_read_u16 v183, v167 offset:1120
	ds_read_u16 v186, v167 offset:592
	ds_read_u16 v187, v167 offset:64
	ds_read_u16 v171, v167 offset:2112
	ds_read_u16 v172, v167 offset:2640
	ds_read_u16 v173, v167 offset:3168
	ds_read_u16 v174, v167 offset:3696
	ds_read_u16 v184, v167 offset:3760
	ds_read_u16 v185, v167 offset:3232
	ds_read_u16 v188, v167 offset:2704
	ds_read_u16 v190, v167 offset:2176
	s_waitcnt lgkmcnt(4)
	v_perm_b32 v173, v174, v173, s19
	v_perm_b32 v172, v172, v171, s19
	v_perm_b32 v171, v170, v169, s19
	v_perm_b32 v170, v147, v146, s19
	s_waitcnt lgkmcnt(2)
	v_perm_b32 v185, v184, v185, s19
	s_waitcnt lgkmcnt(0)
	v_perm_b32 v184, v188, v190, s19
	v_perm_b32 v183, v182, v183, s19
	v_perm_b32 v182, v186, v187, s19
	ds_read_b128 v[174:177], v151 offset:36864
	ds_read_b128 v[178:181], v151 offset:36896
	s_waitcnt lgkmcnt(1)
	v_mfma_f32_32x32x16_bf16 v[64:79], v[170:173], v[174:177], v[64:79]
	v_mfma_f32_32x32x16_bf16 v[0:15], v[182:185], v[174:177], v[0:15]
	ds_read_b128 v[174:177], v151 offset:41472
	ds_read_b128 v[190:193], v151 offset:41504
	s_waitcnt lgkmcnt(1)
	v_mfma_f32_32x32x16_bf16 v[96:111], v[170:173], v[174:177], v[96:111]
	v_mfma_f32_32x32x16_bf16 v[32:47], v[182:185], v[174:177], v[32:47]
	ds_read_b128 v[174:177], v151 offset:46080
	ds_read_b128 v[194:197], v151 offset:46112
	s_waitcnt lgkmcnt(1)
	v_mfma_f32_32x32x16_bf16 v[112:127], v[170:173], v[174:177], v[112:127]
	v_mfma_f32_32x32x16_bf16 v[48:63], v[182:185], v[174:177], v[48:63]
	ds_read_b128 v[174:177], v151 offset:50688
	ds_read_b128 v[220:223], v151 offset:50720
	s_waitcnt lgkmcnt(1)
	v_mfma_f32_32x32x16_bf16 v[80:95], v[170:173], v[174:177], v[80:95]
	v_mfma_f32_32x32x16_bf16 v[16:31], v[182:185], v[174:177], v[16:31]
	ds_read_u16 v146, v167 offset:8448
	ds_read_u16 v147, v167 offset:8976
	ds_read_u16 v169, v167 offset:9504
	ds_read_u16 v170, v167 offset:10032
	ds_read_u16 v174, v167 offset:10096
	ds_read_u16 v175, v167 offset:9568
	ds_read_u16 v182, v167 offset:9040
	ds_read_u16 v183, v167 offset:8512
	ds_read_u16 v171, v167 offset:10560
	ds_read_u16 v172, v167 offset:11088
	ds_read_u16 v173, v167 offset:11616
	ds_read_u16 v176, v167 offset:12144
	ds_read_u16 v177, v167 offset:12208
	ds_read_u16 v184, v167 offset:11680
	ds_read_u16 v185, v167 offset:11152
	ds_read_u16 v186, v167 offset:10624
	s_waitcnt lgkmcnt(4)
	v_perm_b32 v173, v176, v173, s19
	v_perm_b32 v172, v172, v171, s19
	v_perm_b32 v171, v170, v169, s19
	v_perm_b32 v170, v147, v146, s19
	s_waitcnt lgkmcnt(2)
	v_perm_b32 v177, v177, v184, s19
	s_waitcnt lgkmcnt(0)
	v_perm_b32 v176, v185, v186, s19
	v_perm_b32 v175, v174, v175, s19
	v_perm_b32 v174, v182, v183, s19
	v_mfma_f32_32x32x16_bf16 v[64:79], v[170:173], v[178:181], v[64:79]
	s_nop 0
	v_mfma_f32_32x32x16_bf16 v[0:15], v[174:177], v[178:181], v[0:15]
	v_mfma_f32_32x32x16_bf16 v[96:111], v[170:173], v[190:193], v[96:111]
	v_mfma_f32_32x32x16_bf16 v[32:47], v[174:177], v[190:193], v[32:47]
	v_mfma_f32_32x32x16_bf16 v[112:127], v[170:173], v[194:197], v[112:127]
	v_mfma_f32_32x32x16_bf16 v[48:63], v[174:177], v[194:197], v[48:63]
	v_mfma_f32_32x32x16_bf16 v[80:95], v[170:173], v[220:223], v[80:95]
	v_mfma_f32_32x32x16_bf16 v[16:31], v[174:177], v[220:223], v[16:31]
	ds_read_u16 v146, v167 offset:16896
	ds_read_u16 v147, v167 offset:17424
	ds_read_u16 v169, v167 offset:17952
	ds_read_u16 v170, v167 offset:18480
	ds_read_u16 v182, v167 offset:18544
	ds_read_u16 v183, v167 offset:18016
	ds_read_u16 v186, v167 offset:17488
	ds_read_u16 v187, v167 offset:16960
	ds_read_u16 v171, v167 offset:19008
	ds_read_u16 v172, v167 offset:19536
	ds_read_u16 v173, v167 offset:20064
	ds_read_u16 v174, v167 offset:20592
	ds_read_u16 v184, v167 offset:20656
	ds_read_u16 v185, v167 offset:20128
	ds_read_u16 v188, v167 offset:19600
	ds_read_u16 v190, v167 offset:19072
	s_waitcnt lgkmcnt(4)
	v_perm_b32 v173, v174, v173, s19
	v_perm_b32 v172, v172, v171, s19
	v_perm_b32 v171, v170, v169, s19
	v_perm_b32 v170, v147, v146, s19
	s_waitcnt lgkmcnt(2)
	v_perm_b32 v185, v184, v185, s19
	s_waitcnt lgkmcnt(0)
	v_perm_b32 v184, v188, v190, s19
	v_perm_b32 v183, v182, v183, s19
	v_perm_b32 v182, v186, v187, s19
	ds_read_b128 v[174:177], v151 offset:36928
	ds_read_b128 v[178:181], v151 offset:36960
	s_waitcnt lgkmcnt(1)
	v_mfma_f32_32x32x16_bf16 v[64:79], v[170:173], v[174:177], v[64:79]
	v_mfma_f32_32x32x16_bf16 v[0:15], v[182:185], v[174:177], v[0:15]
	ds_read_b128 v[174:177], v151 offset:41536
	ds_read_b128 v[190:193], v151 offset:41568
	s_waitcnt lgkmcnt(1)
	v_mfma_f32_32x32x16_bf16 v[96:111], v[170:173], v[174:177], v[96:111]
	v_mfma_f32_32x32x16_bf16 v[32:47], v[182:185], v[174:177], v[32:47]
	ds_read_b128 v[174:177], v151 offset:46144
	ds_read_b128 v[194:197], v151 offset:46176
	s_waitcnt lgkmcnt(1)
	v_mfma_f32_32x32x16_bf16 v[112:127], v[170:173], v[174:177], v[112:127]
	v_mfma_f32_32x32x16_bf16 v[48:63], v[182:185], v[174:177], v[48:63]
	ds_read_b128 v[174:177], v151 offset:50752
	ds_read_b128 v[220:223], v151 offset:50784
	s_waitcnt lgkmcnt(1)
; template <bool AT>
; DI void gemm_main(f32x16 (&acc)[2][4], const u16* __restrict__ R, int ldr, const u16* __restrict__ Cm, int ldc,
;                   const u16* __restrict__ RT, int ldrt, int K, char* smem, int tid) {
;     ...
;   for (int kt = -1; kt < nk; ++kt) {
;     if (kt + 1 < nk) {
;       const int ks1 = kt + 1;
;       u16* Rs = S0 + (ks1 & 1) * STG;
;       u16* Cs = Rs + 256 * 72;
; #pragma unroll
;       for (int i = 0; i < 4; ++i) {
;         const int cid = tid + NT * i;
;         const int row = cid >> 3, kc = cid & 7;
;         if (AT && ks1 < 8) {
;           const int kr = cid >> 5, tc = cid & 31;
;           *(u32x4*)(Rs + kr * 264 + tc * 8) = rr[i];
;         } else {
;           *(u32x4*)(Rs + row * 72 + kc * 8) = rr[i];
;         }
;         *(u32x4*)(Cs + row * 72 + kc * 8) = cr[i];
;       }
;     }
;     if (kt + 2 < nk) {
;       const int kn = kt + 2;
; #pragma unroll
;       for (int i = 0; i < 4; ++i) {
;         const int cid = tid + NT * i;
;         const int row = cid >> 3, kc = cid & 7;
;         if (AT && kn < 8) {
;           const int kr = cid >> 5, tc = cid & 31;
;           rr[i] = *(const u32x4*)(RT + (size_t)(kn * 64 + kr) * ldrt + tc * 8);
;         } else {
;           rr[i] = *(const u32x4*)(R + (size_t)row * ldr + kn * 64 + kc * 8);
;         }
;         cr[i] = *(const u32x4*)(Cm + (size_t)row * ldc + kn * 64 + kc * 8);
;       }
;     }
;     __builtin_amdgcn_sched_barrier(0x38F);
;     if (kt >= 0) {
;       const u16* Rs = S0 + (kt & 1) * STG;
;       const u16* Cs = Rs + 256 * 72;
;       const u16* RTs = Rs;
; #pragma unroll
;       for (int ks = 0; ks < 4; ++ks) {
;         bf16x8 rf[2];
; #pragma unroll
;         for (int rb = 0; rb < 2; ++rb) {
;           if (AT && kt < 8) {
;             const u16* src = RTs + (16 * ks + 8 * g) * 264 + 64 * wr + 32 * rb + li;
;             bf16x8 t;
; #pragma unroll
;             for (int j = 0; j < 8; ++j) t[j] = (short)src[j * 264];
;             rf[rb] = t;
;           } else {
;             rf[rb] = *(const bf16x8*)(Rs + (64 * wr + 32 * rb + li) * 72 + 16 * ks + 8 * g);
;           }
;         }
; #pragma unroll
;         for (int cb = 0; cb < 4; ++cb) {
;           const bf16x8 cfv = *(const bf16x8*)(Cs + (128 * wc + 32 * cb + li) * 72 + 16 * ks + 8 * g);
; #pragma unroll
;           for (int rb = 0; rb < 2; ++rb) acc[rb][cb] = MFMA(rf[rb], cfv, acc[rb][cb]);
	v_mfma_f32_32x32x16_bf16 v[80:95], v[170:173], v[174:177], v[80:95]
	v_mfma_f32_32x32x16_bf16 v[16:31], v[182:185], v[174:177], v[16:31]
	ds_read_u16 v146, v167 offset:25344
	ds_read_u16 v147, v167 offset:25872
	ds_read_u16 v169, v167 offset:26400
	ds_read_u16 v170, v167 offset:26928
	ds_read_u16 v174, v167 offset:26992
	ds_read_u16 v175, v167 offset:26464
	ds_read_u16 v182, v167 offset:25936
	ds_read_u16 v183, v167 offset:25408
	ds_read_u16 v171, v167 offset:27456
	ds_read_u16 v172, v167 offset:27984
	ds_read_u16 v173, v167 offset:28512
	ds_read_u16 v176, v167 offset:29040
	ds_read_u16 v177, v167 offset:29104
	ds_read_u16 v184, v167 offset:28576
	ds_read_u16 v185, v167 offset:28048
	ds_read_u16 v167, v167 offset:27520
	s_waitcnt lgkmcnt(4)
	v_perm_b32 v173, v176, v173, s19
	v_perm_b32 v172, v172, v171, s19
	v_perm_b32 v171, v170, v169, s19
	v_perm_b32 v170, v147, v146, s19
	s_waitcnt lgkmcnt(2)
	v_perm_b32 v177, v177, v184, s19
	s_waitcnt lgkmcnt(0)
	v_perm_b32 v176, v185, v167, s19
	v_perm_b32 v175, v174, v175, s19
	v_perm_b32 v174, v182, v183, s19
	v_lshl_add_u64 v[146:147], s[6:7], 0, v[136:137]
	v_lshl_add_u64 v[138:139], v[146:147], 0, v[138:139]
	v_lshl_add_u64 v[142:143], v[146:147], 0, v[142:143]
	v_mfma_f32_32x32x16_bf16 v[64:79], v[170:173], v[178:181], v[64:79]
	v_lshl_add_u64 v[140:141], v[146:147], 0, v[140:141]
	v_lshl_add_u64 v[144:145], v[146:147], 0, v[144:145]
	v_add_u32_e32 v136, s26, v136
	s_lshl_b32 s6, s24, 8
	v_mfma_f32_32x32x16_bf16 v[0:15], v[174:177], v[178:181], v[0:15]
	global_load_dwordx4 v[178:181], v[138:139], off
	global_load_dwordx4 v[182:185], v[140:141], off
	v_mfma_f32_32x32x16_bf16 v[96:111], v[170:173], v[190:193], v[96:111]
	v_mfma_f32_32x32x16_bf16 v[32:47], v[174:177], v[190:193], v[32:47]
	v_mfma_f32_32x32x16_bf16 v[112:127], v[170:173], v[194:197], v[112:127]
	v_mfma_f32_32x32x16_bf16 v[48:63], v[174:177], v[194:197], v[48:63]
	global_load_dwordx4 v[190:193], v[128:129], off offset:1024
	global_load_dwordx4 v[194:197], v[130:131], off offset:1024
	global_load_dwordx4 v[224:227], v[132:133], off offset:1024
	global_load_dwordx4 v[228:231], v[142:143], off
	global_load_dwordx4 v[232:235], v[144:145], off
	v_mfma_f32_32x32x16_bf16 v[80:95], v[170:173], v[220:223], v[80:95]
	global_load_dwordx4 v[170:173], v[134:135], off offset:1024
	s_barrier
	s_waitcnt vmcnt(7)
	ds_write_b128 v156, v[178:181]
	s_waitcnt vmcnt(5)
	ds_write_b128 v156, v[190:193] offset:36864
	ds_write_b128 v157, v[182:185]
	s_waitcnt vmcnt(4)
	ds_write_b128 v157, v[194:197] offset:36864
	s_waitcnt vmcnt(2)
	ds_write_b128 v158, v[228:231]
	ds_write_b128 v158, v[224:227] offset:36864
	s_waitcnt vmcnt(1)
	ds_write_b128 v159, v[232:235]
	s_waitcnt vmcnt(0)
	ds_write_b128 v159, v[170:173] offset:36864
	ds_read_u16 v137, v168
	ds_read_u16 v146, v168 offset:528
	ds_read_u16 v147, v168 offset:1056
	ds_read_u16 v167, v168 offset:1584
	ds_read_u16 v169, v168 offset:1648
	ds_read_u16 v182, v168 offset:1120
	ds_read_u16 v186, v168 offset:592
	ds_read_u16 v187, v168 offset:64
	ds_read_u16 v170, v168 offset:2112
	ds_read_u16 v171, v168 offset:2640
	ds_read_u16 v172, v168 offset:3168
	ds_read_u16 v173, v168 offset:3696
	ds_read_u16 v183, v168 offset:3760
	ds_read_u16 v184, v168 offset:3232
	ds_read_u16 v188, v168 offset:2704
	ds_read_u16 v190, v168 offset:2176
	s_waitcnt lgkmcnt(4)
	v_perm_b32 v173, v173, v172, s19
	v_perm_b32 v172, v171, v170, s19
	v_perm_b32 v171, v167, v147, s19
	v_perm_b32 v170, v146, v137, s19
	s_waitcnt lgkmcnt(2)
	v_perm_b32 v185, v183, v184, s19
	s_waitcnt lgkmcnt(0)
	v_perm_b32 v184, v188, v190, s19
	v_perm_b32 v183, v169, v182, s19
	v_perm_b32 v182, v186, v187, s19
	v_mfma_f32_32x32x16_bf16 v[16:31], v[174:177], v[220:223], v[16:31]
	ds_read_b128 v[174:177], v160
	ds_read_b128 v[178:181], v160 offset:32
	s_waitcnt lgkmcnt(1)
	v_mfma_f32_32x32x16_bf16 v[64:79], v[170:173], v[174:177], v[64:79]
	v_mfma_f32_32x32x16_bf16 v[0:15], v[182:185], v[174:177], v[0:15]
	ds_read_b128 v[174:177], v160 offset:4608
	ds_read_b128 v[190:193], v160 offset:4640
	s_waitcnt lgkmcnt(1)
	v_mfma_f32_32x32x16_bf16 v[96:111], v[170:173], v[174:177], v[96:111]
	v_mfma_f32_32x32x16_bf16 v[32:47], v[182:185], v[174:177], v[32:47]
	ds_read_b128 v[174:177], v160 offset:9216
	ds_read_b128 v[194:197], v160 offset:9248
	s_waitcnt lgkmcnt(1)
	v_mfma_f32_32x32x16_bf16 v[112:127], v[170:173], v[174:177], v[112:127]
	v_mfma_f32_32x32x16_bf16 v[48:63], v[182:185], v[174:177], v[48:63]
	ds_read_b128 v[174:177], v160 offset:13824
	ds_read_b128 v[220:223], v160 offset:13856
	s_waitcnt lgkmcnt(1)
	v_mfma_f32_32x32x16_bf16 v[80:95], v[170:173], v[174:177], v[80:95]
	v_mfma_f32_32x32x16_bf16 v[16:31], v[182:185], v[174:177], v[16:31]
	ds_read_u16 v137, v168 offset:8448
	ds_read_u16 v146, v168 offset:8976
	ds_read_u16 v147, v168 offset:9504
	ds_read_u16 v167, v168 offset:10032
	ds_read_u16 v169, v168 offset:10096
	ds_read_u16 v174, v168 offset:9568
	ds_read_u16 v182, v168 offset:9040
	ds_read_u16 v183, v168 offset:8512
	ds_read_u16 v170, v168 offset:10560
	ds_read_u16 v171, v168 offset:11088
	ds_read_u16 v172, v168 offset:11616
	ds_read_u16 v173, v168 offset:12144
	ds_read_u16 v175, v168 offset:12208
	ds_read_u16 v176, v168 offset:11680
	ds_read_u16 v184, v168 offset:11152
	ds_read_u16 v185, v168 offset:10624
	s_waitcnt lgkmcnt(4)
	v_perm_b32 v173, v173, v172, s19
	v_perm_b32 v172, v171, v170, s19
	v_perm_b32 v171, v167, v147, s19
	v_perm_b32 v170, v146, v137, s19
	s_waitcnt lgkmcnt(2)
	v_perm_b32 v177, v175, v176, s19
	s_waitcnt lgkmcnt(0)
; template <bool AT>
; DI void gemm_main(f32x16 (&acc)[2][4], const u16* __restrict__ R, int ldr, const u16* __restrict__ Cm, int ldc,
;                   const u16* __restrict__ RT, int ldrt, int K, char* smem, int tid) {
;     ...
;   for (int kt = -1; kt < nk; ++kt) {
;     if (kt + 1 < nk) {
;       const int ks1 = kt + 1;
;       u16* Rs = S0 + (ks1 & 1) * STG;
;       u16* Cs = Rs + 256 * 72;
; #pragma unroll
;       for (int i = 0; i < 4; ++i) {
;         const int cid = tid + NT * i;
;         const int row = cid >> 3, kc = cid & 7;
;         if (AT && ks1 < 8) {
;           const int kr = cid >> 5, tc = cid & 31;
;           *(u32x4*)(Rs + kr * 264 + tc * 8) = rr[i];
;         } else {
;           *(u32x4*)(Rs + row * 72 + kc * 8) = rr[i];
;         }
;         *(u32x4*)(Cs + row * 72 + kc * 8) = cr[i];
;       }
;     }
;     if (kt + 2 < nk) {
;       const int kn = kt + 2;
; #pragma unroll
;       for (int i = 0; i < 4; ++i) {
;         const int cid = tid + NT * i;
;         const int row = cid >> 3, kc = cid & 7;
;         if (AT && kn < 8) {
;           const int kr = cid >> 5, tc = cid & 31;
;           rr[i] = *(const u32x4*)(RT + (size_t)(kn * 64 + kr) * ldrt + tc * 8);
;         } else {
;           rr[i] = *(const u32x4*)(R + (size_t)row * ldr + kn * 64 + kc * 8);
;         }
;         cr[i] = *(const u32x4*)(Cm + (size_t)row * ldc + kn * 64 + kc * 8);
;       }
;     }
;     __builtin_amdgcn_sched_barrier(0x38F);
;     if (kt >= 0) {
;       const u16* Rs = S0 + (kt & 1) * STG;
;       const u16* Cs = Rs + 256 * 72;
;       const u16* RTs = Rs;
; #pragma unroll
;       for (int ks = 0; ks < 4; ++ks) {
;         bf16x8 rf[2];
; #pragma unroll
;         for (int rb = 0; rb < 2; ++rb) {
;           if (AT && kt < 8) {
;             const u16* src = RTs + (16 * ks + 8 * g) * 264 + 64 * wr + 32 * rb + li;
;             bf16x8 t;
; #pragma unroll
;             for (int j = 0; j < 8; ++j) t[j] = (short)src[j * 264];
;             rf[rb] = t;
;           } else {
;             rf[rb] = *(const bf16x8*)(Rs + (64 * wr + 32 * rb + li) * 72 + 16 * ks + 8 * g);
;           }
;         }
; #pragma unroll
;         for (int cb = 0; cb < 4; ++cb) {
;           const bf16x8 cfv = *(const bf16x8*)(Cs + (128 * wc + 32 * cb + li) * 72 + 16 * ks + 8 * g);
; #pragma unroll
;           for (int rb = 0; rb < 2; ++rb) acc[rb][cb] = MFMA(rf[rb], cfv, acc[rb][cb]);
	v_perm_b32 v176, v184, v185, s19
	v_perm_b32 v175, v169, v174, s19
	v_perm_b32 v174, v182, v183, s19
	v_mfma_f32_32x32x16_bf16 v[64:79], v[170:173], v[178:181], v[64:79]
	v_mfma_f32_32x32x16_bf16 v[96:111], v[170:173], v[190:193], v[96:111]
	v_mfma_f32_32x32x16_bf16 v[32:47], v[174:177], v[190:193], v[32:47]
	v_mfma_f32_32x32x16_bf16 v[112:127], v[170:173], v[194:197], v[112:127]
	v_mfma_f32_32x32x16_bf16 v[80:95], v[170:173], v[220:223], v[80:95]
	ds_read_u16 v137, v168 offset:16896
	ds_read_u16 v146, v168 offset:17424
	ds_read_u16 v147, v168 offset:17952
	ds_read_u16 v167, v168 offset:18480
	ds_read_u16 v169, v168 offset:18544
	ds_read_u16 v182, v168 offset:18016
	ds_read_u16 v186, v168 offset:17488
	ds_read_u16 v187, v168 offset:16960
	ds_read_u16 v170, v168 offset:19008
	ds_read_u16 v171, v168 offset:19536
	ds_read_u16 v172, v168 offset:20064
	ds_read_u16 v173, v168 offset:20592
	ds_read_u16 v183, v168 offset:20656
	ds_read_u16 v184, v168 offset:20128
	ds_read_u16 v188, v168 offset:19600
	ds_read_u16 v190, v168 offset:19072
	s_waitcnt lgkmcnt(4)
	v_perm_b32 v173, v173, v172, s19
	v_perm_b32 v172, v171, v170, s19
	v_perm_b32 v171, v167, v147, s19
	v_perm_b32 v170, v146, v137, s19
	s_waitcnt lgkmcnt(2)
	v_perm_b32 v185, v183, v184, s19
	s_waitcnt lgkmcnt(0)
	v_perm_b32 v184, v188, v190, s19
	v_mfma_f32_32x32x16_bf16 v[0:15], v[174:177], v[178:181], v[0:15]
	v_perm_b32 v183, v169, v182, s19
	v_perm_b32 v182, v186, v187, s19
	v_mfma_f32_32x32x16_bf16 v[48:63], v[174:177], v[194:197], v[48:63]
	v_mfma_f32_32x32x16_bf16 v[16:31], v[174:177], v[220:223], v[16:31]
	ds_read_b128 v[174:177], v160 offset:64
	ds_read_b128 v[178:181], v160 offset:96
	s_waitcnt lgkmcnt(1)
	v_mfma_f32_32x32x16_bf16 v[64:79], v[170:173], v[174:177], v[64:79]
	v_mfma_f32_32x32x16_bf16 v[0:15], v[182:185], v[174:177], v[0:15]
	ds_read_b128 v[174:177], v160 offset:4672
	ds_read_b128 v[190:193], v160 offset:4704
	s_waitcnt lgkmcnt(1)
	v_mfma_f32_32x32x16_bf16 v[96:111], v[170:173], v[174:177], v[96:111]
	v_mfma_f32_32x32x16_bf16 v[32:47], v[182:185], v[174:177], v[32:47]
	ds_read_b128 v[174:177], v160 offset:9280
	ds_read_b128 v[194:197], v160 offset:9312
	s_waitcnt lgkmcnt(1)
	v_mfma_f32_32x32x16_bf16 v[112:127], v[170:173], v[174:177], v[112:127]
	v_mfma_f32_32x32x16_bf16 v[48:63], v[182:185], v[174:177], v[48:63]
	ds_read_b128 v[174:177], v160 offset:13888
	ds_read_b128 v[220:223], v160 offset:13920
	s_waitcnt lgkmcnt(1)
	v_mfma_f32_32x32x16_bf16 v[80:95], v[170:173], v[174:177], v[80:95]
	v_mfma_f32_32x32x16_bf16 v[16:31], v[182:185], v[174:177], v[16:31]
	ds_read_u16 v137, v168 offset:25344
	ds_read_u16 v146, v168 offset:25872
	ds_read_u16 v147, v168 offset:26400
	ds_read_u16 v167, v168 offset:26928
	ds_read_u16 v172, v168 offset:26992
	ds_read_u16 v173, v168 offset:26464
	ds_read_u16 v176, v168 offset:25936
	ds_read_u16 v177, v168 offset:25408
	ds_read_u16 v169, v168 offset:27456
	ds_read_u16 v170, v168 offset:27984
	ds_read_u16 v171, v168 offset:28512
	ds_read_u16 v174, v168 offset:29040
	ds_read_u16 v175, v168 offset:29104
	ds_read_u16 v182, v168 offset:28576
	ds_read_u16 v183, v168 offset:28048
	ds_read_u16 v184, v168 offset:27520
	s_waitcnt lgkmcnt(4)
	v_perm_b32 v171, v174, v171, s19
	v_perm_b32 v170, v170, v169, s19
	v_perm_b32 v169, v167, v147, s19
	v_perm_b32 v168, v146, v137, s19
	s_waitcnt lgkmcnt(2)
	v_perm_b32 v175, v175, v182, s19
	s_waitcnt lgkmcnt(0)
	v_perm_b32 v174, v183, v184, s19
	v_perm_b32 v173, v172, v173, s19
	v_perm_b32 v172, v176, v177, s19
	v_mfma_f32_32x32x16_bf16 v[64:79], v[168:171], v[178:181], v[64:79]
	v_ashrrev_i32_e32 v137, 1, v148
	v_and_b32_e32 v137, 0xffffffc0, v137
	v_or_b32_e32 v146, v137, v149
	v_mul_lo_u32 v146, v146, s94
	v_add_u32_e32 v147, v136, v162
	v_add_u32_e32 v162, v136, v163
	v_add_u32_e32 v163, v136, v164
	v_mfma_f32_32x32x16_bf16 v[0:15], v[172:175], v[178:181], v[0:15]
	global_load_dwordx4 v[176:179], v[138:139], off offset:128
	v_add_u32_e32 v164, v136, v165
	v_add_u32_e32 v136, v166, v146
	v_add3_u32 v146, s26, v161, v146
	v_mfma_f32_32x32x16_bf16 v[96:111], v[168:171], v[190:193], v[96:111]
	v_mfma_f32_32x32x16_bf16 v[32:47], v[172:175], v[190:193], v[32:47]
	v_mfma_f32_32x32x16_bf16 v[112:127], v[168:171], v[194:197], v[112:127]
	v_mfma_f32_32x32x16_bf16 v[48:63], v[172:175], v[194:197], v[48:63]
	global_load_dwordx4 v[180:183], v[128:129], off offset:1152
	global_load_dwordx4 v[184:187], v[140:141], off offset:128
	global_load_dwordx4 v[190:193], v[130:131], off offset:1152
	global_load_dwordx4 v[194:197], v[142:143], off offset:128
	global_load_dwordx4 v[224:227], v[132:133], off offset:1152
	global_load_dwordx4 v[228:231], v[144:145], off offset:128
	v_mfma_f32_32x32x16_bf16 v[80:95], v[168:171], v[220:223], v[80:95]
	global_load_dwordx4 v[168:171], v[134:135], off offset:1152
	s_barrier
; template <bool AT>
; DI void gemm_main(f32x16 (&acc)[2][4], const u16* __restrict__ R, int ldr, const u16* __restrict__ Cm, int ldc,
;                   const u16* __restrict__ RT, int ldrt, int K, char* smem, int tid) {
;     ...
;   for (int kt = -1; kt < nk; ++kt) {
;     if (kt + 1 < nk) {
;       const int ks1 = kt + 1;
;       u16* Rs = S0 + (ks1 & 1) * STG;
;       u16* Cs = Rs + 256 * 72;
; #pragma unroll
;       for (int i = 0; i < 4; ++i) {
;         const int cid = tid + NT * i;
;         const int row = cid >> 3, kc = cid & 7;
;         if (AT && ks1 < 8) {
;           const int kr = cid >> 5, tc = cid & 31;
;           *(u32x4*)(Rs + kr * 264 + tc * 8) = rr[i];
;         } else {
;           *(u32x4*)(Rs + row * 72 + kc * 8) = rr[i];
;         }
;         *(u32x4*)(Cs + row * 72 + kc * 8) = cr[i];
;       }
;     }
;     if (kt + 2 < nk) {
;       const int kn = kt + 2;
; #pragma unroll
;       for (int i = 0; i < 4; ++i) {
;         const int cid = tid + NT * i;
;         const int row = cid >> 3, kc = cid & 7;
;         if (AT && kn < 8) {
;           const int kr = cid >> 5, tc = cid & 31;
;           rr[i] = *(const u32x4*)(RT + (size_t)(kn * 64 + kr) * ldrt + tc * 8);
;         } else {
;           rr[i] = *(const u32x4*)(R + (size_t)row * ldr + kn * 64 + kc * 8);
;         }
;         cr[i] = *(const u32x4*)(Cm + (size_t)row * ldc + kn * 64 + kc * 8);
;       }
;     }
;     __builtin_amdgcn_sched_barrier(0x38F);
;     if (kt >= 0) {
;       const u16* Rs = S0 + (kt & 1) * STG;
;       const u16* Cs = Rs + 256 * 72;
;       const u16* RTs = Rs;
; #pragma unroll
;       for (int ks = 0; ks < 4; ++ks) {
;         bf16x8 rf[2];
; #pragma unroll
;         for (int rb = 0; rb < 2; ++rb) {
;           if (AT && kt < 8) {
;             const u16* src = RTs + (16 * ks + 8 * g) * 264 + 64 * wr + 32 * rb + li;
;             bf16x8 t;
; #pragma unroll
;             for (int j = 0; j < 8; ++j) t[j] = (short)src[j * 264];
;             rf[rb] = t;
;           } else {
;             rf[rb] = *(const bf16x8*)(Rs + (64 * wr + 32 * rb + li) * 72 + 16 * ks + 8 * g);
;           }
;         }
; #pragma unroll
;         for (int cb = 0; cb < 4; ++cb) {
;           const bf16x8 cfv = *(const bf16x8*)(Cs + (128 * wc + 32 * cb + li) * 72 + 16 * ks + 8 * g);
; #pragma unroll
;           for (int rb = 0; rb < 2; ++rb) acc[rb][cb] = MFMA(rf[rb], cfv, acc[rb][cb]);
	s_waitcnt vmcnt(7)
	ds_write_b128 v147, v[176:179]
	s_waitcnt vmcnt(6)
	ds_write_b128 v152, v[180:183]
	s_waitcnt vmcnt(5)
	ds_write_b128 v162, v[184:187]
	s_waitcnt vmcnt(4)
	ds_write_b128 v153, v[190:193]
	s_waitcnt vmcnt(3)
	ds_write_b128 v163, v[194:197]
	s_waitcnt vmcnt(2)
	ds_write_b128 v154, v[224:227]
	s_waitcnt vmcnt(1)
	ds_write_b128 v164, v[228:231]
	s_waitcnt vmcnt(0)
	ds_write_b128 v155, v[168:171]
	v_mfma_f32_32x32x16_bf16 v[16:31], v[172:175], v[220:223], v[16:31]
	ds_read_b128 v[166:169], v136
	ds_read_b128 v[170:173], v151 offset:36864
	ds_read_b128 v[174:177], v136 offset:32
	ds_read_b128 v[178:181], v151 offset:36896
	ds_read_b128 v[182:185], v136 offset:4608
	ds_read_b128 v[190:193], v136 offset:4640
	s_waitcnt lgkmcnt(4)
	v_mfma_f32_32x32x16_bf16 v[64:79], v[166:169], v[170:173], v[64:79]
	s_waitcnt lgkmcnt(1)
	v_mfma_f32_32x32x16_bf16 v[0:15], v[182:185], v[170:173], v[0:15]
	ds_read_b128 v[170:173], v151 offset:41472
	ds_read_b128 v[194:197], v151 offset:41504
	s_waitcnt lgkmcnt(1)
	v_mfma_f32_32x32x16_bf16 v[96:111], v[166:169], v[170:173], v[96:111]
	v_mfma_f32_32x32x16_bf16 v[32:47], v[182:185], v[170:173], v[32:47]
	ds_read_b128 v[170:173], v151 offset:46080
	ds_read_b128 v[220:223], v151 offset:46112
	s_waitcnt lgkmcnt(1)
	v_mfma_f32_32x32x16_bf16 v[112:127], v[166:169], v[170:173], v[112:127]
	v_mfma_f32_32x32x16_bf16 v[48:63], v[182:185], v[170:173], v[48:63]
	ds_read_b128 v[170:173], v151 offset:50688
	ds_read_b128 v[224:227], v151 offset:50720
	s_waitcnt lgkmcnt(1)
	v_mfma_f32_32x32x16_bf16 v[80:95], v[166:169], v[170:173], v[80:95]
	v_mfma_f32_32x32x16_bf16 v[16:31], v[182:185], v[170:173], v[16:31]
	v_mfma_f32_32x32x16_bf16 v[64:79], v[174:177], v[178:181], v[64:79]
	v_mfma_f32_32x32x16_bf16 v[0:15], v[190:193], v[178:181], v[0:15]
	v_mfma_f32_32x32x16_bf16 v[96:111], v[174:177], v[194:197], v[96:111]
	v_mfma_f32_32x32x16_bf16 v[32:47], v[190:193], v[194:197], v[32:47]
	v_mfma_f32_32x32x16_bf16 v[112:127], v[174:177], v[220:223], v[112:127]
	v_mfma_f32_32x32x16_bf16 v[48:63], v[190:193], v[220:223], v[48:63]
	s_waitcnt lgkmcnt(0)
	v_mfma_f32_32x32x16_bf16 v[80:95], v[174:177], v[224:227], v[80:95]
	ds_read_b128 v[166:169], v136 offset:64
	ds_read_b128 v[170:173], v151 offset:36928
	ds_read_b128 v[174:177], v136 offset:96
	ds_read_b128 v[178:181], v151 offset:36960
	v_mfma_f32_32x32x16_bf16 v[16:31], v[190:193], v[224:227], v[16:31]
	ds_read_b128 v[182:185], v136 offset:4672
	ds_read_b128 v[190:193], v136 offset:4704
	s_waitcnt lgkmcnt(4)
	v_mfma_f32_32x32x16_bf16 v[64:79], v[166:169], v[170:173], v[64:79]
	s_waitcnt lgkmcnt(1)
	v_mfma_f32_32x32x16_bf16 v[0:15], v[182:185], v[170:173], v[0:15]
	ds_read_b128 v[170:173], v151 offset:41536
	ds_read_b128 v[194:197], v151 offset:41568
	s_waitcnt lgkmcnt(1)
	v_mfma_f32_32x32x16_bf16 v[96:111], v[166:169], v[170:173], v[96:111]
	v_mfma_f32_32x32x16_bf16 v[32:47], v[182:185], v[170:173], v[32:47]
	ds_read_b128 v[170:173], v151 offset:46144
	ds_read_b128 v[220:223], v151 offset:46176
	s_waitcnt lgkmcnt(1)
	v_mfma_f32_32x32x16_bf16 v[112:127], v[166:169], v[170:173], v[112:127]
	v_mfma_f32_32x32x16_bf16 v[48:63], v[182:185], v[170:173], v[48:63]
	ds_read_b128 v[170:173], v151 offset:50752
	ds_read_b128 v[224:227], v151 offset:50784
	s_waitcnt lgkmcnt(1)
	v_mfma_f32_32x32x16_bf16 v[80:95], v[166:169], v[170:173], v[80:95]
	v_mfma_f32_32x32x16_bf16 v[16:31], v[182:185], v[170:173], v[16:31]
	v_mfma_f32_32x32x16_bf16 v[64:79], v[174:177], v[178:181], v[64:79]
	v_mfma_f32_32x32x16_bf16 v[0:15], v[190:193], v[178:181], v[0:15]
	v_mfma_f32_32x32x16_bf16 v[96:111], v[174:177], v[194:197], v[96:111]
	v_mfma_f32_32x32x16_bf16 v[32:47], v[190:193], v[194:197], v[32:47]
	v_mfma_f32_32x32x16_bf16 v[112:127], v[174:177], v[220:223], v[112:127]
	v_mfma_f32_32x32x16_bf16 v[48:63], v[190:193], v[220:223], v[48:63]
	global_load_dwordx4 v[166:169], v[138:139], off offset:256
	global_load_dwordx4 v[170:173], v[140:141], off offset:256
	global_load_dwordx4 v[178:181], v[128:129], off offset:1280
	global_load_dwordx4 v[182:185], v[130:131], off offset:1280
	global_load_dwordx4 v[194:197], v[132:133], off offset:1280
	global_load_dwordx4 v[220:223], v[142:143], off offset:256
	global_load_dwordx4 v[228:231], v[144:145], off offset:256
	s_waitcnt lgkmcnt(0)
	v_mfma_f32_32x32x16_bf16 v[80:95], v[174:177], v[224:227], v[80:95]
	global_load_dwordx4 v[174:177], v[134:135], off offset:1280
	s_barrier
; template <bool AT>
; DI void gemm_main(f32x16 (&acc)[2][4], const u16* __restrict__ R, int ldr, const u16* __restrict__ Cm, int ldc,
;                   const u16* __restrict__ RT, int ldrt, int K, char* smem, int tid) {
;     ...
;   for (int kt = -1; kt < nk; ++kt) {
;     if (kt + 1 < nk) {
;       const int ks1 = kt + 1;
;       u16* Rs = S0 + (ks1 & 1) * STG;
;       u16* Cs = Rs + 256 * 72;
; #pragma unroll
;       for (int i = 0; i < 4; ++i) {
;         const int cid = tid + NT * i;
;         const int row = cid >> 3, kc = cid & 7;
;         if (AT && ks1 < 8) {
;           const int kr = cid >> 5, tc = cid & 31;
;           *(u32x4*)(Rs + kr * 264 + tc * 8) = rr[i];
;         } else {
;           *(u32x4*)(Rs + row * 72 + kc * 8) = rr[i];
;         }
;         *(u32x4*)(Cs + row * 72 + kc * 8) = cr[i];
;       }
;     }
;     if (kt + 2 < nk) {
;       const int kn = kt + 2;
; #pragma unroll
;       for (int i = 0; i < 4; ++i) {
;         const int cid = tid + NT * i;
;         const int row = cid >> 3, kc = cid & 7;
;         if (AT && kn < 8) {
;           const int kr = cid >> 5, tc = cid & 31;
;           rr[i] = *(const u32x4*)(RT + (size_t)(kn * 64 + kr) * ldrt + tc * 8);
;         } else {
;           rr[i] = *(const u32x4*)(R + (size_t)row * ldr + kn * 64 + kc * 8);
;         }
;         cr[i] = *(const u32x4*)(Cm + (size_t)row * ldc + kn * 64 + kc * 8);
;       }
;     }
;     __builtin_amdgcn_sched_barrier(0x38F);
;     if (kt >= 0) {
;       const u16* Rs = S0 + (kt & 1) * STG;
;       const u16* Cs = Rs + 256 * 72;
;       const u16* RTs = Rs;
; #pragma unroll
;       for (int ks = 0; ks < 4; ++ks) {
;         bf16x8 rf[2];
; #pragma unroll
;         for (int rb = 0; rb < 2; ++rb) {
;           if (AT && kt < 8) {
;             const u16* src = RTs + (16 * ks + 8 * g) * 264 + 64 * wr + 32 * rb + li;
;             bf16x8 t;
; #pragma unroll
;             for (int j = 0; j < 8; ++j) t[j] = (short)src[j * 264];
;             rf[rb] = t;
;           } else {
;             rf[rb] = *(const bf16x8*)(Rs + (64 * wr + 32 * rb + li) * 72 + 16 * ks + 8 * g);
;           }
;         }
; #pragma unroll
;         for (int cb = 0; cb < 4; ++cb) {
;           const bf16x8 cfv = *(const bf16x8*)(Cs + (128 * wc + 32 * cb + li) * 72 + 16 * ks + 8 * g);
; #pragma unroll
;           for (int rb = 0; rb < 2; ++rb) acc[rb][cb] = MFMA(rf[rb], cfv, acc[rb][cb]);
	s_waitcnt vmcnt(7)
	ds_write_b128 v156, v[166:169]
	s_waitcnt vmcnt(5)
	ds_write_b128 v156, v[178:181] offset:36864
	ds_write_b128 v157, v[170:173]
	s_waitcnt vmcnt(4)
	ds_write_b128 v157, v[182:185] offset:36864
	s_waitcnt vmcnt(2)
	ds_write_b128 v158, v[220:223]
	ds_write_b128 v158, v[194:197] offset:36864
	s_waitcnt vmcnt(1)
	ds_write_b128 v159, v[228:231]
	s_waitcnt vmcnt(0)
	ds_write_b128 v159, v[174:177] offset:36864
	v_mfma_f32_32x32x16_bf16 v[16:31], v[190:193], v[224:227], v[16:31]
	ds_read_b128 v[166:169], v146
	ds_read_b128 v[170:173], v160
	ds_read_b128 v[174:177], v146 offset:32
	ds_read_b128 v[178:181], v160 offset:32
	ds_read_b128 v[182:185], v146 offset:4608
	ds_read_b128 v[190:193], v146 offset:4640
	s_waitcnt lgkmcnt(4)
	v_mfma_f32_32x32x16_bf16 v[64:79], v[166:169], v[170:173], v[64:79]
	s_waitcnt lgkmcnt(1)
	v_mfma_f32_32x32x16_bf16 v[0:15], v[182:185], v[170:173], v[0:15]
	ds_read_b128 v[170:173], v160 offset:4608
	ds_read_b128 v[194:197], v160 offset:4640
	s_waitcnt lgkmcnt(1)
	v_mfma_f32_32x32x16_bf16 v[96:111], v[166:169], v[170:173], v[96:111]
	v_mfma_f32_32x32x16_bf16 v[32:47], v[182:185], v[170:173], v[32:47]
	ds_read_b128 v[170:173], v160 offset:9216
	ds_read_b128 v[220:223], v160 offset:9248
	s_waitcnt lgkmcnt(1)
	v_mfma_f32_32x32x16_bf16 v[112:127], v[166:169], v[170:173], v[112:127]
	v_mfma_f32_32x32x16_bf16 v[48:63], v[182:185], v[170:173], v[48:63]
	ds_read_b128 v[170:173], v160 offset:13824
	ds_read_b128 v[224:227], v160 offset:13856
	s_waitcnt lgkmcnt(1)
	v_mfma_f32_32x32x16_bf16 v[80:95], v[166:169], v[170:173], v[80:95]
	v_mfma_f32_32x32x16_bf16 v[16:31], v[182:185], v[170:173], v[16:31]
	v_mfma_f32_32x32x16_bf16 v[64:79], v[174:177], v[178:181], v[64:79]
	v_mfma_f32_32x32x16_bf16 v[0:15], v[190:193], v[178:181], v[0:15]
	v_mfma_f32_32x32x16_bf16 v[96:111], v[174:177], v[194:197], v[96:111]
	v_mfma_f32_32x32x16_bf16 v[32:47], v[190:193], v[194:197], v[32:47]
	v_mfma_f32_32x32x16_bf16 v[112:127], v[174:177], v[220:223], v[112:127]
	v_mfma_f32_32x32x16_bf16 v[48:63], v[190:193], v[220:223], v[48:63]
	s_waitcnt lgkmcnt(0)
	v_mfma_f32_32x32x16_bf16 v[80:95], v[174:177], v[224:227], v[80:95]
	ds_read_b128 v[166:169], v146 offset:64
	ds_read_b128 v[170:173], v160 offset:64
	ds_read_b128 v[174:177], v146 offset:96
	ds_read_b128 v[178:181], v160 offset:96
	v_mfma_f32_32x32x16_bf16 v[16:31], v[190:193], v[224:227], v[16:31]
	ds_read_b128 v[182:185], v146 offset:4672
	ds_read_b128 v[190:193], v146 offset:4704
	s_waitcnt lgkmcnt(4)
	v_mfma_f32_32x32x16_bf16 v[64:79], v[166:169], v[170:173], v[64:79]
	s_waitcnt lgkmcnt(1)
	v_mfma_f32_32x32x16_bf16 v[0:15], v[182:185], v[170:173], v[0:15]
	ds_read_b128 v[170:173], v160 offset:4672
	ds_read_b128 v[194:197], v160 offset:4704
	s_waitcnt lgkmcnt(1)
	v_mfma_f32_32x32x16_bf16 v[96:111], v[166:169], v[170:173], v[96:111]
	v_mfma_f32_32x32x16_bf16 v[32:47], v[182:185], v[170:173], v[32:47]
	ds_read_b128 v[170:173], v160 offset:9280
	ds_read_b128 v[220:223], v160 offset:9312
	s_waitcnt lgkmcnt(1)
	v_mfma_f32_32x32x16_bf16 v[112:127], v[166:169], v[170:173], v[112:127]
	v_mfma_f32_32x32x16_bf16 v[48:63], v[182:185], v[170:173], v[48:63]
	ds_read_b128 v[170:173], v160 offset:13888
	ds_read_b128 v[224:227], v160 offset:13920
	s_waitcnt lgkmcnt(1)
	v_mfma_f32_32x32x16_bf16 v[80:95], v[166:169], v[170:173], v[80:95]
	v_mfma_f32_32x32x16_bf16 v[16:31], v[182:185], v[170:173], v[16:31]
	v_mfma_f32_32x32x16_bf16 v[64:79], v[174:177], v[178:181], v[64:79]
	v_mfma_f32_32x32x16_bf16 v[0:15], v[190:193], v[178:181], v[0:15]
	v_mfma_f32_32x32x16_bf16 v[96:111], v[174:177], v[194:197], v[96:111]
	v_mfma_f32_32x32x16_bf16 v[32:47], v[190:193], v[194:197], v[32:47]
	v_mfma_f32_32x32x16_bf16 v[112:127], v[174:177], v[220:223], v[112:127]
	v_mfma_f32_32x32x16_bf16 v[48:63], v[190:193], v[220:223], v[48:63]
	global_load_dwordx4 v[166:169], v[138:139], off offset:384
	global_load_dwordx4 v[170:173], v[140:141], off offset:384
	global_load_dwordx4 v[178:181], v[128:129], off offset:1408
	global_load_dwordx4 v[182:185], v[130:131], off offset:1408
	global_load_dwordx4 v[194:197], v[132:133], off offset:1408
	global_load_dwordx4 v[220:223], v[142:143], off offset:384
	global_load_dwordx4 v[228:231], v[144:145], off offset:384
	s_waitcnt lgkmcnt(0)
	v_mfma_f32_32x32x16_bf16 v[80:95], v[174:177], v[224:227], v[80:95]
	global_load_dwordx4 v[174:177], v[134:135], off offset:1408
	s_barrier
; template <bool AT>
; DI void gemm_main(f32x16 (&acc)[2][4], const u16* __restrict__ R, int ldr, const u16* __restrict__ Cm, int ldc,
;                   const u16* __restrict__ RT, int ldrt, int K, char* smem, int tid) {
;     ...
;   for (int kt = -1; kt < nk; ++kt) {
;     if (kt + 1 < nk) {
;       const int ks1 = kt + 1;
;       u16* Rs = S0 + (ks1 & 1) * STG;
;       u16* Cs = Rs + 256 * 72;
; #pragma unroll
;       for (int i = 0; i < 4; ++i) {
;         const int cid = tid + NT * i;
;         const int row = cid >> 3, kc = cid & 7;
;         if (AT && ks1 < 8) {
;           const int kr = cid >> 5, tc = cid & 31;
;           *(u32x4*)(Rs + kr * 264 + tc * 8) = rr[i];
;         } else {
;           *(u32x4*)(Rs + row * 72 + kc * 8) = rr[i];
;         }
;         *(u32x4*)(Cs + row * 72 + kc * 8) = cr[i];
;       }
;     }
;     if (kt + 2 < nk) {
;       const int kn = kt + 2;
; #pragma unroll
;       for (int i = 0; i < 4; ++i) {
;         const int cid = tid + NT * i;
;         const int row = cid >> 3, kc = cid & 7;
;         if (AT && kn < 8) {
;           const int kr = cid >> 5, tc = cid & 31;
;           rr[i] = *(const u32x4*)(RT + (size_t)(kn * 64 + kr) * ldrt + tc * 8);
;         } else {
;           rr[i] = *(const u32x4*)(R + (size_t)row * ldr + kn * 64 + kc * 8);
;         }
;         cr[i] = *(const u32x4*)(Cm + (size_t)row * ldc + kn * 64 + kc * 8);
;       }
;     }
;     __builtin_amdgcn_sched_barrier(0x38F);
;     if (kt >= 0) {
;       const u16* Rs = S0 + (kt & 1) * STG;
;       const u16* Cs = Rs + 256 * 72;
;       const u16* RTs = Rs;
; #pragma unroll
;       for (int ks = 0; ks < 4; ++ks) {
;         bf16x8 rf[2];
; #pragma unroll
;         for (int rb = 0; rb < 2; ++rb) {
;           if (AT && kt < 8) {
;             const u16* src = RTs + (16 * ks + 8 * g) * 264 + 64 * wr + 32 * rb + li;
;             bf16x8 t;
; #pragma unroll
;             for (int j = 0; j < 8; ++j) t[j] = (short)src[j * 264];
;             rf[rb] = t;
;           } else {
;             rf[rb] = *(const bf16x8*)(Rs + (64 * wr + 32 * rb + li) * 72 + 16 * ks + 8 * g);
;           }
;         }
; #pragma unroll
;         for (int cb = 0; cb < 4; ++cb) {
;           const bf16x8 cfv = *(const bf16x8*)(Cs + (128 * wc + 32 * cb + li) * 72 + 16 * ks + 8 * g);
; #pragma unroll
;           for (int rb = 0; rb < 2; ++rb) acc[rb][cb] = MFMA(rf[rb], cfv, acc[rb][cb]);
	s_waitcnt vmcnt(7)
	ds_write_b128 v147, v[166:169]
	s_waitcnt vmcnt(5)
	ds_write_b128 v152, v[178:181]
	ds_write_b128 v162, v[170:173]
	s_waitcnt vmcnt(4)
	ds_write_b128 v153, v[182:185]
	s_waitcnt vmcnt(2)
	ds_write_b128 v163, v[220:223]
	ds_write_b128 v154, v[194:197]
	s_waitcnt vmcnt(1)
	ds_write_b128 v164, v[228:231]
	s_waitcnt vmcnt(0)
	ds_write_b128 v155, v[174:177]
	v_mfma_f32_32x32x16_bf16 v[16:31], v[190:193], v[224:227], v[16:31]
	ds_read_b128 v[166:169], v136
	ds_read_b128 v[170:173], v151 offset:36864
	ds_read_b128 v[174:177], v136 offset:32
	ds_read_b128 v[178:181], v151 offset:36896
	ds_read_b128 v[182:185], v136 offset:4608
	ds_read_b128 v[190:193], v136 offset:4640
	s_waitcnt lgkmcnt(4)
	v_mfma_f32_32x32x16_bf16 v[64:79], v[166:169], v[170:173], v[64:79]
	s_waitcnt lgkmcnt(1)
	v_mfma_f32_32x32x16_bf16 v[0:15], v[182:185], v[170:173], v[0:15]
	ds_read_b128 v[170:173], v151 offset:41472
	ds_read_b128 v[194:197], v151 offset:41504
	s_waitcnt lgkmcnt(1)
	v_mfma_f32_32x32x16_bf16 v[96:111], v[166:169], v[170:173], v[96:111]
	v_mfma_f32_32x32x16_bf16 v[32:47], v[182:185], v[170:173], v[32:47]
	ds_read_b128 v[170:173], v151 offset:46080
	ds_read_b128 v[220:223], v151 offset:46112
	s_waitcnt lgkmcnt(1)
	v_mfma_f32_32x32x16_bf16 v[112:127], v[166:169], v[170:173], v[112:127]
	v_mfma_f32_32x32x16_bf16 v[48:63], v[182:185], v[170:173], v[48:63]
	ds_read_b128 v[170:173], v151 offset:50688
	ds_read_b128 v[224:227], v151 offset:50720
	s_waitcnt lgkmcnt(1)
	v_mfma_f32_32x32x16_bf16 v[80:95], v[166:169], v[170:173], v[80:95]
	v_mfma_f32_32x32x16_bf16 v[16:31], v[182:185], v[170:173], v[16:31]
	v_mfma_f32_32x32x16_bf16 v[64:79], v[174:177], v[178:181], v[64:79]
	v_mfma_f32_32x32x16_bf16 v[0:15], v[190:193], v[178:181], v[0:15]
	v_mfma_f32_32x32x16_bf16 v[96:111], v[174:177], v[194:197], v[96:111]
	v_mfma_f32_32x32x16_bf16 v[32:47], v[190:193], v[194:197], v[32:47]
	v_mfma_f32_32x32x16_bf16 v[112:127], v[174:177], v[220:223], v[112:127]
	v_mfma_f32_32x32x16_bf16 v[48:63], v[190:193], v[220:223], v[48:63]
	s_waitcnt lgkmcnt(0)
	v_mfma_f32_32x32x16_bf16 v[80:95], v[174:177], v[224:227], v[80:95]
	ds_read_b128 v[166:169], v136 offset:64
	ds_read_b128 v[170:173], v151 offset:36928
	ds_read_b128 v[174:177], v136 offset:96
	ds_read_b128 v[178:181], v151 offset:36960
	v_mfma_f32_32x32x16_bf16 v[16:31], v[190:193], v[224:227], v[16:31]
	ds_read_b128 v[182:185], v136 offset:4672
	ds_read_b128 v[190:193], v136 offset:4704
	s_waitcnt lgkmcnt(4)
	v_mfma_f32_32x32x16_bf16 v[64:79], v[166:169], v[170:173], v[64:79]
	s_waitcnt lgkmcnt(1)
	v_mfma_f32_32x32x16_bf16 v[0:15], v[182:185], v[170:173], v[0:15]
	ds_read_b128 v[170:173], v151 offset:41536
	ds_read_b128 v[194:197], v151 offset:41568
	s_waitcnt lgkmcnt(1)
	v_mfma_f32_32x32x16_bf16 v[96:111], v[166:169], v[170:173], v[96:111]
	v_mfma_f32_32x32x16_bf16 v[32:47], v[182:185], v[170:173], v[32:47]
	ds_read_b128 v[170:173], v151 offset:46144
	ds_read_b128 v[220:223], v151 offset:46176
	s_waitcnt lgkmcnt(1)
	v_mfma_f32_32x32x16_bf16 v[112:127], v[166:169], v[170:173], v[112:127]
	v_mfma_f32_32x32x16_bf16 v[48:63], v[182:185], v[170:173], v[48:63]
	ds_read_b128 v[170:173], v151 offset:50752
	ds_read_b128 v[224:227], v151 offset:50784
	s_waitcnt lgkmcnt(1)
	v_mfma_f32_32x32x16_bf16 v[80:95], v[166:169], v[170:173], v[80:95]
	v_mfma_f32_32x32x16_bf16 v[16:31], v[182:185], v[170:173], v[16:31]
	v_mfma_f32_32x32x16_bf16 v[64:79], v[174:177], v[178:181], v[64:79]
	v_mfma_f32_32x32x16_bf16 v[0:15], v[190:193], v[178:181], v[0:15]
	v_mfma_f32_32x32x16_bf16 v[96:111], v[174:177], v[194:197], v[96:111]
	v_mfma_f32_32x32x16_bf16 v[32:47], v[190:193], v[194:197], v[32:47]
	v_mfma_f32_32x32x16_bf16 v[112:127], v[174:177], v[220:223], v[112:127]
	v_mfma_f32_32x32x16_bf16 v[48:63], v[190:193], v[220:223], v[48:63]
	global_load_dwordx4 v[166:169], v[138:139], off offset:512
	global_load_dwordx4 v[170:173], v[140:141], off offset:512
	global_load_dwordx4 v[178:181], v[128:129], off offset:1536
	global_load_dwordx4 v[182:185], v[130:131], off offset:1536
	global_load_dwordx4 v[194:197], v[132:133], off offset:1536
	global_load_dwordx4 v[220:223], v[142:143], off offset:512
	global_load_dwordx4 v[228:231], v[144:145], off offset:512
	s_waitcnt lgkmcnt(0)
	v_mfma_f32_32x32x16_bf16 v[80:95], v[174:177], v[224:227], v[80:95]
	global_load_dwordx4 v[174:177], v[134:135], off offset:1536
	s_barrier
; template <bool AT>
; DI void gemm_main(f32x16 (&acc)[2][4], const u16* __restrict__ R, int ldr, const u16* __restrict__ Cm, int ldc,
;                   const u16* __restrict__ RT, int ldrt, int K, char* smem, int tid) {
;     ...
;   for (int kt = -1; kt < nk; ++kt) {
;     if (kt + 1 < nk) {
;       const int ks1 = kt + 1;
;       u16* Rs = S0 + (ks1 & 1) * STG;
;       u16* Cs = Rs + 256 * 72;
; #pragma unroll
;       for (int i = 0; i < 4; ++i) {
;         const int cid = tid + NT * i;
;         const int row = cid >> 3, kc = cid & 7;
;         if (AT && ks1 < 8) {
;           const int kr = cid >> 5, tc = cid & 31;
;           *(u32x4*)(Rs + kr * 264 + tc * 8) = rr[i];
;         } else {
;           *(u32x4*)(Rs + row * 72 + kc * 8) = rr[i];
;         }
;         *(u32x4*)(Cs + row * 72 + kc * 8) = cr[i];
;       }
;     }
;     if (kt + 2 < nk) {
;       const int kn = kt + 2;
; #pragma unroll
;       for (int i = 0; i < 4; ++i) {
;         const int cid = tid + NT * i;
;         const int row = cid >> 3, kc = cid & 7;
;         if (AT && kn < 8) {
;           const int kr = cid >> 5, tc = cid & 31;
;           rr[i] = *(const u32x4*)(RT + (size_t)(kn * 64 + kr) * ldrt + tc * 8);
;         } else {
;           rr[i] = *(const u32x4*)(R + (size_t)row * ldr + kn * 64 + kc * 8);
;         }
;         cr[i] = *(const u32x4*)(Cm + (size_t)row * ldc + kn * 64 + kc * 8);
;       }
;     }
;     __builtin_amdgcn_sched_barrier(0x38F);
;     if (kt >= 0) {
;       const u16* Rs = S0 + (kt & 1) * STG;
;       const u16* Cs = Rs + 256 * 72;
;       const u16* RTs = Rs;
; #pragma unroll
;       for (int ks = 0; ks < 4; ++ks) {
;         bf16x8 rf[2];
; #pragma unroll
;         for (int rb = 0; rb < 2; ++rb) {
;           if (AT && kt < 8) {
;             const u16* src = RTs + (16 * ks + 8 * g) * 264 + 64 * wr + 32 * rb + li;
;             bf16x8 t;
; #pragma unroll
;             for (int j = 0; j < 8; ++j) t[j] = (short)src[j * 264];
;             rf[rb] = t;
;           } else {
;             rf[rb] = *(const bf16x8*)(Rs + (64 * wr + 32 * rb + li) * 72 + 16 * ks + 8 * g);
;           }
;         }
; #pragma unroll
;         for (int cb = 0; cb < 4; ++cb) {
;           const bf16x8 cfv = *(const bf16x8*)(Cs + (128 * wc + 32 * cb + li) * 72 + 16 * ks + 8 * g);
; #pragma unroll
;           for (int rb = 0; rb < 2; ++rb) acc[rb][cb] = MFMA(rf[rb], cfv, acc[rb][cb]);
	s_waitcnt vmcnt(7)
	ds_write_b128 v156, v[166:169]
	s_waitcnt vmcnt(5)
	ds_write_b128 v156, v[178:181] offset:36864
	ds_write_b128 v157, v[170:173]
	s_waitcnt vmcnt(4)
	ds_write_b128 v157, v[182:185] offset:36864
	s_waitcnt vmcnt(2)
	ds_write_b128 v158, v[220:223]
	ds_write_b128 v158, v[194:197] offset:36864
	s_waitcnt vmcnt(1)
	ds_write_b128 v159, v[228:231]
	s_waitcnt vmcnt(0)
	ds_write_b128 v159, v[174:177] offset:36864
	v_mfma_f32_32x32x16_bf16 v[16:31], v[190:193], v[224:227], v[16:31]
	ds_read_b128 v[166:169], v146
	ds_read_b128 v[170:173], v160
	ds_read_b128 v[174:177], v146 offset:32
	ds_read_b128 v[178:181], v160 offset:32
	ds_read_b128 v[182:185], v146 offset:4608
	ds_read_b128 v[190:193], v146 offset:4640
	s_waitcnt lgkmcnt(4)
	v_mfma_f32_32x32x16_bf16 v[64:79], v[166:169], v[170:173], v[64:79]
	s_waitcnt lgkmcnt(1)
	v_mfma_f32_32x32x16_bf16 v[0:15], v[182:185], v[170:173], v[0:15]
	ds_read_b128 v[170:173], v160 offset:4608
	ds_read_b128 v[194:197], v160 offset:4640
	s_waitcnt lgkmcnt(1)
	v_mfma_f32_32x32x16_bf16 v[96:111], v[166:169], v[170:173], v[96:111]
	v_mfma_f32_32x32x16_bf16 v[32:47], v[182:185], v[170:173], v[32:47]
	ds_read_b128 v[170:173], v160 offset:9216
	ds_read_b128 v[220:223], v160 offset:9248
	s_waitcnt lgkmcnt(1)
	v_mfma_f32_32x32x16_bf16 v[112:127], v[166:169], v[170:173], v[112:127]
	v_mfma_f32_32x32x16_bf16 v[48:63], v[182:185], v[170:173], v[48:63]
	ds_read_b128 v[170:173], v160 offset:13824
	ds_read_b128 v[224:227], v160 offset:13856
	s_waitcnt lgkmcnt(1)
	v_mfma_f32_32x32x16_bf16 v[80:95], v[166:169], v[170:173], v[80:95]
	v_mfma_f32_32x32x16_bf16 v[16:31], v[182:185], v[170:173], v[16:31]
	v_mfma_f32_32x32x16_bf16 v[64:79], v[174:177], v[178:181], v[64:79]
	v_mfma_f32_32x32x16_bf16 v[0:15], v[190:193], v[178:181], v[0:15]
	v_mfma_f32_32x32x16_bf16 v[96:111], v[174:177], v[194:197], v[96:111]
	v_mfma_f32_32x32x16_bf16 v[32:47], v[190:193], v[194:197], v[32:47]
	v_mfma_f32_32x32x16_bf16 v[112:127], v[174:177], v[220:223], v[112:127]
	v_mfma_f32_32x32x16_bf16 v[48:63], v[190:193], v[220:223], v[48:63]
	s_waitcnt lgkmcnt(0)
	v_mfma_f32_32x32x16_bf16 v[80:95], v[174:177], v[224:227], v[80:95]
	ds_read_b128 v[166:169], v146 offset:64
	ds_read_b128 v[170:173], v160 offset:64
	ds_read_b128 v[174:177], v146 offset:96
	ds_read_b128 v[178:181], v160 offset:96
	v_mfma_f32_32x32x16_bf16 v[16:31], v[190:193], v[224:227], v[16:31]
	ds_read_b128 v[182:185], v146 offset:4672
	ds_read_b128 v[190:193], v146 offset:4704
	s_waitcnt lgkmcnt(4)
	v_mfma_f32_32x32x16_bf16 v[64:79], v[166:169], v[170:173], v[64:79]
	s_waitcnt lgkmcnt(1)
	v_mfma_f32_32x32x16_bf16 v[0:15], v[182:185], v[170:173], v[0:15]
	ds_read_b128 v[170:173], v160 offset:4672
	ds_read_b128 v[194:197], v160 offset:4704
	s_waitcnt lgkmcnt(1)
	v_mfma_f32_32x32x16_bf16 v[96:111], v[166:169], v[170:173], v[96:111]
	v_mfma_f32_32x32x16_bf16 v[32:47], v[182:185], v[170:173], v[32:47]
	ds_read_b128 v[170:173], v160 offset:9280
	ds_read_b128 v[220:223], v160 offset:9312
	s_waitcnt lgkmcnt(1)
	v_mfma_f32_32x32x16_bf16 v[112:127], v[166:169], v[170:173], v[112:127]
	v_mfma_f32_32x32x16_bf16 v[48:63], v[182:185], v[170:173], v[48:63]
	ds_read_b128 v[170:173], v160 offset:13888
	ds_read_b128 v[224:227], v160 offset:13920
	s_waitcnt lgkmcnt(1)
	v_mfma_f32_32x32x16_bf16 v[80:95], v[166:169], v[170:173], v[80:95]
	v_mfma_f32_32x32x16_bf16 v[16:31], v[182:185], v[170:173], v[16:31]
	v_mfma_f32_32x32x16_bf16 v[64:79], v[174:177], v[178:181], v[64:79]
	v_mfma_f32_32x32x16_bf16 v[0:15], v[190:193], v[178:181], v[0:15]
	v_mfma_f32_32x32x16_bf16 v[96:111], v[174:177], v[194:197], v[96:111]
	v_mfma_f32_32x32x16_bf16 v[32:47], v[190:193], v[194:197], v[32:47]
	v_mfma_f32_32x32x16_bf16 v[112:127], v[174:177], v[220:223], v[112:127]
	v_mfma_f32_32x32x16_bf16 v[48:63], v[190:193], v[220:223], v[48:63]
	global_load_dwordx4 v[166:169], v[138:139], off offset:640
	global_load_dwordx4 v[170:173], v[140:141], off offset:640
	global_load_dwordx4 v[178:181], v[128:129], off offset:1664
	global_load_dwordx4 v[182:185], v[130:131], off offset:1664
	global_load_dwordx4 v[194:197], v[132:133], off offset:1664
	global_load_dwordx4 v[220:223], v[142:143], off offset:640
	global_load_dwordx4 v[228:231], v[144:145], off offset:640
	s_waitcnt lgkmcnt(0)
	v_mfma_f32_32x32x16_bf16 v[80:95], v[174:177], v[224:227], v[80:95]
	global_load_dwordx4 v[174:177], v[134:135], off offset:1664
	s_barrier
; template <bool AT>
; DI void gemm_main(f32x16 (&acc)[2][4], const u16* __restrict__ R, int ldr, const u16* __restrict__ Cm, int ldc,
;                   const u16* __restrict__ RT, int ldrt, int K, char* smem, int tid) {
;     ...
;   for (int kt = -1; kt < nk; ++kt) {
;     if (kt + 1 < nk) {
;       const int ks1 = kt + 1;
;       u16* Rs = S0 + (ks1 & 1) * STG;
;       u16* Cs = Rs + 256 * 72;
; #pragma unroll
;       for (int i = 0; i < 4; ++i) {
;         const int cid = tid + NT * i;
;         const int row = cid >> 3, kc = cid & 7;
;         if (AT && ks1 < 8) {
;           const int kr = cid >> 5, tc = cid & 31;
;           *(u32x4*)(Rs + kr * 264 + tc * 8) = rr[i];
;         } else {
;           *(u32x4*)(Rs + row * 72 + kc * 8) = rr[i];
;         }
;         *(u32x4*)(Cs + row * 72 + kc * 8) = cr[i];
;       }
;     }
;     if (kt + 2 < nk) {
;       const int kn = kt + 2;
; #pragma unroll
;       for (int i = 0; i < 4; ++i) {
;         const int cid = tid + NT * i;
;         const int row = cid >> 3, kc = cid & 7;
;         if (AT && kn < 8) {
;           const int kr = cid >> 5, tc = cid & 31;
;           rr[i] = *(const u32x4*)(RT + (size_t)(kn * 64 + kr) * ldrt + tc * 8);
;         } else {
;           rr[i] = *(const u32x4*)(R + (size_t)row * ldr + kn * 64 + kc * 8);
;         }
;         cr[i] = *(const u32x4*)(Cm + (size_t)row * ldc + kn * 64 + kc * 8);
;       }
;     }
;     __builtin_amdgcn_sched_barrier(0x38F);
;     if (kt >= 0) {
;       const u16* Rs = S0 + (kt & 1) * STG;
;       const u16* Cs = Rs + 256 * 72;
;       const u16* RTs = Rs;
; #pragma unroll
;       for (int ks = 0; ks < 4; ++ks) {
;         bf16x8 rf[2];
; #pragma unroll
;         for (int rb = 0; rb < 2; ++rb) {
;           if (AT && kt < 8) {
;             const u16* src = RTs + (16 * ks + 8 * g) * 264 + 64 * wr + 32 * rb + li;
;             bf16x8 t;
; #pragma unroll
;             for (int j = 0; j < 8; ++j) t[j] = (short)src[j * 264];
;             rf[rb] = t;
;           } else {
;             rf[rb] = *(const bf16x8*)(Rs + (64 * wr + 32 * rb + li) * 72 + 16 * ks + 8 * g);
;           }
;         }
; #pragma unroll
;         for (int cb = 0; cb < 4; ++cb) {
;           const bf16x8 cfv = *(const bf16x8*)(Cs + (128 * wc + 32 * cb + li) * 72 + 16 * ks + 8 * g);
; #pragma unroll
;           for (int rb = 0; rb < 2; ++rb) acc[rb][cb] = MFMA(rf[rb], cfv, acc[rb][cb]);
	s_waitcnt vmcnt(7)
	ds_write_b128 v147, v[166:169]
	s_waitcnt vmcnt(5)
	ds_write_b128 v152, v[178:181]
	ds_write_b128 v162, v[170:173]
	s_waitcnt vmcnt(4)
	ds_write_b128 v153, v[182:185]
	s_waitcnt vmcnt(2)
	ds_write_b128 v163, v[220:223]
	ds_write_b128 v154, v[194:197]
	s_waitcnt vmcnt(1)
	ds_write_b128 v164, v[228:231]
	s_waitcnt vmcnt(0)
	ds_write_b128 v155, v[174:177]
	v_mfma_f32_32x32x16_bf16 v[16:31], v[190:193], v[224:227], v[16:31]
	ds_read_b128 v[166:169], v136
	ds_read_b128 v[170:173], v151 offset:36864
	ds_read_b128 v[174:177], v136 offset:32
	ds_read_b128 v[178:181], v151 offset:36896
	ds_read_b128 v[182:185], v136 offset:4608
	ds_read_b128 v[190:193], v136 offset:4640
	s_waitcnt lgkmcnt(4)
	v_mfma_f32_32x32x16_bf16 v[64:79], v[166:169], v[170:173], v[64:79]
	s_waitcnt lgkmcnt(1)
	v_mfma_f32_32x32x16_bf16 v[0:15], v[182:185], v[170:173], v[0:15]
	ds_read_b128 v[170:173], v151 offset:41472
	ds_read_b128 v[194:197], v151 offset:41504
	s_waitcnt lgkmcnt(1)
	v_mfma_f32_32x32x16_bf16 v[96:111], v[166:169], v[170:173], v[96:111]
	v_mfma_f32_32x32x16_bf16 v[32:47], v[182:185], v[170:173], v[32:47]
	ds_read_b128 v[170:173], v151 offset:46080
	ds_read_b128 v[220:223], v151 offset:46112
	s_waitcnt lgkmcnt(1)
	v_mfma_f32_32x32x16_bf16 v[112:127], v[166:169], v[170:173], v[112:127]
	v_mfma_f32_32x32x16_bf16 v[48:63], v[182:185], v[170:173], v[48:63]
	ds_read_b128 v[170:173], v151 offset:50688
	ds_read_b128 v[224:227], v151 offset:50720
	s_waitcnt lgkmcnt(1)
	v_mfma_f32_32x32x16_bf16 v[80:95], v[166:169], v[170:173], v[80:95]
	v_mfma_f32_32x32x16_bf16 v[16:31], v[182:185], v[170:173], v[16:31]
	v_mfma_f32_32x32x16_bf16 v[64:79], v[174:177], v[178:181], v[64:79]
	v_mfma_f32_32x32x16_bf16 v[0:15], v[190:193], v[178:181], v[0:15]
	v_mfma_f32_32x32x16_bf16 v[96:111], v[174:177], v[194:197], v[96:111]
	v_mfma_f32_32x32x16_bf16 v[32:47], v[190:193], v[194:197], v[32:47]
	v_mfma_f32_32x32x16_bf16 v[112:127], v[174:177], v[220:223], v[112:127]
	v_mfma_f32_32x32x16_bf16 v[48:63], v[190:193], v[220:223], v[48:63]
	s_waitcnt lgkmcnt(0)
	v_mfma_f32_32x32x16_bf16 v[80:95], v[174:177], v[224:227], v[80:95]
	ds_read_b128 v[166:169], v136 offset:64
	ds_read_b128 v[170:173], v151 offset:36928
	ds_read_b128 v[174:177], v136 offset:96
	ds_read_b128 v[178:181], v151 offset:36960
	v_mfma_f32_32x32x16_bf16 v[16:31], v[190:193], v[224:227], v[16:31]
	ds_read_b128 v[182:185], v136 offset:4672
	ds_read_b128 v[190:193], v136 offset:4704
	s_waitcnt lgkmcnt(4)
	v_mfma_f32_32x32x16_bf16 v[64:79], v[166:169], v[170:173], v[64:79]
	s_waitcnt lgkmcnt(1)
	v_mfma_f32_32x32x16_bf16 v[0:15], v[182:185], v[170:173], v[0:15]
	ds_read_b128 v[170:173], v151 offset:41536
	ds_read_b128 v[194:197], v151 offset:41568
	s_waitcnt lgkmcnt(1)
	v_mfma_f32_32x32x16_bf16 v[96:111], v[166:169], v[170:173], v[96:111]
	v_mfma_f32_32x32x16_bf16 v[32:47], v[182:185], v[170:173], v[32:47]
	ds_read_b128 v[170:173], v151 offset:46144
	ds_read_b128 v[220:223], v151 offset:46176
	s_waitcnt lgkmcnt(1)
	v_mfma_f32_32x32x16_bf16 v[112:127], v[166:169], v[170:173], v[112:127]
	v_mfma_f32_32x32x16_bf16 v[48:63], v[182:185], v[170:173], v[48:63]
	ds_read_b128 v[170:173], v151 offset:50752
	ds_read_b128 v[224:227], v151 offset:50784
	s_waitcnt lgkmcnt(1)
	v_mfma_f32_32x32x16_bf16 v[80:95], v[166:169], v[170:173], v[80:95]
	v_mfma_f32_32x32x16_bf16 v[16:31], v[182:185], v[170:173], v[16:31]
	v_mfma_f32_32x32x16_bf16 v[64:79], v[174:177], v[178:181], v[64:79]
	v_mfma_f32_32x32x16_bf16 v[0:15], v[190:193], v[178:181], v[0:15]
	v_mfma_f32_32x32x16_bf16 v[96:111], v[174:177], v[194:197], v[96:111]
	v_mfma_f32_32x32x16_bf16 v[32:47], v[190:193], v[194:197], v[32:47]
	v_mfma_f32_32x32x16_bf16 v[112:127], v[174:177], v[220:223], v[112:127]
	v_mfma_f32_32x32x16_bf16 v[48:63], v[190:193], v[220:223], v[48:63]
	global_load_dwordx4 v[166:169], v[138:139], off offset:768
	global_load_dwordx4 v[170:173], v[140:141], off offset:768
	global_load_dwordx4 v[178:181], v[128:129], off offset:1792
	global_load_dwordx4 v[182:185], v[130:131], off offset:1792
	global_load_dwordx4 v[194:197], v[132:133], off offset:1792
	global_load_dwordx4 v[220:223], v[142:143], off offset:768
	global_load_dwordx4 v[228:231], v[144:145], off offset:768
	s_waitcnt lgkmcnt(0)
	v_mfma_f32_32x32x16_bf16 v[80:95], v[174:177], v[224:227], v[80:95]
	global_load_dwordx4 v[174:177], v[134:135], off offset:1792
	s_barrier
; template <bool AT>
; DI void gemm_main(f32x16 (&acc)[2][4], const u16* __restrict__ R, int ldr, const u16* __restrict__ Cm, int ldc,
;                   const u16* __restrict__ RT, int ldrt, int K, char* smem, int tid) {
;     ...
;   for (int kt = -1; kt < nk; ++kt) {
;     if (kt + 1 < nk) {
;       const int ks1 = kt + 1;
;       u16* Rs = S0 + (ks1 & 1) * STG;
;       u16* Cs = Rs + 256 * 72;
; #pragma unroll
;       for (int i = 0; i < 4; ++i) {
;         const int cid = tid + NT * i;
;         const int row = cid >> 3, kc = cid & 7;
;         if (AT && ks1 < 8) {
;           const int kr = cid >> 5, tc = cid & 31;
;           *(u32x4*)(Rs + kr * 264 + tc * 8) = rr[i];
;         } else {
;           *(u32x4*)(Rs + row * 72 + kc * 8) = rr[i];
;         }
;         *(u32x4*)(Cs + row * 72 + kc * 8) = cr[i];
;       }
;     }
;     if (kt + 2 < nk) {
;       const int kn = kt + 2;
; #pragma unroll
;       for (int i = 0; i < 4; ++i) {
;         const int cid = tid + NT * i;
;         const int row = cid >> 3, kc = cid & 7;
;         if (AT && kn < 8) {
;           const int kr = cid >> 5, tc = cid & 31;
;           rr[i] = *(const u32x4*)(RT + (size_t)(kn * 64 + kr) * ldrt + tc * 8);
;         } else {
;           rr[i] = *(const u32x4*)(R + (size_t)row * ldr + kn * 64 + kc * 8);
;         }
;         cr[i] = *(const u32x4*)(Cm + (size_t)row * ldc + kn * 64 + kc * 8);
;       }
;     }
;     __builtin_amdgcn_sched_barrier(0x38F);
;     if (kt >= 0) {
;       const u16* Rs = S0 + (kt & 1) * STG;
;       const u16* Cs = Rs + 256 * 72;
;       const u16* RTs = Rs;
; #pragma unroll
;       for (int ks = 0; ks < 4; ++ks) {
;         bf16x8 rf[2];
; #pragma unroll
;         for (int rb = 0; rb < 2; ++rb) {
;           if (AT && kt < 8) {
;             const u16* src = RTs + (16 * ks + 8 * g) * 264 + 64 * wr + 32 * rb + li;
;             bf16x8 t;
; #pragma unroll
;             for (int j = 0; j < 8; ++j) t[j] = (short)src[j * 264];
;             rf[rb] = t;
;           } else {
;             rf[rb] = *(const bf16x8*)(Rs + (64 * wr + 32 * rb + li) * 72 + 16 * ks + 8 * g);
;           }
;         }
; #pragma unroll
;         for (int cb = 0; cb < 4; ++cb) {
;           const bf16x8 cfv = *(const bf16x8*)(Cs + (128 * wc + 32 * cb + li) * 72 + 16 * ks + 8 * g);
; #pragma unroll
;           for (int rb = 0; rb < 2; ++rb) acc[rb][cb] = MFMA(rf[rb], cfv, acc[rb][cb]);
	s_waitcnt vmcnt(7)
	ds_write_b128 v156, v[166:169]
	s_waitcnt vmcnt(5)
	ds_write_b128 v156, v[178:181] offset:36864
	ds_write_b128 v157, v[170:173]
	s_waitcnt vmcnt(4)
	ds_write_b128 v157, v[182:185] offset:36864
	s_waitcnt vmcnt(2)
	ds_write_b128 v158, v[220:223]
	ds_write_b128 v158, v[194:197] offset:36864
	s_waitcnt vmcnt(1)
	ds_write_b128 v159, v[228:231]
	s_waitcnt vmcnt(0)
	ds_write_b128 v159, v[174:177] offset:36864
	ds_read_b128 v[156:159], v146
	ds_read_b128 v[166:169], v160
	ds_read_b128 v[170:173], v146 offset:32
	ds_read_b128 v[174:177], v160 offset:32
	ds_read_b128 v[178:181], v146 offset:4608
	ds_read_b128 v[182:185], v146 offset:4640
	v_mfma_f32_32x32x16_bf16 v[16:31], v[190:193], v[224:227], v[16:31]
	s_waitcnt lgkmcnt(4)
	v_mfma_f32_32x32x16_bf16 v[64:79], v[156:159], v[166:169], v[64:79]
	s_waitcnt lgkmcnt(1)
	v_mfma_f32_32x32x16_bf16 v[0:15], v[178:181], v[166:169], v[0:15]
	ds_read_b128 v[166:169], v160 offset:4608
	ds_read_b128 v[190:193], v160 offset:4640
	s_waitcnt lgkmcnt(1)
	v_mfma_f32_32x32x16_bf16 v[96:111], v[156:159], v[166:169], v[96:111]
	v_mfma_f32_32x32x16_bf16 v[32:47], v[178:181], v[166:169], v[32:47]
	ds_read_b128 v[166:169], v160 offset:9216
	ds_read_b128 v[194:197], v160 offset:9248
	s_waitcnt lgkmcnt(1)
	v_mfma_f32_32x32x16_bf16 v[112:127], v[156:159], v[166:169], v[112:127]
	v_mfma_f32_32x32x16_bf16 v[48:63], v[178:181], v[166:169], v[48:63]
	ds_read_b128 v[166:169], v160 offset:13824
	ds_read_b128 v[220:223], v160 offset:13856
	s_waitcnt lgkmcnt(1)
	v_mfma_f32_32x32x16_bf16 v[80:95], v[156:159], v[166:169], v[80:95]
	v_mfma_f32_32x32x16_bf16 v[16:31], v[178:181], v[166:169], v[16:31]
	v_mfma_f32_32x32x16_bf16 v[64:79], v[170:173], v[174:177], v[64:79]
	v_mfma_f32_32x32x16_bf16 v[0:15], v[182:185], v[174:177], v[0:15]
	v_mfma_f32_32x32x16_bf16 v[96:111], v[170:173], v[190:193], v[96:111]
	v_mfma_f32_32x32x16_bf16 v[32:47], v[182:185], v[190:193], v[32:47]
	v_mfma_f32_32x32x16_bf16 v[112:127], v[170:173], v[194:197], v[112:127]
	v_mfma_f32_32x32x16_bf16 v[48:63], v[182:185], v[194:197], v[48:63]
	s_waitcnt lgkmcnt(0)
	v_mfma_f32_32x32x16_bf16 v[80:95], v[170:173], v[220:223], v[80:95]
	ds_read_b128 v[156:159], v146 offset:64
	ds_read_b128 v[166:169], v160 offset:64
	ds_read_b128 v[170:173], v146 offset:96
	ds_read_b128 v[174:177], v160 offset:96
	v_mfma_f32_32x32x16_bf16 v[16:31], v[182:185], v[220:223], v[16:31]
	ds_read_b128 v[178:181], v146 offset:4672
	ds_read_b128 v[182:185], v146 offset:4704
	s_waitcnt lgkmcnt(4)
	v_mfma_f32_32x32x16_bf16 v[64:79], v[156:159], v[166:169], v[64:79]
	s_waitcnt lgkmcnt(1)
	v_mfma_f32_32x32x16_bf16 v[0:15], v[178:181], v[166:169], v[0:15]
	ds_read_b128 v[166:169], v160 offset:4672
	ds_read_b128 v[190:193], v160 offset:4704
	s_waitcnt lgkmcnt(1)
	v_mfma_f32_32x32x16_bf16 v[96:111], v[156:159], v[166:169], v[96:111]
	v_mfma_f32_32x32x16_bf16 v[32:47], v[178:181], v[166:169], v[32:47]
	ds_read_b128 v[166:169], v160 offset:9280
	ds_read_b128 v[194:197], v160 offset:9312
	s_waitcnt lgkmcnt(1)
	v_mfma_f32_32x32x16_bf16 v[112:127], v[156:159], v[166:169], v[112:127]
	v_mfma_f32_32x32x16_bf16 v[48:63], v[178:181], v[166:169], v[48:63]
	ds_read_b128 v[166:169], v160 offset:13888
	ds_read_b128 v[220:223], v160 offset:13920
	s_waitcnt lgkmcnt(1)
	v_mfma_f32_32x32x16_bf16 v[80:95], v[156:159], v[166:169], v[80:95]
	v_mfma_f32_32x32x16_bf16 v[16:31], v[178:181], v[166:169], v[16:31]
	v_mfma_f32_32x32x16_bf16 v[64:79], v[170:173], v[174:177], v[64:79]
	v_mfma_f32_32x32x16_bf16 v[0:15], v[182:185], v[174:177], v[0:15]
	global_load_dwordx4 v[156:159], v[138:139], off offset:896
	s_nop 0
	global_load_dwordx4 v[138:141], v[140:141], off offset:896
	s_nop 0
	global_load_dwordx4 v[166:169], v[128:129], off offset:1920
	s_nop 0
	global_load_dwordx4 v[128:131], v[130:131], off offset:1920
	s_nop 0
	global_load_dwordx4 v[174:177], v[132:133], off offset:1920
	global_load_dwordx4 v[178:181], v[142:143], off offset:896
	s_nop 0
	global_load_dwordx4 v[142:145], v[144:145], off offset:896
	s_nop 0
	global_load_dwordx4 v[132:135], v[134:135], off offset:1920
	s_waitcnt lgkmcnt(0)
	s_barrier
	s_waitcnt vmcnt(7)
	ds_write_b128 v147, v[156:159]
	s_waitcnt vmcnt(5)
	ds_write_b128 v152, v[166:169]
	ds_write_b128 v162, v[138:141]
	s_waitcnt vmcnt(4)
	ds_write_b128 v153, v[128:131]
	s_waitcnt vmcnt(2)
	ds_write_b128 v163, v[178:181]
	ds_write_b128 v154, v[174:177]
	s_waitcnt vmcnt(1)
	ds_write_b128 v164, v[142:145]
	s_waitcnt vmcnt(0)
	ds_write_b128 v155, v[132:135]
	v_mfma_f32_32x32x16_bf16 v[96:111], v[170:173], v[190:193], v[96:111]
	ds_read_b128 v[128:131], v136
	ds_read_b128 v[132:135], v151 offset:36864
	ds_read_b128 v[138:141], v136 offset:32
	ds_read_b128 v[142:145], v151 offset:36896
	ds_read_b128 v[152:155], v136 offset:4608
	ds_read_b128 v[156:159], v136 offset:4640
	v_mfma_f32_32x32x16_bf16 v[32:47], v[182:185], v[190:193], v[32:47]
	v_mfma_f32_32x32x16_bf16 v[112:127], v[170:173], v[194:197], v[112:127]
	v_mfma_f32_32x32x16_bf16 v[48:63], v[182:185], v[194:197], v[48:63]
	s_waitcnt lgkmcnt(4)
	v_mfma_f32_32x32x16_bf16 v[64:79], v[128:131], v[132:135], v[64:79]
	s_waitcnt lgkmcnt(1)
	v_mfma_f32_32x32x16_bf16 v[0:15], v[152:155], v[132:135], v[0:15]
	ds_read_b128 v[132:135], v151 offset:41472
	ds_read_b128 v[162:165], v151 offset:41504
	v_mfma_f32_32x32x16_bf16 v[80:95], v[170:173], v[220:223], v[80:95]
	v_mfma_f32_32x32x16_bf16 v[16:31], v[182:185], v[220:223], v[16:31]
	s_waitcnt lgkmcnt(1)
	v_mfma_f32_32x32x16_bf16 v[96:111], v[128:131], v[132:135], v[96:111]
	v_mfma_f32_32x32x16_bf16 v[32:47], v[152:155], v[132:135], v[32:47]
	ds_read_b128 v[132:135], v151 offset:46080
	ds_read_b128 v[166:169], v151 offset:46112
	s_waitcnt lgkmcnt(1)
; #define MFMA(a, b, c) __builtin_amdgcn_mfma_f32_32x32x16_bf16((a), (b), (c), 0, 0, 0)
; template <bool AT>
; DI void gemm_main(f32x16 (&acc)[2][4], const u16* __restrict__ R, int ldr, const u16* __restrict__ Cm, int ldc,
;                   const u16* __restrict__ RT, int ldrt, int K, char* smem, int tid) {
;     ...
;     if (kt >= 0) {
;       const u16* Rs = S0 + (kt & 1) * STG;
;       const u16* Cs = Rs + 256 * 72;
;       const u16* RTs = Rs;
; #pragma unroll
;       for (int ks = 0; ks < 4; ++ks) {
;         bf16x8 rf[2];
; #pragma unroll
;         for (int rb = 0; rb < 2; ++rb) {
;           if (AT && kt < 8) {
;             const u16* src = RTs + (16 * ks + 8 * g) * 264 + 64 * wr + 32 * rb + li;
;             bf16x8 t;
; #pragma unroll
;             for (int j = 0; j < 8; ++j) t[j] = (short)src[j * 264];
;             rf[rb] = t;
;           } else {
;             rf[rb] = *(const bf16x8*)(Rs + (64 * wr + 32 * rb + li) * 72 + 16 * ks + 8 * g);
;           }
;         }
; #pragma unroll
;         for (int cb = 0; cb < 4; ++cb) {
;           const bf16x8 cfv = *(const bf16x8*)(Cs + (128 * wc + 32 * cb + li) * 72 + 16 * ks + 8 * g);
; #pragma unroll
;           for (int rb = 0; rb < 2; ++rb) acc[rb][cb] = MFMA(rf[rb], cfv, acc[rb][cb]);
;         }
;       }
;     }
;     __syncthreads();
; DI void gemm_out_tile(const P& p, int l, int id, char* smem) {
;     ...
;   __syncthreads();
	v_mfma_f32_32x32x16_bf16 v[112:127], v[128:131], v[132:135], v[112:127]
	v_mfma_f32_32x32x16_bf16 v[48:63], v[152:155], v[132:135], v[48:63]
	ds_read_b128 v[132:135], v151 offset:50688
	ds_read_b128 v[170:173], v151 offset:50720
	s_waitcnt lgkmcnt(1)
	v_mfma_f32_32x32x16_bf16 v[80:95], v[128:131], v[132:135], v[80:95]
	v_mfma_f32_32x32x16_bf16 v[16:31], v[152:155], v[132:135], v[16:31]
	v_mfma_f32_32x32x16_bf16 v[64:79], v[138:141], v[142:145], v[64:79]
	v_mfma_f32_32x32x16_bf16 v[0:15], v[156:159], v[142:145], v[0:15]
	v_mfma_f32_32x32x16_bf16 v[96:111], v[138:141], v[162:165], v[96:111]
	v_mfma_f32_32x32x16_bf16 v[32:47], v[156:159], v[162:165], v[32:47]
	v_mfma_f32_32x32x16_bf16 v[112:127], v[138:141], v[166:169], v[112:127]
	v_mfma_f32_32x32x16_bf16 v[48:63], v[156:159], v[166:169], v[48:63]
	s_waitcnt lgkmcnt(0)
	v_mfma_f32_32x32x16_bf16 v[80:95], v[138:141], v[170:173], v[80:95]
	ds_read_b128 v[128:131], v136 offset:64
	ds_read_b128 v[132:135], v151 offset:36928
	ds_read_b128 v[138:141], v136 offset:96
	ds_read_b128 v[142:145], v151 offset:36960
	v_mfma_f32_32x32x16_bf16 v[16:31], v[156:159], v[170:173], v[16:31]
	ds_read_b128 v[152:155], v136 offset:4672
	ds_read_b128 v[156:159], v136 offset:4704
	s_waitcnt lgkmcnt(4)
	v_mfma_f32_32x32x16_bf16 v[64:79], v[128:131], v[132:135], v[64:79]
	s_waitcnt lgkmcnt(1)
	v_mfma_f32_32x32x16_bf16 v[0:15], v[152:155], v[132:135], v[0:15]
	ds_read_b128 v[132:135], v151 offset:41536
	ds_read_b128 v[162:165], v151 offset:41568
	s_waitcnt lgkmcnt(1)
	v_mfma_f32_32x32x16_bf16 v[96:111], v[128:131], v[132:135], v[96:111]
	v_mfma_f32_32x32x16_bf16 v[32:47], v[152:155], v[132:135], v[32:47]
	ds_read_b128 v[132:135], v151 offset:46144
	ds_read_b128 v[166:169], v151 offset:46176
	s_waitcnt lgkmcnt(1)
	v_mfma_f32_32x32x16_bf16 v[112:127], v[128:131], v[132:135], v[112:127]
	v_mfma_f32_32x32x16_bf16 v[48:63], v[152:155], v[132:135], v[48:63]
	ds_read_b128 v[132:135], v151 offset:50752
	ds_read_b128 v[170:173], v151 offset:50784
	s_waitcnt lgkmcnt(0)
	s_barrier
	v_mfma_f32_32x32x16_bf16 v[80:95], v[128:131], v[132:135], v[80:95]
	v_mfma_f32_32x32x16_bf16 v[16:31], v[152:155], v[132:135], v[16:31]
	v_mfma_f32_32x32x16_bf16 v[64:79], v[138:141], v[142:145], v[64:79]
	v_mfma_f32_32x32x16_bf16 v[0:15], v[156:159], v[142:145], v[0:15]
	v_mfma_f32_32x32x16_bf16 v[96:111], v[138:141], v[162:165], v[96:111]
	v_mfma_f32_32x32x16_bf16 v[32:47], v[156:159], v[162:165], v[32:47]
	v_mfma_f32_32x32x16_bf16 v[112:127], v[138:141], v[166:169], v[112:127]
	v_mfma_f32_32x32x16_bf16 v[48:63], v[156:159], v[166:169], v[48:63]
	v_mfma_f32_32x32x16_bf16 v[80:95], v[138:141], v[170:173], v[80:95]
	ds_read_b128 v[128:131], v146
	ds_read_b128 v[132:135], v160
	ds_read_b128 v[138:141], v146 offset:32
	ds_read_b128 v[142:145], v160 offset:32
	v_mfma_f32_32x32x16_bf16 v[16:31], v[156:159], v[170:173], v[16:31]
	ds_read_b128 v[152:155], v146 offset:4608
	ds_read_b128 v[156:159], v146 offset:4640
	s_waitcnt lgkmcnt(4)
	v_mfma_f32_32x32x16_bf16 v[64:79], v[128:131], v[132:135], v[64:79]
	s_waitcnt lgkmcnt(1)
	v_mfma_f32_32x32x16_bf16 v[0:15], v[152:155], v[132:135], v[0:15]
	ds_read_b128 v[132:135], v160 offset:4608
	ds_read_b128 v[162:165], v160 offset:4640
	s_waitcnt lgkmcnt(1)
	v_mfma_f32_32x32x16_bf16 v[96:111], v[128:131], v[132:135], v[96:111]
	v_mfma_f32_32x32x16_bf16 v[32:47], v[152:155], v[132:135], v[32:47]
	ds_read_b128 v[132:135], v160 offset:9216
	ds_read_b128 v[166:169], v160 offset:9248
	s_waitcnt lgkmcnt(1)
	v_mfma_f32_32x32x16_bf16 v[112:127], v[128:131], v[132:135], v[112:127]
	v_mfma_f32_32x32x16_bf16 v[48:63], v[152:155], v[132:135], v[48:63]
	ds_read_b128 v[132:135], v160 offset:13824
	ds_read_b128 v[170:173], v160 offset:13856
	s_waitcnt lgkmcnt(1)
	v_mfma_f32_32x32x16_bf16 v[80:95], v[128:131], v[132:135], v[80:95]
	v_mfma_f32_32x32x16_bf16 v[16:31], v[152:155], v[132:135], v[16:31]
	v_mfma_f32_32x32x16_bf16 v[64:79], v[138:141], v[142:145], v[64:79]
	v_mfma_f32_32x32x16_bf16 v[0:15], v[156:159], v[142:145], v[0:15]
	v_mfma_f32_32x32x16_bf16 v[96:111], v[138:141], v[162:165], v[96:111]
	v_mfma_f32_32x32x16_bf16 v[32:47], v[156:159], v[162:165], v[32:47]
	v_mfma_f32_32x32x16_bf16 v[112:127], v[138:141], v[166:169], v[112:127]
	v_mfma_f32_32x32x16_bf16 v[48:63], v[156:159], v[166:169], v[48:63]
	s_waitcnt lgkmcnt(0)
	v_mfma_f32_32x32x16_bf16 v[80:95], v[138:141], v[170:173], v[80:95]
	ds_read_b128 v[128:131], v146 offset:64
	ds_read_b128 v[132:135], v160 offset:64
	ds_read_b128 v[138:141], v146 offset:96
	ds_read_b128 v[142:145], v160 offset:96
	v_mfma_f32_32x32x16_bf16 v[16:31], v[156:159], v[170:173], v[16:31]
	ds_read_b128 v[152:155], v146 offset:4672
	ds_read_b128 v[156:159], v146 offset:4704
	s_waitcnt lgkmcnt(4)
	v_mfma_f32_32x32x16_bf16 v[64:79], v[128:131], v[132:135], v[64:79]
	s_waitcnt lgkmcnt(1)
	v_mfma_f32_32x32x16_bf16 v[0:15], v[152:155], v[132:135], v[0:15]
	ds_read_b128 v[132:135], v160 offset:4672
	ds_read_b128 v[162:165], v160 offset:4704
	s_waitcnt lgkmcnt(1)
	v_mfma_f32_32x32x16_bf16 v[96:111], v[128:131], v[132:135], v[96:111]
	v_mfma_f32_32x32x16_bf16 v[32:47], v[152:155], v[132:135], v[32:47]
	ds_read_b128 v[132:135], v160 offset:9280
	ds_read_b128 v[166:169], v160 offset:9312
	ds_read_b128 v[170:173], v160 offset:13888
	ds_read_b128 v[174:177], v160 offset:13920
	s_waitcnt lgkmcnt(0)
	s_barrier
	s_barrier
; DI u16 f2bf(float a) { return (u16)(pack2(a, 0.f) & 0xffffu); }
; DI float bf2f(unsigned v) { return __uint_as_float(v << 16); }
; DI int crow(int reg, int g) { return (reg & 3) + 8 * (reg >> 2) + 4 * g; }
; DI void gemm_out_tile(const P& p, int l, int id, char* smem) {
;     ...
; #pragma unroll
;   for (int rb = 0; rb < 2; ++rb) {
; #pragma unroll
;     for (int reg = 0; reg < 16; ++reg) {
;       const int rl = 64 * wr + 32 * rb + crow(reg, g);
;       const int tok = m0 + rl;
;       float sacc = 0.f;
; #pragma unroll
;       for (int cb = 0; cb < 4; ++cb) {
;         const int col = n0 + 128 * wc + 32 * cb + li;
;         const size_t idx = (size_t)tok * 1024 + col;
;         const float hn = bf2f((unsigned)p.hb[idx]) + acc[rb][cb][reg];
;         p.hb[idx] = f2bf(hn);
;         sacc += hn * hn;
;       }
; #pragma unroll
;       for (int m = 16; m >= 1; m >>= 1) sacc += __shfl_xor(sacc, m);
;       if (li == 0) red[wc * 256 + rl] = sacc;
;     }
;   }
	v_mfma_f32_32x32x16_bf16 v[112:127], v[128:131], v[132:135], v[112:127]
	v_mfma_f32_32x32x16_bf16 v[80:95], v[128:131], v[170:173], v[80:95]
	v_mfma_f32_32x32x16_bf16 v[64:79], v[138:141], v[142:145], v[64:79]
	v_mfma_f32_32x32x16_bf16 v[96:111], v[138:141], v[162:165], v[96:111]
	v_mfma_f32_32x32x16_bf16 v[112:127], v[138:141], v[166:169], v[112:127]
	v_mfma_f32_32x32x16_bf16 v[80:95], v[138:141], v[174:177], v[80:95]
	v_mfma_f32_32x32x16_bf16 v[48:63], v[152:155], v[132:135], v[48:63]
	v_mfma_f32_32x32x16_bf16 v[16:31], v[152:155], v[170:173], v[16:31]
	v_mfma_f32_32x32x16_bf16 v[0:15], v[156:159], v[142:145], v[0:15]
	v_mfma_f32_32x32x16_bf16 v[32:47], v[156:159], v[162:165], v[32:47]
	v_mfma_f32_32x32x16_bf16 v[48:63], v[156:159], v[166:169], v[48:63]
	v_mfma_f32_32x32x16_bf16 v[16:31], v[156:159], v[174:177], v[16:31]
	v_lshrrev_b32_e32 v133, 7, v148
	v_bfe_u32 v134, v148, 5, 1
	v_bfe_u32 v135, v148, 6, 1
	v_and_b32_e32 v136, 31, v148
	v_lshlrev_b32_e32 v133, 6, v133
	v_lshl_add_u32 v137, v134, 2, v133
	v_lshl_add_u32 v132, v135, 8, v137
	v_lshlrev_b32_e32 v132, 2, v132
	v_add_u32_e32 v137, s25, v137
	s_lshl_b32 s6, s24, 8
	v_lshl_add_u32 v136, v135, 7, v136
	v_add_u32_e32 v136, s6, v136
	v_lshlrev_b32_e32 v136, 1, v136
	v_lshl_add_u32 v128, v137, 11, v136
	v_add_u32_e32 v129, 0x1000, v128
	v_mov_b32_e32 v130, v128
	v_mov_b32_e32 v131, v129
	global_load_ushort v150, v128, s[10:11] offset:0
	global_load_ushort v151, v128, s[10:11] offset:64
	global_load_ushort v152, v128, s[10:11] offset:128
	global_load_ushort v153, v128, s[10:11] offset:192
	global_load_ushort v154, v128, s[10:11] offset:2048
	global_load_ushort v155, v128, s[10:11] offset:2112
	global_load_ushort v156, v128, s[10:11] offset:2176
	global_load_ushort v157, v128, s[10:11] offset:2240
	global_load_ushort v158, v129, s[10:11] offset:0
	global_load_ushort v159, v129, s[10:11] offset:64
	global_load_ushort v160, v129, s[10:11] offset:128
	global_load_ushort v161, v129, s[10:11] offset:192
	global_load_ushort v162, v129, s[10:11] offset:2048
	global_load_ushort v163, v129, s[10:11] offset:2112
	global_load_ushort v164, v129, s[10:11] offset:2176
	global_load_ushort v165, v129, s[10:11] offset:2240
	v_add_u32_e32 v128, 0x4000, v128
	v_add_u32_e32 v129, 0x4000, v129
	global_load_ushort v166, v128, s[10:11] offset:0
	global_load_ushort v167, v128, s[10:11] offset:64
	global_load_ushort v168, v128, s[10:11] offset:128
	global_load_ushort v169, v128, s[10:11] offset:192
	global_load_ushort v170, v128, s[10:11] offset:2048
	global_load_ushort v171, v128, s[10:11] offset:2112
	global_load_ushort v172, v128, s[10:11] offset:2176
	global_load_ushort v173, v128, s[10:11] offset:2240
	global_load_ushort v174, v129, s[10:11] offset:0
	global_load_ushort v175, v129, s[10:11] offset:64
	global_load_ushort v176, v129, s[10:11] offset:128
	global_load_ushort v177, v129, s[10:11] offset:192
	global_load_ushort v178, v129, s[10:11] offset:2048
	global_load_ushort v179, v129, s[10:11] offset:2112
	global_load_ushort v180, v129, s[10:11] offset:2176
	global_load_ushort v181, v129, s[10:11] offset:2240
	v_add_u32_e32 v128, 0x4000, v128
	v_add_u32_e32 v129, 0x4000, v129
	s_waitcnt vmcnt(16)
	v_lshlrev_b32_e32 v150, 16, v150
	v_lshlrev_b32_e32 v151, 16, v151
	v_lshlrev_b32_e32 v152, 16, v152
	v_lshlrev_b32_e32 v153, 16, v153
	v_lshlrev_b32_e32 v154, 16, v154
	v_lshlrev_b32_e32 v155, 16, v155
	v_lshlrev_b32_e32 v156, 16, v156
	v_lshlrev_b32_e32 v157, 16, v157
	v_lshlrev_b32_e32 v158, 16, v158
	v_lshlrev_b32_e32 v159, 16, v159
	v_lshlrev_b32_e32 v160, 16, v160
	v_lshlrev_b32_e32 v161, 16, v161
	v_lshlrev_b32_e32 v162, 16, v162
	v_lshlrev_b32_e32 v163, 16, v163
	v_lshlrev_b32_e32 v164, 16, v164
	v_lshlrev_b32_e32 v165, 16, v165
	v_add_f32_e32 v150, v64, v150
	v_add_f32_e32 v151, v96, v151
	v_add_f32_e32 v152, v112, v152
	v_add_f32_e32 v153, v80, v153
	v_add_f32_e32 v154, v65, v154
	v_add_f32_e32 v155, v97, v155
	v_add_f32_e32 v156, v113, v156
	v_add_f32_e32 v157, v81, v157
	v_add_f32_e32 v158, v66, v158
	v_add_f32_e32 v159, v98, v159
	v_add_f32_e32 v160, v114, v160
	v_add_f32_e32 v161, v82, v161
	v_add_f32_e32 v162, v67, v162
	v_add_f32_e32 v163, v99, v163
	v_add_f32_e32 v164, v115, v164
	v_add_f32_e32 v165, v83, v165
	v_mul_f32_e32 v138, v150, v150
	v_mul_f32_e32 v139, v154, v154
	v_mul_f32_e32 v140, v158, v158
	v_mul_f32_e32 v141, v162, v162
	v_fmac_f32_e32 v138, v151, v151
	v_fmac_f32_e32 v139, v155, v155
	v_fmac_f32_e32 v140, v159, v159
	v_fmac_f32_e32 v141, v163, v163
	v_fmac_f32_e32 v138, v152, v152
	v_fmac_f32_e32 v139, v156, v156
	v_fmac_f32_e32 v140, v160, v160
	v_fmac_f32_e32 v141, v164, v164
	v_fmac_f32_e32 v138, v153, v153
	v_fmac_f32_e32 v139, v157, v157
	v_fmac_f32_e32 v140, v161, v161
	v_fmac_f32_e32 v141, v165, v165
	v_cvt_pk_bf16_f32 v150, v150, v150
	v_cvt_pk_bf16_f32 v151, v151, v151
	v_cvt_pk_bf16_f32 v152, v152, v152
	v_cvt_pk_bf16_f32 v153, v153, v153
	v_cvt_pk_bf16_f32 v154, v154, v154
	v_cvt_pk_bf16_f32 v155, v155, v155
	v_cvt_pk_bf16_f32 v156, v156, v156
	v_cvt_pk_bf16_f32 v157, v157, v157
	v_cvt_pk_bf16_f32 v158, v158, v158
	v_cvt_pk_bf16_f32 v159, v159, v159
	v_cvt_pk_bf16_f32 v160, v160, v160
	v_cvt_pk_bf16_f32 v161, v161, v161
	v_cvt_pk_bf16_f32 v162, v162, v162
	v_cvt_pk_bf16_f32 v163, v163, v163
	v_cvt_pk_bf16_f32 v164, v164, v164
	v_cvt_pk_bf16_f32 v165, v165, v165
	global_store_short v130, v150, s[10:11] offset:0
	global_store_short v130, v151, s[10:11] offset:64
	global_store_short v130, v152, s[10:11] offset:128
	global_store_short v130, v153, s[10:11] offset:192
	global_store_short v130, v154, s[10:11] offset:2048
	global_store_short v130, v155, s[10:11] offset:2112
; DI u16 f2bf(float a) { return (u16)(pack2(a, 0.f) & 0xffffu); }
; DI float bf2f(unsigned v) { return __uint_as_float(v << 16); }
; DI int crow(int reg, int g) { return (reg & 3) + 8 * (reg >> 2) + 4 * g; }
; DI void gemm_out_tile(const P& p, int l, int id, char* smem) {
;     ...
; #pragma unroll
;   for (int rb = 0; rb < 2; ++rb) {
; #pragma unroll
;     for (int reg = 0; reg < 16; ++reg) {
;       const int rl = 64 * wr + 32 * rb + crow(reg, g);
;       const int tok = m0 + rl;
;       float sacc = 0.f;
; #pragma unroll
;       for (int cb = 0; cb < 4; ++cb) {
;         const int col = n0 + 128 * wc + 32 * cb + li;
;         const size_t idx = (size_t)tok * 1024 + col;
;         const float hn = bf2f((unsigned)p.hb[idx]) + acc[rb][cb][reg];
;         p.hb[idx] = f2bf(hn);
;         sacc += hn * hn;
;       }
; #pragma unroll
;       for (int m = 16; m >= 1; m >>= 1) sacc += __shfl_xor(sacc, m);
;       if (li == 0) red[wc * 256 + rl] = sacc;
;     }
;   }
	global_store_short v130, v156, s[10:11] offset:2176
	global_store_short v130, v157, s[10:11] offset:2240
	global_store_short v131, v158, s[10:11] offset:0
	global_store_short v131, v159, s[10:11] offset:64
	global_store_short v131, v160, s[10:11] offset:128
	global_store_short v131, v161, s[10:11] offset:192
	global_store_short v131, v162, s[10:11] offset:2048
	global_store_short v131, v163, s[10:11] offset:2112
	global_store_short v131, v164, s[10:11] offset:2176
	global_store_short v131, v165, s[10:11] offset:2240
	v_add_u32_e32 v130, 0x4000, v130
	v_add_u32_e32 v131, 0x4000, v131
	v_add_f32_dpp v138, v138, v138 quad_perm:[1,0,3,2] row_mask:0xf bank_mask:0xf
	v_add_f32_dpp v139, v139, v139 quad_perm:[1,0,3,2] row_mask:0xf bank_mask:0xf
	v_add_f32_dpp v140, v140, v140 quad_perm:[1,0,3,2] row_mask:0xf bank_mask:0xf
	v_add_f32_dpp v141, v141, v141 quad_perm:[1,0,3,2] row_mask:0xf bank_mask:0xf
	v_add_f32_dpp v138, v138, v138 quad_perm:[2,3,0,1] row_mask:0xf bank_mask:0xf
	v_add_f32_dpp v139, v139, v139 quad_perm:[2,3,0,1] row_mask:0xf bank_mask:0xf
	v_add_f32_dpp v140, v140, v140 quad_perm:[2,3,0,1] row_mask:0xf bank_mask:0xf
	v_add_f32_dpp v141, v141, v141 quad_perm:[2,3,0,1] row_mask:0xf bank_mask:0xf
	v_add_f32_dpp v138, v138, v138 row_half_mirror row_mask:0xf bank_mask:0xf
	v_add_f32_dpp v139, v139, v139 row_half_mirror row_mask:0xf bank_mask:0xf
	v_add_f32_dpp v140, v140, v140 row_half_mirror row_mask:0xf bank_mask:0xf
	v_add_f32_dpp v141, v141, v141 row_half_mirror row_mask:0xf bank_mask:0xf
	v_add_f32_dpp v138, v138, v138 row_mirror row_mask:0xf bank_mask:0xf
	v_add_f32_dpp v139, v139, v139 row_mirror row_mask:0xf bank_mask:0xf
	v_add_f32_dpp v140, v140, v140 row_mirror row_mask:0xf bank_mask:0xf
	v_add_f32_dpp v141, v141, v141 row_mirror row_mask:0xf bank_mask:0xf
	v_add_f32_dpp v138, v138, v138 row_bcast:15 row_mask:0xa bank_mask:0xf
	v_add_f32_dpp v139, v139, v139 row_bcast:15 row_mask:0xa bank_mask:0xf
	v_add_f32_dpp v140, v140, v140 row_bcast:15 row_mask:0xa bank_mask:0xf
	v_add_f32_dpp v141, v141, v141 row_bcast:15 row_mask:0xa bank_mask:0xf
	s_mov_b32 exec_lo, 0x10000
	s_mov_b32 exec_hi, 0x10000
	ds_write_b32 v132, v138 offset:0
	ds_write_b32 v132, v139 offset:4
	ds_write_b32 v132, v140 offset:8
	ds_write_b32 v132, v141 offset:12
	s_mov_b64 exec, -1
	global_load_ushort v150, v128, s[10:11] offset:0
	global_load_ushort v151, v128, s[10:11] offset:64
	global_load_ushort v152, v128, s[10:11] offset:128
	global_load_ushort v153, v128, s[10:11] offset:192
	global_load_ushort v154, v128, s[10:11] offset:2048
	global_load_ushort v155, v128, s[10:11] offset:2112
	global_load_ushort v156, v128, s[10:11] offset:2176
	global_load_ushort v157, v128, s[10:11] offset:2240
	global_load_ushort v158, v129, s[10:11] offset:0
	global_load_ushort v159, v129, s[10:11] offset:64
	global_load_ushort v160, v129, s[10:11] offset:128
	global_load_ushort v161, v129, s[10:11] offset:192
	global_load_ushort v162, v129, s[10:11] offset:2048
	global_load_ushort v163, v129, s[10:11] offset:2112
	global_load_ushort v164, v129, s[10:11] offset:2176
	global_load_ushort v165, v129, s[10:11] offset:2240
	v_add_u32_e32 v128, 0x4000, v128
	v_add_u32_e32 v129, 0x4000, v129
	s_waitcnt vmcnt(32)
	v_lshlrev_b32_e32 v166, 16, v166
	v_lshlrev_b32_e32 v167, 16, v167
	v_lshlrev_b32_e32 v168, 16, v168
	v_lshlrev_b32_e32 v169, 16, v169
	v_lshlrev_b32_e32 v170, 16, v170
	v_lshlrev_b32_e32 v171, 16, v171
	v_lshlrev_b32_e32 v172, 16, v172
	v_lshlrev_b32_e32 v173, 16, v173
	v_lshlrev_b32_e32 v174, 16, v174
	v_lshlrev_b32_e32 v175, 16, v175
	v_lshlrev_b32_e32 v176, 16, v176
	v_lshlrev_b32_e32 v177, 16, v177
	v_lshlrev_b32_e32 v178, 16, v178
	v_lshlrev_b32_e32 v179, 16, v179
	v_lshlrev_b32_e32 v180, 16, v180
	v_lshlrev_b32_e32 v181, 16, v181
	v_add_f32_e32 v166, v68, v166
	v_add_f32_e32 v167, v100, v167
	v_add_f32_e32 v168, v116, v168
	v_add_f32_e32 v169, v84, v169
	v_add_f32_e32 v170, v69, v170
	v_add_f32_e32 v171, v101, v171
	v_add_f32_e32 v172, v117, v172
	v_add_f32_e32 v173, v85, v173
	v_add_f32_e32 v174, v70, v174
	v_add_f32_e32 v175, v102, v175
	v_add_f32_e32 v176, v118, v176
	v_add_f32_e32 v177, v86, v177
	v_add_f32_e32 v178, v71, v178
	v_add_f32_e32 v179, v103, v179
	v_add_f32_e32 v180, v119, v180
	v_add_f32_e32 v181, v87, v181
	v_mul_f32_e32 v138, v166, v166
	v_mul_f32_e32 v139, v170, v170
	v_mul_f32_e32 v140, v174, v174
	v_mul_f32_e32 v141, v178, v178
	v_fmac_f32_e32 v138, v167, v167
	v_fmac_f32_e32 v139, v171, v171
	v_fmac_f32_e32 v140, v175, v175
	v_fmac_f32_e32 v141, v179, v179
	v_fmac_f32_e32 v138, v168, v168
	v_fmac_f32_e32 v139, v172, v172
	v_fmac_f32_e32 v140, v176, v176
	v_fmac_f32_e32 v141, v180, v180
	v_fmac_f32_e32 v138, v169, v169
	v_fmac_f32_e32 v139, v173, v173
	v_fmac_f32_e32 v140, v177, v177
	v_fmac_f32_e32 v141, v181, v181
	v_cvt_pk_bf16_f32 v166, v166, v166
	v_cvt_pk_bf16_f32 v167, v167, v167
	v_cvt_pk_bf16_f32 v168, v168, v168
	v_cvt_pk_bf16_f32 v169, v169, v169
	v_cvt_pk_bf16_f32 v170, v170, v170
	v_cvt_pk_bf16_f32 v171, v171, v171
	v_cvt_pk_bf16_f32 v172, v172, v172
	v_cvt_pk_bf16_f32 v173, v173, v173
	v_cvt_pk_bf16_f32 v174, v174, v174
	v_cvt_pk_bf16_f32 v175, v175, v175
	v_cvt_pk_bf16_f32 v176, v176, v176
	v_cvt_pk_bf16_f32 v177, v177, v177
	v_cvt_pk_bf16_f32 v178, v178, v178
	v_cvt_pk_bf16_f32 v179, v179, v179
	v_cvt_pk_bf16_f32 v180, v180, v180
	v_cvt_pk_bf16_f32 v181, v181, v181
	global_store_short v130, v166, s[10:11] offset:0
	global_store_short v130, v167, s[10:11] offset:64
	global_store_short v130, v168, s[10:11] offset:128
	global_store_short v130, v169, s[10:11] offset:192
	global_store_short v130, v170, s[10:11] offset:2048
; DI u16 f2bf(float a) { return (u16)(pack2(a, 0.f) & 0xffffu); }
; DI float bf2f(unsigned v) { return __uint_as_float(v << 16); }
; DI int crow(int reg, int g) { return (reg & 3) + 8 * (reg >> 2) + 4 * g; }
; DI void gemm_out_tile(const P& p, int l, int id, char* smem) {
;     ...
; #pragma unroll
;   for (int rb = 0; rb < 2; ++rb) {
; #pragma unroll
;     for (int reg = 0; reg < 16; ++reg) {
;       const int rl = 64 * wr + 32 * rb + crow(reg, g);
;       const int tok = m0 + rl;
;       float sacc = 0.f;
; #pragma unroll
;       for (int cb = 0; cb < 4; ++cb) {
;         const int col = n0 + 128 * wc + 32 * cb + li;
;         const size_t idx = (size_t)tok * 1024 + col;
;         const float hn = bf2f((unsigned)p.hb[idx]) + acc[rb][cb][reg];
;         p.hb[idx] = f2bf(hn);
;         sacc += hn * hn;
;       }
; #pragma unroll
;       for (int m = 16; m >= 1; m >>= 1) sacc += __shfl_xor(sacc, m);
;       if (li == 0) red[wc * 256 + rl] = sacc;
;     }
;   }
	global_store_short v130, v171, s[10:11] offset:2112
	global_store_short v130, v172, s[10:11] offset:2176
	global_store_short v130, v173, s[10:11] offset:2240
	global_store_short v131, v174, s[10:11] offset:0
	global_store_short v131, v175, s[10:11] offset:64
	global_store_short v131, v176, s[10:11] offset:128
	global_store_short v131, v177, s[10:11] offset:192
	global_store_short v131, v178, s[10:11] offset:2048
	global_store_short v131, v179, s[10:11] offset:2112
	global_store_short v131, v180, s[10:11] offset:2176
	global_store_short v131, v181, s[10:11] offset:2240
	v_add_u32_e32 v130, 0x4000, v130
	v_add_u32_e32 v131, 0x4000, v131
	v_add_f32_dpp v138, v138, v138 quad_perm:[1,0,3,2] row_mask:0xf bank_mask:0xf
	v_add_f32_dpp v139, v139, v139 quad_perm:[1,0,3,2] row_mask:0xf bank_mask:0xf
	v_add_f32_dpp v140, v140, v140 quad_perm:[1,0,3,2] row_mask:0xf bank_mask:0xf
	v_add_f32_dpp v141, v141, v141 quad_perm:[1,0,3,2] row_mask:0xf bank_mask:0xf
	v_add_f32_dpp v138, v138, v138 quad_perm:[2,3,0,1] row_mask:0xf bank_mask:0xf
	v_add_f32_dpp v139, v139, v139 quad_perm:[2,3,0,1] row_mask:0xf bank_mask:0xf
	v_add_f32_dpp v140, v140, v140 quad_perm:[2,3,0,1] row_mask:0xf bank_mask:0xf
	v_add_f32_dpp v141, v141, v141 quad_perm:[2,3,0,1] row_mask:0xf bank_mask:0xf
	v_add_f32_dpp v138, v138, v138 row_half_mirror row_mask:0xf bank_mask:0xf
	v_add_f32_dpp v139, v139, v139 row_half_mirror row_mask:0xf bank_mask:0xf
	v_add_f32_dpp v140, v140, v140 row_half_mirror row_mask:0xf bank_mask:0xf
	v_add_f32_dpp v141, v141, v141 row_half_mirror row_mask:0xf bank_mask:0xf
	v_add_f32_dpp v138, v138, v138 row_mirror row_mask:0xf bank_mask:0xf
	v_add_f32_dpp v139, v139, v139 row_mirror row_mask:0xf bank_mask:0xf
	v_add_f32_dpp v140, v140, v140 row_mirror row_mask:0xf bank_mask:0xf
	v_add_f32_dpp v141, v141, v141 row_mirror row_mask:0xf bank_mask:0xf
	v_add_f32_dpp v138, v138, v138 row_bcast:15 row_mask:0xa bank_mask:0xf
	v_add_f32_dpp v139, v139, v139 row_bcast:15 row_mask:0xa bank_mask:0xf
	v_add_f32_dpp v140, v140, v140 row_bcast:15 row_mask:0xa bank_mask:0xf
	v_add_f32_dpp v141, v141, v141 row_bcast:15 row_mask:0xa bank_mask:0xf
	s_mov_b32 exec_lo, 0x10000
	s_mov_b32 exec_hi, 0x10000
	ds_write_b32 v132, v138 offset:32
	ds_write_b32 v132, v139 offset:36
	ds_write_b32 v132, v140 offset:40
	ds_write_b32 v132, v141 offset:44
	s_mov_b64 exec, -1
	global_load_ushort v166, v128, s[10:11] offset:0
	global_load_ushort v167, v128, s[10:11] offset:64
	global_load_ushort v168, v128, s[10:11] offset:128
	global_load_ushort v169, v128, s[10:11] offset:192
	global_load_ushort v170, v128, s[10:11] offset:2048
	global_load_ushort v171, v128, s[10:11] offset:2112
	global_load_ushort v172, v128, s[10:11] offset:2176
	global_load_ushort v173, v128, s[10:11] offset:2240
	global_load_ushort v174, v129, s[10:11] offset:0
	global_load_ushort v175, v129, s[10:11] offset:64
	global_load_ushort v176, v129, s[10:11] offset:128
	global_load_ushort v177, v129, s[10:11] offset:192
	global_load_ushort v178, v129, s[10:11] offset:2048
	global_load_ushort v179, v129, s[10:11] offset:2112
	global_load_ushort v180, v129, s[10:11] offset:2176
	global_load_ushort v181, v129, s[10:11] offset:2240
	v_add_u32_e32 v128, 0x4000, v128
	v_add_u32_e32 v129, 0x4000, v129
	s_waitcnt vmcnt(32)
	v_lshlrev_b32_e32 v150, 16, v150
	v_lshlrev_b32_e32 v151, 16, v151
	v_lshlrev_b32_e32 v152, 16, v152
	v_lshlrev_b32_e32 v153, 16, v153
	v_lshlrev_b32_e32 v154, 16, v154
	v_lshlrev_b32_e32 v155, 16, v155
	v_lshlrev_b32_e32 v156, 16, v156
	v_lshlrev_b32_e32 v157, 16, v157
	v_lshlrev_b32_e32 v158, 16, v158
	v_lshlrev_b32_e32 v159, 16, v159
	v_lshlrev_b32_e32 v160, 16, v160
	v_lshlrev_b32_e32 v161, 16, v161
	v_lshlrev_b32_e32 v162, 16, v162
	v_lshlrev_b32_e32 v163, 16, v163
	v_lshlrev_b32_e32 v164, 16, v164
	v_lshlrev_b32_e32 v165, 16, v165
	v_add_f32_e32 v150, v72, v150
	v_add_f32_e32 v151, v104, v151
	v_add_f32_e32 v152, v120, v152
	v_add_f32_e32 v153, v88, v153
	v_add_f32_e32 v154, v73, v154
	v_add_f32_e32 v155, v105, v155
	v_add_f32_e32 v156, v121, v156
	v_add_f32_e32 v157, v89, v157
	v_add_f32_e32 v158, v74, v158
	v_add_f32_e32 v159, v106, v159
	v_add_f32_e32 v160, v122, v160
	v_add_f32_e32 v161, v90, v161
	v_add_f32_e32 v162, v75, v162
	v_add_f32_e32 v163, v107, v163
	v_add_f32_e32 v164, v123, v164
	v_add_f32_e32 v165, v91, v165
	v_mul_f32_e32 v138, v150, v150
	v_mul_f32_e32 v139, v154, v154
	v_mul_f32_e32 v140, v158, v158
	v_mul_f32_e32 v141, v162, v162
	v_fmac_f32_e32 v138, v151, v151
	v_fmac_f32_e32 v139, v155, v155
	v_fmac_f32_e32 v140, v159, v159
	v_fmac_f32_e32 v141, v163, v163
	v_fmac_f32_e32 v138, v152, v152
	v_fmac_f32_e32 v139, v156, v156
	v_fmac_f32_e32 v140, v160, v160
	v_fmac_f32_e32 v141, v164, v164
	v_fmac_f32_e32 v138, v153, v153
	v_fmac_f32_e32 v139, v157, v157
	v_fmac_f32_e32 v140, v161, v161
	v_fmac_f32_e32 v141, v165, v165
	v_cvt_pk_bf16_f32 v150, v150, v150
	v_cvt_pk_bf16_f32 v151, v151, v151
	v_cvt_pk_bf16_f32 v152, v152, v152
	v_cvt_pk_bf16_f32 v153, v153, v153
	v_cvt_pk_bf16_f32 v154, v154, v154
	v_cvt_pk_bf16_f32 v155, v155, v155
	v_cvt_pk_bf16_f32 v156, v156, v156
	v_cvt_pk_bf16_f32 v157, v157, v157
	v_cvt_pk_bf16_f32 v158, v158, v158
	v_cvt_pk_bf16_f32 v159, v159, v159
	v_cvt_pk_bf16_f32 v160, v160, v160
	v_cvt_pk_bf16_f32 v161, v161, v161
	v_cvt_pk_bf16_f32 v162, v162, v162
	v_cvt_pk_bf16_f32 v163, v163, v163
	v_cvt_pk_bf16_f32 v164, v164, v164
	v_cvt_pk_bf16_f32 v165, v165, v165
	global_store_short v130, v150, s[10:11] offset:0
	global_store_short v130, v151, s[10:11] offset:64
	global_store_short v130, v152, s[10:11] offset:128
	global_store_short v130, v153, s[10:11] offset:192
; DI u16 f2bf(float a) { return (u16)(pack2(a, 0.f) & 0xffffu); }
; DI float bf2f(unsigned v) { return __uint_as_float(v << 16); }
; DI int crow(int reg, int g) { return (reg & 3) + 8 * (reg >> 2) + 4 * g; }
; DI void gemm_out_tile(const P& p, int l, int id, char* smem) {
;     ...
; #pragma unroll
;   for (int rb = 0; rb < 2; ++rb) {
; #pragma unroll
;     for (int reg = 0; reg < 16; ++reg) {
;       const int rl = 64 * wr + 32 * rb + crow(reg, g);
;       const int tok = m0 + rl;
;       float sacc = 0.f;
; #pragma unroll
;       for (int cb = 0; cb < 4; ++cb) {
;         const int col = n0 + 128 * wc + 32 * cb + li;
;         const size_t idx = (size_t)tok * 1024 + col;
;         const float hn = bf2f((unsigned)p.hb[idx]) + acc[rb][cb][reg];
;         p.hb[idx] = f2bf(hn);
;         sacc += hn * hn;
;       }
; #pragma unroll
;       for (int m = 16; m >= 1; m >>= 1) sacc += __shfl_xor(sacc, m);
;       if (li == 0) red[wc * 256 + rl] = sacc;
;     }
;   }
	global_store_short v130, v154, s[10:11] offset:2048
	global_store_short v130, v155, s[10:11] offset:2112
	global_store_short v130, v156, s[10:11] offset:2176
	global_store_short v130, v157, s[10:11] offset:2240
	global_store_short v131, v158, s[10:11] offset:0
	global_store_short v131, v159, s[10:11] offset:64
	global_store_short v131, v160, s[10:11] offset:128
	global_store_short v131, v161, s[10:11] offset:192
	global_store_short v131, v162, s[10:11] offset:2048
	global_store_short v131, v163, s[10:11] offset:2112
	global_store_short v131, v164, s[10:11] offset:2176
	global_store_short v131, v165, s[10:11] offset:2240
	v_add_u32_e32 v130, 0x4000, v130
	v_add_u32_e32 v131, 0x4000, v131
	v_add_f32_dpp v138, v138, v138 quad_perm:[1,0,3,2] row_mask:0xf bank_mask:0xf
	v_add_f32_dpp v139, v139, v139 quad_perm:[1,0,3,2] row_mask:0xf bank_mask:0xf
	v_add_f32_dpp v140, v140, v140 quad_perm:[1,0,3,2] row_mask:0xf bank_mask:0xf
	v_add_f32_dpp v141, v141, v141 quad_perm:[1,0,3,2] row_mask:0xf bank_mask:0xf
	v_add_f32_dpp v138, v138, v138 quad_perm:[2,3,0,1] row_mask:0xf bank_mask:0xf
	v_add_f32_dpp v139, v139, v139 quad_perm:[2,3,0,1] row_mask:0xf bank_mask:0xf
	v_add_f32_dpp v140, v140, v140 quad_perm:[2,3,0,1] row_mask:0xf bank_mask:0xf
	v_add_f32_dpp v141, v141, v141 quad_perm:[2,3,0,1] row_mask:0xf bank_mask:0xf
	v_add_f32_dpp v138, v138, v138 row_half_mirror row_mask:0xf bank_mask:0xf
	v_add_f32_dpp v139, v139, v139 row_half_mirror row_mask:0xf bank_mask:0xf
	v_add_f32_dpp v140, v140, v140 row_half_mirror row_mask:0xf bank_mask:0xf
	v_add_f32_dpp v141, v141, v141 row_half_mirror row_mask:0xf bank_mask:0xf
	v_add_f32_dpp v138, v138, v138 row_mirror row_mask:0xf bank_mask:0xf
	v_add_f32_dpp v139, v139, v139 row_mirror row_mask:0xf bank_mask:0xf
	v_add_f32_dpp v140, v140, v140 row_mirror row_mask:0xf bank_mask:0xf
	v_add_f32_dpp v141, v141, v141 row_mirror row_mask:0xf bank_mask:0xf
	v_add_f32_dpp v138, v138, v138 row_bcast:15 row_mask:0xa bank_mask:0xf
	v_add_f32_dpp v139, v139, v139 row_bcast:15 row_mask:0xa bank_mask:0xf
	v_add_f32_dpp v140, v140, v140 row_bcast:15 row_mask:0xa bank_mask:0xf
	v_add_f32_dpp v141, v141, v141 row_bcast:15 row_mask:0xa bank_mask:0xf
	s_mov_b32 exec_lo, 0x10000
	s_mov_b32 exec_hi, 0x10000
	ds_write_b32 v132, v138 offset:64
	ds_write_b32 v132, v139 offset:68
	ds_write_b32 v132, v140 offset:72
	ds_write_b32 v132, v141 offset:76
	s_mov_b64 exec, -1
	global_load_ushort v150, v128, s[10:11] offset:0
	global_load_ushort v151, v128, s[10:11] offset:64
	global_load_ushort v152, v128, s[10:11] offset:128
	global_load_ushort v153, v128, s[10:11] offset:192
	global_load_ushort v154, v128, s[10:11] offset:2048
	global_load_ushort v155, v128, s[10:11] offset:2112
	global_load_ushort v156, v128, s[10:11] offset:2176
	global_load_ushort v157, v128, s[10:11] offset:2240
	global_load_ushort v158, v129, s[10:11] offset:0
	global_load_ushort v159, v129, s[10:11] offset:64
	global_load_ushort v160, v129, s[10:11] offset:128
	global_load_ushort v161, v129, s[10:11] offset:192
	global_load_ushort v162, v129, s[10:11] offset:2048
	global_load_ushort v163, v129, s[10:11] offset:2112
	global_load_ushort v164, v129, s[10:11] offset:2176
	global_load_ushort v165, v129, s[10:11] offset:2240
	v_add_u32_e32 v128, 0x4000, v128
	v_add_u32_e32 v129, 0x4000, v129
	s_waitcnt vmcnt(32)
	v_lshlrev_b32_e32 v166, 16, v166
	v_lshlrev_b32_e32 v167, 16, v167
	v_lshlrev_b32_e32 v168, 16, v168
	v_lshlrev_b32_e32 v169, 16, v169
	v_lshlrev_b32_e32 v170, 16, v170
	v_lshlrev_b32_e32 v171, 16, v171
	v_lshlrev_b32_e32 v172, 16, v172
	v_lshlrev_b32_e32 v173, 16, v173
	v_lshlrev_b32_e32 v174, 16, v174
	v_lshlrev_b32_e32 v175, 16, v175
	v_lshlrev_b32_e32 v176, 16, v176
	v_lshlrev_b32_e32 v177, 16, v177
	v_lshlrev_b32_e32 v178, 16, v178
	v_lshlrev_b32_e32 v179, 16, v179
	v_lshlrev_b32_e32 v180, 16, v180
	v_lshlrev_b32_e32 v181, 16, v181
	v_add_f32_e32 v166, v76, v166
	v_add_f32_e32 v167, v108, v167
	v_add_f32_e32 v168, v124, v168
	v_add_f32_e32 v169, v92, v169
	v_add_f32_e32 v170, v77, v170
	v_add_f32_e32 v171, v109, v171
	v_add_f32_e32 v172, v125, v172
	v_add_f32_e32 v173, v93, v173
	v_add_f32_e32 v174, v78, v174
	v_add_f32_e32 v175, v110, v175
	v_add_f32_e32 v176, v126, v176
	v_add_f32_e32 v177, v94, v177
	v_add_f32_e32 v178, v79, v178
	v_add_f32_e32 v179, v111, v179
	v_add_f32_e32 v180, v127, v180
	v_add_f32_e32 v181, v95, v181
	v_mul_f32_e32 v138, v166, v166
	v_mul_f32_e32 v139, v170, v170
	v_mul_f32_e32 v140, v174, v174
	v_mul_f32_e32 v141, v178, v178
	v_fmac_f32_e32 v138, v167, v167
	v_fmac_f32_e32 v139, v171, v171
	v_fmac_f32_e32 v140, v175, v175
	v_fmac_f32_e32 v141, v179, v179
	v_fmac_f32_e32 v138, v168, v168
	v_fmac_f32_e32 v139, v172, v172
	v_fmac_f32_e32 v140, v176, v176
	v_fmac_f32_e32 v141, v180, v180
	v_fmac_f32_e32 v138, v169, v169
	v_fmac_f32_e32 v139, v173, v173
	v_fmac_f32_e32 v140, v177, v177
	v_fmac_f32_e32 v141, v181, v181
	v_cvt_pk_bf16_f32 v166, v166, v166
	v_cvt_pk_bf16_f32 v167, v167, v167
	v_cvt_pk_bf16_f32 v168, v168, v168
	v_cvt_pk_bf16_f32 v169, v169, v169
	v_cvt_pk_bf16_f32 v170, v170, v170
	v_cvt_pk_bf16_f32 v171, v171, v171
	v_cvt_pk_bf16_f32 v172, v172, v172
	v_cvt_pk_bf16_f32 v173, v173, v173
	v_cvt_pk_bf16_f32 v174, v174, v174
	v_cvt_pk_bf16_f32 v175, v175, v175
	v_cvt_pk_bf16_f32 v176, v176, v176
	v_cvt_pk_bf16_f32 v177, v177, v177
	v_cvt_pk_bf16_f32 v178, v178, v178
	v_cvt_pk_bf16_f32 v179, v179, v179
	v_cvt_pk_bf16_f32 v180, v180, v180
	v_cvt_pk_bf16_f32 v181, v181, v181
	global_store_short v130, v166, s[10:11] offset:0
	global_store_short v130, v167, s[10:11] offset:64
	global_store_short v130, v168, s[10:11] offset:128
; DI u16 f2bf(float a) { return (u16)(pack2(a, 0.f) & 0xffffu); }
; DI float bf2f(unsigned v) { return __uint_as_float(v << 16); }
; DI int crow(int reg, int g) { return (reg & 3) + 8 * (reg >> 2) + 4 * g; }
; DI void gemm_out_tile(const P& p, int l, int id, char* smem) {
;     ...
; #pragma unroll
;   for (int rb = 0; rb < 2; ++rb) {
; #pragma unroll
;     for (int reg = 0; reg < 16; ++reg) {
;       const int rl = 64 * wr + 32 * rb + crow(reg, g);
;       const int tok = m0 + rl;
;       float sacc = 0.f;
; #pragma unroll
;       for (int cb = 0; cb < 4; ++cb) {
;         const int col = n0 + 128 * wc + 32 * cb + li;
;         const size_t idx = (size_t)tok * 1024 + col;
;         const float hn = bf2f((unsigned)p.hb[idx]) + acc[rb][cb][reg];
;         p.hb[idx] = f2bf(hn);
;         sacc += hn * hn;
;       }
; #pragma unroll
;       for (int m = 16; m >= 1; m >>= 1) sacc += __shfl_xor(sacc, m);
;       if (li == 0) red[wc * 256 + rl] = sacc;
;     }
;   }
	global_store_short v130, v169, s[10:11] offset:192
	global_store_short v130, v170, s[10:11] offset:2048
	global_store_short v130, v171, s[10:11] offset:2112
	global_store_short v130, v172, s[10:11] offset:2176
	global_store_short v130, v173, s[10:11] offset:2240
	global_store_short v131, v174, s[10:11] offset:0
	global_store_short v131, v175, s[10:11] offset:64
	global_store_short v131, v176, s[10:11] offset:128
	global_store_short v131, v177, s[10:11] offset:192
	global_store_short v131, v178, s[10:11] offset:2048
	global_store_short v131, v179, s[10:11] offset:2112
	global_store_short v131, v180, s[10:11] offset:2176
	global_store_short v131, v181, s[10:11] offset:2240
	v_add_u32_e32 v130, 0x4000, v130
	v_add_u32_e32 v131, 0x4000, v131
	v_add_f32_dpp v138, v138, v138 quad_perm:[1,0,3,2] row_mask:0xf bank_mask:0xf
	v_add_f32_dpp v139, v139, v139 quad_perm:[1,0,3,2] row_mask:0xf bank_mask:0xf
	v_add_f32_dpp v140, v140, v140 quad_perm:[1,0,3,2] row_mask:0xf bank_mask:0xf
	v_add_f32_dpp v141, v141, v141 quad_perm:[1,0,3,2] row_mask:0xf bank_mask:0xf
	v_add_f32_dpp v138, v138, v138 quad_perm:[2,3,0,1] row_mask:0xf bank_mask:0xf
	v_add_f32_dpp v139, v139, v139 quad_perm:[2,3,0,1] row_mask:0xf bank_mask:0xf
	v_add_f32_dpp v140, v140, v140 quad_perm:[2,3,0,1] row_mask:0xf bank_mask:0xf
	v_add_f32_dpp v141, v141, v141 quad_perm:[2,3,0,1] row_mask:0xf bank_mask:0xf
	v_add_f32_dpp v138, v138, v138 row_half_mirror row_mask:0xf bank_mask:0xf
	v_add_f32_dpp v139, v139, v139 row_half_mirror row_mask:0xf bank_mask:0xf
	v_add_f32_dpp v140, v140, v140 row_half_mirror row_mask:0xf bank_mask:0xf
	v_add_f32_dpp v141, v141, v141 row_half_mirror row_mask:0xf bank_mask:0xf
	v_add_f32_dpp v138, v138, v138 row_mirror row_mask:0xf bank_mask:0xf
	v_add_f32_dpp v139, v139, v139 row_mirror row_mask:0xf bank_mask:0xf
	v_add_f32_dpp v140, v140, v140 row_mirror row_mask:0xf bank_mask:0xf
	v_add_f32_dpp v141, v141, v141 row_mirror row_mask:0xf bank_mask:0xf
	v_add_f32_dpp v138, v138, v138 row_bcast:15 row_mask:0xa bank_mask:0xf
	v_add_f32_dpp v139, v139, v139 row_bcast:15 row_mask:0xa bank_mask:0xf
	v_add_f32_dpp v140, v140, v140 row_bcast:15 row_mask:0xa bank_mask:0xf
	v_add_f32_dpp v141, v141, v141 row_bcast:15 row_mask:0xa bank_mask:0xf
	s_mov_b32 exec_lo, 0x10000
	s_mov_b32 exec_hi, 0x10000
	ds_write_b32 v132, v138 offset:96
	ds_write_b32 v132, v139 offset:100
	ds_write_b32 v132, v140 offset:104
	ds_write_b32 v132, v141 offset:108
	s_mov_b64 exec, -1
	global_load_ushort v166, v128, s[10:11] offset:0
	global_load_ushort v167, v128, s[10:11] offset:64
	global_load_ushort v168, v128, s[10:11] offset:128
	global_load_ushort v169, v128, s[10:11] offset:192
	global_load_ushort v170, v128, s[10:11] offset:2048
	global_load_ushort v171, v128, s[10:11] offset:2112
	global_load_ushort v172, v128, s[10:11] offset:2176
	global_load_ushort v173, v128, s[10:11] offset:2240
	global_load_ushort v174, v129, s[10:11] offset:0
	global_load_ushort v175, v129, s[10:11] offset:64
	global_load_ushort v176, v129, s[10:11] offset:128
	global_load_ushort v177, v129, s[10:11] offset:192
	global_load_ushort v178, v129, s[10:11] offset:2048
	global_load_ushort v179, v129, s[10:11] offset:2112
	global_load_ushort v180, v129, s[10:11] offset:2176
	global_load_ushort v181, v129, s[10:11] offset:2240
	v_add_u32_e32 v128, 0x4000, v128
	v_add_u32_e32 v129, 0x4000, v129
	s_waitcnt vmcnt(32)
	v_lshlrev_b32_e32 v150, 16, v150
	v_lshlrev_b32_e32 v151, 16, v151
	v_lshlrev_b32_e32 v152, 16, v152
	v_lshlrev_b32_e32 v153, 16, v153
	v_lshlrev_b32_e32 v154, 16, v154
	v_lshlrev_b32_e32 v155, 16, v155
	v_lshlrev_b32_e32 v156, 16, v156
	v_lshlrev_b32_e32 v157, 16, v157
	v_lshlrev_b32_e32 v158, 16, v158
	v_lshlrev_b32_e32 v159, 16, v159
	v_lshlrev_b32_e32 v160, 16, v160
	v_lshlrev_b32_e32 v161, 16, v161
	v_lshlrev_b32_e32 v162, 16, v162
	v_lshlrev_b32_e32 v163, 16, v163
	v_lshlrev_b32_e32 v164, 16, v164
	v_lshlrev_b32_e32 v165, 16, v165
	v_add_f32_e32 v150, v0, v150
	v_add_f32_e32 v151, v32, v151
	v_add_f32_e32 v152, v48, v152
	v_add_f32_e32 v153, v16, v153
	v_add_f32_e32 v154, v1, v154
	v_add_f32_e32 v155, v33, v155
	v_add_f32_e32 v156, v49, v156
	v_add_f32_e32 v157, v17, v157
	v_add_f32_e32 v158, v2, v158
	v_add_f32_e32 v159, v34, v159
	v_add_f32_e32 v160, v50, v160
	v_add_f32_e32 v161, v18, v161
	v_add_f32_e32 v162, v3, v162
	v_add_f32_e32 v163, v35, v163
	v_add_f32_e32 v164, v51, v164
	v_add_f32_e32 v165, v19, v165
	v_mul_f32_e32 v138, v150, v150
	v_mul_f32_e32 v139, v154, v154
	v_mul_f32_e32 v140, v158, v158
	v_mul_f32_e32 v141, v162, v162
	v_fmac_f32_e32 v138, v151, v151
	v_fmac_f32_e32 v139, v155, v155
	v_fmac_f32_e32 v140, v159, v159
	v_fmac_f32_e32 v141, v163, v163
	v_fmac_f32_e32 v138, v152, v152
	v_fmac_f32_e32 v139, v156, v156
	v_fmac_f32_e32 v140, v160, v160
	v_fmac_f32_e32 v141, v164, v164
	v_fmac_f32_e32 v138, v153, v153
	v_fmac_f32_e32 v139, v157, v157
	v_fmac_f32_e32 v140, v161, v161
	v_fmac_f32_e32 v141, v165, v165
	v_cvt_pk_bf16_f32 v150, v150, v150
	v_cvt_pk_bf16_f32 v151, v151, v151
	v_cvt_pk_bf16_f32 v152, v152, v152
	v_cvt_pk_bf16_f32 v153, v153, v153
	v_cvt_pk_bf16_f32 v154, v154, v154
	v_cvt_pk_bf16_f32 v155, v155, v155
	v_cvt_pk_bf16_f32 v156, v156, v156
	v_cvt_pk_bf16_f32 v157, v157, v157
	v_cvt_pk_bf16_f32 v158, v158, v158
	v_cvt_pk_bf16_f32 v159, v159, v159
	v_cvt_pk_bf16_f32 v160, v160, v160
	v_cvt_pk_bf16_f32 v161, v161, v161
	v_cvt_pk_bf16_f32 v162, v162, v162
	v_cvt_pk_bf16_f32 v163, v163, v163
	v_cvt_pk_bf16_f32 v164, v164, v164
	v_cvt_pk_bf16_f32 v165, v165, v165
	global_store_short v130, v150, s[10:11] offset:0
	global_store_short v130, v151, s[10:11] offset:64
; DI u16 f2bf(float a) { return (u16)(pack2(a, 0.f) & 0xffffu); }
; DI float bf2f(unsigned v) { return __uint_as_float(v << 16); }
; DI int crow(int reg, int g) { return (reg & 3) + 8 * (reg >> 2) + 4 * g; }
; DI void gemm_out_tile(const P& p, int l, int id, char* smem) {
;     ...
; #pragma unroll
;   for (int rb = 0; rb < 2; ++rb) {
; #pragma unroll
;     for (int reg = 0; reg < 16; ++reg) {
;       const int rl = 64 * wr + 32 * rb + crow(reg, g);
;       const int tok = m0 + rl;
;       float sacc = 0.f;
; #pragma unroll
;       for (int cb = 0; cb < 4; ++cb) {
;         const int col = n0 + 128 * wc + 32 * cb + li;
;         const size_t idx = (size_t)tok * 1024 + col;
;         const float hn = bf2f((unsigned)p.hb[idx]) + acc[rb][cb][reg];
;         p.hb[idx] = f2bf(hn);
;         sacc += hn * hn;
;       }
; #pragma unroll
;       for (int m = 16; m >= 1; m >>= 1) sacc += __shfl_xor(sacc, m);
;       if (li == 0) red[wc * 256 + rl] = sacc;
;     }
;   }
	global_store_short v130, v152, s[10:11] offset:128
	global_store_short v130, v153, s[10:11] offset:192
	global_store_short v130, v154, s[10:11] offset:2048
	global_store_short v130, v155, s[10:11] offset:2112
	global_store_short v130, v156, s[10:11] offset:2176
	global_store_short v130, v157, s[10:11] offset:2240
	global_store_short v131, v158, s[10:11] offset:0
	global_store_short v131, v159, s[10:11] offset:64
	global_store_short v131, v160, s[10:11] offset:128
	global_store_short v131, v161, s[10:11] offset:192
	global_store_short v131, v162, s[10:11] offset:2048
	global_store_short v131, v163, s[10:11] offset:2112
	global_store_short v131, v164, s[10:11] offset:2176
	global_store_short v131, v165, s[10:11] offset:2240
	v_add_u32_e32 v130, 0x4000, v130
	v_add_u32_e32 v131, 0x4000, v131
	v_add_f32_dpp v138, v138, v138 quad_perm:[1,0,3,2] row_mask:0xf bank_mask:0xf
	v_add_f32_dpp v139, v139, v139 quad_perm:[1,0,3,2] row_mask:0xf bank_mask:0xf
	v_add_f32_dpp v140, v140, v140 quad_perm:[1,0,3,2] row_mask:0xf bank_mask:0xf
	v_add_f32_dpp v141, v141, v141 quad_perm:[1,0,3,2] row_mask:0xf bank_mask:0xf
	v_add_f32_dpp v138, v138, v138 quad_perm:[2,3,0,1] row_mask:0xf bank_mask:0xf
	v_add_f32_dpp v139, v139, v139 quad_perm:[2,3,0,1] row_mask:0xf bank_mask:0xf
	v_add_f32_dpp v140, v140, v140 quad_perm:[2,3,0,1] row_mask:0xf bank_mask:0xf
	v_add_f32_dpp v141, v141, v141 quad_perm:[2,3,0,1] row_mask:0xf bank_mask:0xf
	v_add_f32_dpp v138, v138, v138 row_half_mirror row_mask:0xf bank_mask:0xf
	v_add_f32_dpp v139, v139, v139 row_half_mirror row_mask:0xf bank_mask:0xf
	v_add_f32_dpp v140, v140, v140 row_half_mirror row_mask:0xf bank_mask:0xf
	v_add_f32_dpp v141, v141, v141 row_half_mirror row_mask:0xf bank_mask:0xf
	v_add_f32_dpp v138, v138, v138 row_mirror row_mask:0xf bank_mask:0xf
	v_add_f32_dpp v139, v139, v139 row_mirror row_mask:0xf bank_mask:0xf
	v_add_f32_dpp v140, v140, v140 row_mirror row_mask:0xf bank_mask:0xf
	v_add_f32_dpp v141, v141, v141 row_mirror row_mask:0xf bank_mask:0xf
	v_add_f32_dpp v138, v138, v138 row_bcast:15 row_mask:0xa bank_mask:0xf
	v_add_f32_dpp v139, v139, v139 row_bcast:15 row_mask:0xa bank_mask:0xf
	v_add_f32_dpp v140, v140, v140 row_bcast:15 row_mask:0xa bank_mask:0xf
	v_add_f32_dpp v141, v141, v141 row_bcast:15 row_mask:0xa bank_mask:0xf
	s_mov_b32 exec_lo, 0x10000
	s_mov_b32 exec_hi, 0x10000
	ds_write_b32 v132, v138 offset:128
	ds_write_b32 v132, v139 offset:132
	ds_write_b32 v132, v140 offset:136
	ds_write_b32 v132, v141 offset:140
	s_mov_b64 exec, -1
	global_load_ushort v150, v128, s[10:11] offset:0
	global_load_ushort v151, v128, s[10:11] offset:64
	global_load_ushort v152, v128, s[10:11] offset:128
	global_load_ushort v153, v128, s[10:11] offset:192
	global_load_ushort v154, v128, s[10:11] offset:2048
	global_load_ushort v155, v128, s[10:11] offset:2112
	global_load_ushort v156, v128, s[10:11] offset:2176
	global_load_ushort v157, v128, s[10:11] offset:2240
	global_load_ushort v158, v129, s[10:11] offset:0
	global_load_ushort v159, v129, s[10:11] offset:64
	global_load_ushort v160, v129, s[10:11] offset:128
	global_load_ushort v161, v129, s[10:11] offset:192
	global_load_ushort v162, v129, s[10:11] offset:2048
	global_load_ushort v163, v129, s[10:11] offset:2112
	global_load_ushort v164, v129, s[10:11] offset:2176
	global_load_ushort v165, v129, s[10:11] offset:2240
	v_add_u32_e32 v128, 0x4000, v128
	v_add_u32_e32 v129, 0x4000, v129
	s_waitcnt vmcnt(32)
	v_lshlrev_b32_e32 v166, 16, v166
	v_lshlrev_b32_e32 v167, 16, v167
	v_lshlrev_b32_e32 v168, 16, v168
	v_lshlrev_b32_e32 v169, 16, v169
	v_lshlrev_b32_e32 v170, 16, v170
	v_lshlrev_b32_e32 v171, 16, v171
	v_lshlrev_b32_e32 v172, 16, v172
	v_lshlrev_b32_e32 v173, 16, v173
	v_lshlrev_b32_e32 v174, 16, v174
	v_lshlrev_b32_e32 v175, 16, v175
	v_lshlrev_b32_e32 v176, 16, v176
	v_lshlrev_b32_e32 v177, 16, v177
	v_lshlrev_b32_e32 v178, 16, v178
	v_lshlrev_b32_e32 v179, 16, v179
	v_lshlrev_b32_e32 v180, 16, v180
	v_lshlrev_b32_e32 v181, 16, v181
	v_add_f32_e32 v166, v4, v166
	v_add_f32_e32 v167, v36, v167
	v_add_f32_e32 v168, v52, v168
	v_add_f32_e32 v169, v20, v169
	v_add_f32_e32 v170, v5, v170
	v_add_f32_e32 v171, v37, v171
	v_add_f32_e32 v172, v53, v172
	v_add_f32_e32 v173, v21, v173
	v_add_f32_e32 v174, v6, v174
	v_add_f32_e32 v175, v38, v175
	v_add_f32_e32 v176, v54, v176
	v_add_f32_e32 v177, v22, v177
	v_add_f32_e32 v178, v7, v178
	v_add_f32_e32 v179, v39, v179
	v_add_f32_e32 v180, v55, v180
	v_add_f32_e32 v181, v23, v181
	v_mul_f32_e32 v138, v166, v166
	v_mul_f32_e32 v139, v170, v170
	v_mul_f32_e32 v140, v174, v174
	v_mul_f32_e32 v141, v178, v178
	v_fmac_f32_e32 v138, v167, v167
	v_fmac_f32_e32 v139, v171, v171
	v_fmac_f32_e32 v140, v175, v175
	v_fmac_f32_e32 v141, v179, v179
	v_fmac_f32_e32 v138, v168, v168
	v_fmac_f32_e32 v139, v172, v172
	v_fmac_f32_e32 v140, v176, v176
	v_fmac_f32_e32 v141, v180, v180
	v_fmac_f32_e32 v138, v169, v169
	v_fmac_f32_e32 v139, v173, v173
	v_fmac_f32_e32 v140, v177, v177
	v_fmac_f32_e32 v141, v181, v181
	v_cvt_pk_bf16_f32 v166, v166, v166
	v_cvt_pk_bf16_f32 v167, v167, v167
	v_cvt_pk_bf16_f32 v168, v168, v168
	v_cvt_pk_bf16_f32 v169, v169, v169
	v_cvt_pk_bf16_f32 v170, v170, v170
	v_cvt_pk_bf16_f32 v171, v171, v171
	v_cvt_pk_bf16_f32 v172, v172, v172
	v_cvt_pk_bf16_f32 v173, v173, v173
	v_cvt_pk_bf16_f32 v174, v174, v174
	v_cvt_pk_bf16_f32 v175, v175, v175
	v_cvt_pk_bf16_f32 v176, v176, v176
	v_cvt_pk_bf16_f32 v177, v177, v177
	v_cvt_pk_bf16_f32 v178, v178, v178
	v_cvt_pk_bf16_f32 v179, v179, v179
	v_cvt_pk_bf16_f32 v180, v180, v180
	v_cvt_pk_bf16_f32 v181, v181, v181
	global_store_short v130, v166, s[10:11] offset:0
; DI u16 f2bf(float a) { return (u16)(pack2(a, 0.f) & 0xffffu); }
; DI float bf2f(unsigned v) { return __uint_as_float(v << 16); }
; DI int crow(int reg, int g) { return (reg & 3) + 8 * (reg >> 2) + 4 * g; }
; DI void gemm_out_tile(const P& p, int l, int id, char* smem) {
;     ...
; #pragma unroll
;   for (int rb = 0; rb < 2; ++rb) {
; #pragma unroll
;     for (int reg = 0; reg < 16; ++reg) {
;       const int rl = 64 * wr + 32 * rb + crow(reg, g);
;       const int tok = m0 + rl;
;       float sacc = 0.f;
; #pragma unroll
;       for (int cb = 0; cb < 4; ++cb) {
;         const int col = n0 + 128 * wc + 32 * cb + li;
;         const size_t idx = (size_t)tok * 1024 + col;
;         const float hn = bf2f((unsigned)p.hb[idx]) + acc[rb][cb][reg];
;         p.hb[idx] = f2bf(hn);
;         sacc += hn * hn;
;       }
; #pragma unroll
;       for (int m = 16; m >= 1; m >>= 1) sacc += __shfl_xor(sacc, m);
;       if (li == 0) red[wc * 256 + rl] = sacc;
;     }
;   }
	global_store_short v130, v167, s[10:11] offset:64
	global_store_short v130, v168, s[10:11] offset:128
	global_store_short v130, v169, s[10:11] offset:192
	global_store_short v130, v170, s[10:11] offset:2048
	global_store_short v130, v171, s[10:11] offset:2112
	global_store_short v130, v172, s[10:11] offset:2176
	global_store_short v130, v173, s[10:11] offset:2240
	global_store_short v131, v174, s[10:11] offset:0
	global_store_short v131, v175, s[10:11] offset:64
	global_store_short v131, v176, s[10:11] offset:128
	global_store_short v131, v177, s[10:11] offset:192
	global_store_short v131, v178, s[10:11] offset:2048
	global_store_short v131, v179, s[10:11] offset:2112
	global_store_short v131, v180, s[10:11] offset:2176
	global_store_short v131, v181, s[10:11] offset:2240
	v_add_u32_e32 v130, 0x4000, v130
	v_add_u32_e32 v131, 0x4000, v131
	v_add_f32_dpp v138, v138, v138 quad_perm:[1,0,3,2] row_mask:0xf bank_mask:0xf
	v_add_f32_dpp v139, v139, v139 quad_perm:[1,0,3,2] row_mask:0xf bank_mask:0xf
	v_add_f32_dpp v140, v140, v140 quad_perm:[1,0,3,2] row_mask:0xf bank_mask:0xf
	v_add_f32_dpp v141, v141, v141 quad_perm:[1,0,3,2] row_mask:0xf bank_mask:0xf
	v_add_f32_dpp v138, v138, v138 quad_perm:[2,3,0,1] row_mask:0xf bank_mask:0xf
	v_add_f32_dpp v139, v139, v139 quad_perm:[2,3,0,1] row_mask:0xf bank_mask:0xf
	v_add_f32_dpp v140, v140, v140 quad_perm:[2,3,0,1] row_mask:0xf bank_mask:0xf
	v_add_f32_dpp v141, v141, v141 quad_perm:[2,3,0,1] row_mask:0xf bank_mask:0xf
	v_add_f32_dpp v138, v138, v138 row_half_mirror row_mask:0xf bank_mask:0xf
	v_add_f32_dpp v139, v139, v139 row_half_mirror row_mask:0xf bank_mask:0xf
	v_add_f32_dpp v140, v140, v140 row_half_mirror row_mask:0xf bank_mask:0xf
	v_add_f32_dpp v141, v141, v141 row_half_mirror row_mask:0xf bank_mask:0xf
	v_add_f32_dpp v138, v138, v138 row_mirror row_mask:0xf bank_mask:0xf
	v_add_f32_dpp v139, v139, v139 row_mirror row_mask:0xf bank_mask:0xf
	v_add_f32_dpp v140, v140, v140 row_mirror row_mask:0xf bank_mask:0xf
	v_add_f32_dpp v141, v141, v141 row_mirror row_mask:0xf bank_mask:0xf
	v_add_f32_dpp v138, v138, v138 row_bcast:15 row_mask:0xa bank_mask:0xf
	v_add_f32_dpp v139, v139, v139 row_bcast:15 row_mask:0xa bank_mask:0xf
	v_add_f32_dpp v140, v140, v140 row_bcast:15 row_mask:0xa bank_mask:0xf
	v_add_f32_dpp v141, v141, v141 row_bcast:15 row_mask:0xa bank_mask:0xf
	s_mov_b32 exec_lo, 0x10000
	s_mov_b32 exec_hi, 0x10000
	ds_write_b32 v132, v138 offset:160
	ds_write_b32 v132, v139 offset:164
	ds_write_b32 v132, v140 offset:168
	ds_write_b32 v132, v141 offset:172
	s_mov_b64 exec, -1
	global_load_ushort v166, v128, s[10:11] offset:0
	global_load_ushort v167, v128, s[10:11] offset:64
	global_load_ushort v168, v128, s[10:11] offset:128
	global_load_ushort v169, v128, s[10:11] offset:192
	global_load_ushort v170, v128, s[10:11] offset:2048
	global_load_ushort v171, v128, s[10:11] offset:2112
	global_load_ushort v172, v128, s[10:11] offset:2176
	global_load_ushort v173, v128, s[10:11] offset:2240
	global_load_ushort v174, v129, s[10:11] offset:0
	global_load_ushort v175, v129, s[10:11] offset:64
	global_load_ushort v176, v129, s[10:11] offset:128
	global_load_ushort v177, v129, s[10:11] offset:192
	global_load_ushort v178, v129, s[10:11] offset:2048
	global_load_ushort v179, v129, s[10:11] offset:2112
	global_load_ushort v180, v129, s[10:11] offset:2176
	global_load_ushort v181, v129, s[10:11] offset:2240
	v_add_u32_e32 v128, 0x4000, v128
	v_add_u32_e32 v129, 0x4000, v129
	s_waitcnt vmcnt(32)
	v_lshlrev_b32_e32 v150, 16, v150
	v_lshlrev_b32_e32 v151, 16, v151
	v_lshlrev_b32_e32 v152, 16, v152
	v_lshlrev_b32_e32 v153, 16, v153
	v_lshlrev_b32_e32 v154, 16, v154
	v_lshlrev_b32_e32 v155, 16, v155
	v_lshlrev_b32_e32 v156, 16, v156
	v_lshlrev_b32_e32 v157, 16, v157
	v_lshlrev_b32_e32 v158, 16, v158
	v_lshlrev_b32_e32 v159, 16, v159
	v_lshlrev_b32_e32 v160, 16, v160
	v_lshlrev_b32_e32 v161, 16, v161
	v_lshlrev_b32_e32 v162, 16, v162
	v_lshlrev_b32_e32 v163, 16, v163
	v_lshlrev_b32_e32 v164, 16, v164
	v_lshlrev_b32_e32 v165, 16, v165
	v_add_f32_e32 v150, v8, v150
	v_add_f32_e32 v151, v40, v151
	v_add_f32_e32 v152, v56, v152
	v_add_f32_e32 v153, v24, v153
	v_add_f32_e32 v154, v9, v154
	v_add_f32_e32 v155, v41, v155
	v_add_f32_e32 v156, v57, v156
	v_add_f32_e32 v157, v25, v157
	v_add_f32_e32 v158, v10, v158
	v_add_f32_e32 v159, v42, v159
	v_add_f32_e32 v160, v58, v160
	v_add_f32_e32 v161, v26, v161
	v_add_f32_e32 v162, v11, v162
	v_add_f32_e32 v163, v43, v163
	v_add_f32_e32 v164, v59, v164
	v_add_f32_e32 v165, v27, v165
	v_mul_f32_e32 v138, v150, v150
	v_mul_f32_e32 v139, v154, v154
	v_mul_f32_e32 v140, v158, v158
	v_mul_f32_e32 v141, v162, v162
	v_fmac_f32_e32 v138, v151, v151
	v_fmac_f32_e32 v139, v155, v155
	v_fmac_f32_e32 v140, v159, v159
	v_fmac_f32_e32 v141, v163, v163
	v_fmac_f32_e32 v138, v152, v152
	v_fmac_f32_e32 v139, v156, v156
	v_fmac_f32_e32 v140, v160, v160
	v_fmac_f32_e32 v141, v164, v164
	v_fmac_f32_e32 v138, v153, v153
	v_fmac_f32_e32 v139, v157, v157
	v_fmac_f32_e32 v140, v161, v161
	v_fmac_f32_e32 v141, v165, v165
	v_cvt_pk_bf16_f32 v150, v150, v150
	v_cvt_pk_bf16_f32 v151, v151, v151
	v_cvt_pk_bf16_f32 v152, v152, v152
	v_cvt_pk_bf16_f32 v153, v153, v153
	v_cvt_pk_bf16_f32 v154, v154, v154
	v_cvt_pk_bf16_f32 v155, v155, v155
	v_cvt_pk_bf16_f32 v156, v156, v156
	v_cvt_pk_bf16_f32 v157, v157, v157
	v_cvt_pk_bf16_f32 v158, v158, v158
	v_cvt_pk_bf16_f32 v159, v159, v159
	v_cvt_pk_bf16_f32 v160, v160, v160
	v_cvt_pk_bf16_f32 v161, v161, v161
	v_cvt_pk_bf16_f32 v162, v162, v162
	v_cvt_pk_bf16_f32 v163, v163, v163
	v_cvt_pk_bf16_f32 v164, v164, v164
	v_cvt_pk_bf16_f32 v165, v165, v165
; DI u16 f2bf(float a) { return (u16)(pack2(a, 0.f) & 0xffffu); }
; DI float bf2f(unsigned v) { return __uint_as_float(v << 16); }
; DI int crow(int reg, int g) { return (reg & 3) + 8 * (reg >> 2) + 4 * g; }
; DI void gemm_out_tile(const P& p, int l, int id, char* smem) {
;     ...
; #pragma unroll
;   for (int rb = 0; rb < 2; ++rb) {
; #pragma unroll
;     for (int reg = 0; reg < 16; ++reg) {
;       const int rl = 64 * wr + 32 * rb + crow(reg, g);
;       const int tok = m0 + rl;
;       float sacc = 0.f;
; #pragma unroll
;       for (int cb = 0; cb < 4; ++cb) {
;         const int col = n0 + 128 * wc + 32 * cb + li;
;         const size_t idx = (size_t)tok * 1024 + col;
;         const float hn = bf2f((unsigned)p.hb[idx]) + acc[rb][cb][reg];
;         p.hb[idx] = f2bf(hn);
;         sacc += hn * hn;
;       }
; #pragma unroll
;       for (int m = 16; m >= 1; m >>= 1) sacc += __shfl_xor(sacc, m);
;       if (li == 0) red[wc * 256 + rl] = sacc;
;     }
;   }
	global_store_short v130, v150, s[10:11] offset:0
	global_store_short v130, v151, s[10:11] offset:64
	global_store_short v130, v152, s[10:11] offset:128
	global_store_short v130, v153, s[10:11] offset:192
	global_store_short v130, v154, s[10:11] offset:2048
	global_store_short v130, v155, s[10:11] offset:2112
	global_store_short v130, v156, s[10:11] offset:2176
	global_store_short v130, v157, s[10:11] offset:2240
	global_store_short v131, v158, s[10:11] offset:0
	global_store_short v131, v159, s[10:11] offset:64
	global_store_short v131, v160, s[10:11] offset:128
	global_store_short v131, v161, s[10:11] offset:192
	global_store_short v131, v162, s[10:11] offset:2048
	global_store_short v131, v163, s[10:11] offset:2112
	global_store_short v131, v164, s[10:11] offset:2176
	global_store_short v131, v165, s[10:11] offset:2240
	v_add_u32_e32 v130, 0x4000, v130
	v_add_u32_e32 v131, 0x4000, v131
	v_add_f32_dpp v138, v138, v138 quad_perm:[1,0,3,2] row_mask:0xf bank_mask:0xf
	v_add_f32_dpp v139, v139, v139 quad_perm:[1,0,3,2] row_mask:0xf bank_mask:0xf
	v_add_f32_dpp v140, v140, v140 quad_perm:[1,0,3,2] row_mask:0xf bank_mask:0xf
	v_add_f32_dpp v141, v141, v141 quad_perm:[1,0,3,2] row_mask:0xf bank_mask:0xf
	v_add_f32_dpp v138, v138, v138 quad_perm:[2,3,0,1] row_mask:0xf bank_mask:0xf
	v_add_f32_dpp v139, v139, v139 quad_perm:[2,3,0,1] row_mask:0xf bank_mask:0xf
	v_add_f32_dpp v140, v140, v140 quad_perm:[2,3,0,1] row_mask:0xf bank_mask:0xf
	v_add_f32_dpp v141, v141, v141 quad_perm:[2,3,0,1] row_mask:0xf bank_mask:0xf
	v_add_f32_dpp v138, v138, v138 row_half_mirror row_mask:0xf bank_mask:0xf
	v_add_f32_dpp v139, v139, v139 row_half_mirror row_mask:0xf bank_mask:0xf
	v_add_f32_dpp v140, v140, v140 row_half_mirror row_mask:0xf bank_mask:0xf
	v_add_f32_dpp v141, v141, v141 row_half_mirror row_mask:0xf bank_mask:0xf
	v_add_f32_dpp v138, v138, v138 row_mirror row_mask:0xf bank_mask:0xf
	v_add_f32_dpp v139, v139, v139 row_mirror row_mask:0xf bank_mask:0xf
	v_add_f32_dpp v140, v140, v140 row_mirror row_mask:0xf bank_mask:0xf
	v_add_f32_dpp v141, v141, v141 row_mirror row_mask:0xf bank_mask:0xf
	v_add_f32_dpp v138, v138, v138 row_bcast:15 row_mask:0xa bank_mask:0xf
	v_add_f32_dpp v139, v139, v139 row_bcast:15 row_mask:0xa bank_mask:0xf
	v_add_f32_dpp v140, v140, v140 row_bcast:15 row_mask:0xa bank_mask:0xf
	v_add_f32_dpp v141, v141, v141 row_bcast:15 row_mask:0xa bank_mask:0xf
	s_mov_b32 exec_lo, 0x10000
	s_mov_b32 exec_hi, 0x10000
	ds_write_b32 v132, v138 offset:192
	ds_write_b32 v132, v139 offset:196
	ds_write_b32 v132, v140 offset:200
	ds_write_b32 v132, v141 offset:204
	s_mov_b64 exec, -1
	s_waitcnt vmcnt(16)
; DI u16 f2bf(float a) { return (u16)(pack2(a, 0.f) & 0xffffu); }
; DI float bf2f(unsigned v) { return __uint_as_float(v << 16); }
; DI int crow(int reg, int g) { return (reg & 3) + 8 * (reg >> 2) + 4 * g; }
; DI void gemm_out_tile(const P& p, int l, int id, char* smem) {
;     ...
; #pragma unroll
;   for (int rb = 0; rb < 2; ++rb) {
; #pragma unroll
;     for (int reg = 0; reg < 16; ++reg) {
;       const int rl = 64 * wr + 32 * rb + crow(reg, g);
;       const int tok = m0 + rl;
;       float sacc = 0.f;
; #pragma unroll
;       for (int cb = 0; cb < 4; ++cb) {
;         const int col = n0 + 128 * wc + 32 * cb + li;
;         const size_t idx = (size_t)tok * 1024 + col;
;         const float hn = bf2f((unsigned)p.hb[idx]) + acc[rb][cb][reg];
;         p.hb[idx] = f2bf(hn);
;         sacc += hn * hn;
;       }
; #pragma unroll
;       for (int m = 16; m >= 1; m >>= 1) sacc += __shfl_xor(sacc, m);
;       if (li == 0) red[wc * 256 + rl] = sacc;
;     }
;   }
	v_lshlrev_b32_e32 v166, 16, v166
	v_lshlrev_b32_e32 v167, 16, v167
	v_lshlrev_b32_e32 v168, 16, v168
	v_lshlrev_b32_e32 v169, 16, v169
	v_lshlrev_b32_e32 v170, 16, v170
	v_lshlrev_b32_e32 v171, 16, v171
	v_lshlrev_b32_e32 v172, 16, v172
	v_lshlrev_b32_e32 v173, 16, v173
	v_lshlrev_b32_e32 v174, 16, v174
	v_lshlrev_b32_e32 v175, 16, v175
	v_lshlrev_b32_e32 v176, 16, v176
	v_lshlrev_b32_e32 v177, 16, v177
	v_lshlrev_b32_e32 v178, 16, v178
	v_lshlrev_b32_e32 v179, 16, v179
	v_lshlrev_b32_e32 v180, 16, v180
	v_lshlrev_b32_e32 v181, 16, v181
	v_add_f32_e32 v166, v12, v166
	v_add_f32_e32 v167, v44, v167
	v_add_f32_e32 v168, v60, v168
	v_add_f32_e32 v169, v28, v169
	v_add_f32_e32 v170, v13, v170
	v_add_f32_e32 v171, v45, v171
	v_add_f32_e32 v172, v61, v172
	v_add_f32_e32 v173, v29, v173
	v_add_f32_e32 v174, v14, v174
	v_add_f32_e32 v175, v46, v175
	v_add_f32_e32 v176, v62, v176
	v_add_f32_e32 v177, v30, v177
	v_add_f32_e32 v178, v15, v178
	v_add_f32_e32 v179, v47, v179
	v_add_f32_e32 v180, v63, v180
	v_add_f32_e32 v181, v31, v181
	v_mul_f32_e32 v138, v166, v166
	v_mul_f32_e32 v139, v170, v170
	v_mul_f32_e32 v140, v174, v174
	v_mul_f32_e32 v141, v178, v178
	v_fmac_f32_e32 v138, v167, v167
	v_fmac_f32_e32 v139, v171, v171
	v_fmac_f32_e32 v140, v175, v175
	v_fmac_f32_e32 v141, v179, v179
	v_fmac_f32_e32 v138, v168, v168
	v_fmac_f32_e32 v139, v172, v172
	v_fmac_f32_e32 v140, v176, v176
	v_fmac_f32_e32 v141, v180, v180
	v_fmac_f32_e32 v138, v169, v169
	v_fmac_f32_e32 v139, v173, v173
	v_fmac_f32_e32 v140, v177, v177
	v_fmac_f32_e32 v141, v181, v181
	v_cvt_pk_bf16_f32 v166, v166, v166
	v_cvt_pk_bf16_f32 v167, v167, v167
	v_cvt_pk_bf16_f32 v168, v168, v168
	v_cvt_pk_bf16_f32 v169, v169, v169
	v_cvt_pk_bf16_f32 v170, v170, v170
	v_cvt_pk_bf16_f32 v171, v171, v171
	v_cvt_pk_bf16_f32 v172, v172, v172
	v_cvt_pk_bf16_f32 v173, v173, v173
	v_cvt_pk_bf16_f32 v174, v174, v174
	v_cvt_pk_bf16_f32 v175, v175, v175
	v_cvt_pk_bf16_f32 v176, v176, v176
	v_cvt_pk_bf16_f32 v177, v177, v177
	v_cvt_pk_bf16_f32 v178, v178, v178
	v_cvt_pk_bf16_f32 v179, v179, v179
	v_cvt_pk_bf16_f32 v180, v180, v180
	v_cvt_pk_bf16_f32 v181, v181, v181
	global_store_short v130, v166, s[10:11] offset:0
	global_store_short v130, v167, s[10:11] offset:64
	global_store_short v130, v168, s[10:11] offset:128
	global_store_short v130, v169, s[10:11] offset:192
	global_store_short v130, v170, s[10:11] offset:2048
	global_store_short v130, v171, s[10:11] offset:2112
	global_store_short v130, v172, s[10:11] offset:2176
	global_store_short v130, v173, s[10:11] offset:2240
	global_store_short v131, v174, s[10:11] offset:0
	global_store_short v131, v175, s[10:11] offset:64
	global_store_short v131, v176, s[10:11] offset:128
	global_store_short v131, v177, s[10:11] offset:192
	global_store_short v131, v178, s[10:11] offset:2048
	global_store_short v131, v179, s[10:11] offset:2112
	global_store_short v131, v180, s[10:11] offset:2176
	global_store_short v131, v181, s[10:11] offset:2240
	v_add_u32_e32 v130, 0x4000, v130
	v_add_u32_e32 v131, 0x4000, v131
	v_add_f32_dpp v138, v138, v138 quad_perm:[1,0,3,2] row_mask:0xf bank_mask:0xf
	v_add_f32_dpp v139, v139, v139 quad_perm:[1,0,3,2] row_mask:0xf bank_mask:0xf
	v_add_f32_dpp v140, v140, v140 quad_perm:[1,0,3,2] row_mask:0xf bank_mask:0xf
	v_add_f32_dpp v141, v141, v141 quad_perm:[1,0,3,2] row_mask:0xf bank_mask:0xf
	v_add_f32_dpp v138, v138, v138 quad_perm:[2,3,0,1] row_mask:0xf bank_mask:0xf
	v_add_f32_dpp v139, v139, v139 quad_perm:[2,3,0,1] row_mask:0xf bank_mask:0xf
	v_add_f32_dpp v140, v140, v140 quad_perm:[2,3,0,1] row_mask:0xf bank_mask:0xf
	v_add_f32_dpp v141, v141, v141 quad_perm:[2,3,0,1] row_mask:0xf bank_mask:0xf
	v_add_f32_dpp v138, v138, v138 row_half_mirror row_mask:0xf bank_mask:0xf
	v_add_f32_dpp v139, v139, v139 row_half_mirror row_mask:0xf bank_mask:0xf
	v_add_f32_dpp v140, v140, v140 row_half_mirror row_mask:0xf bank_mask:0xf
	v_add_f32_dpp v141, v141, v141 row_half_mirror row_mask:0xf bank_mask:0xf
	v_add_f32_dpp v138, v138, v138 row_mirror row_mask:0xf bank_mask:0xf
	v_add_f32_dpp v139, v139, v139 row_mirror row_mask:0xf bank_mask:0xf
	v_add_f32_dpp v140, v140, v140 row_mirror row_mask:0xf bank_mask:0xf
	v_add_f32_dpp v141, v141, v141 row_mirror row_mask:0xf bank_mask:0xf
	v_add_f32_dpp v138, v138, v138 row_bcast:15 row_mask:0xa bank_mask:0xf
	v_add_f32_dpp v139, v139, v139 row_bcast:15 row_mask:0xa bank_mask:0xf
	v_add_f32_dpp v140, v140, v140 row_bcast:15 row_mask:0xa bank_mask:0xf
	v_add_f32_dpp v141, v141, v141 row_bcast:15 row_mask:0xa bank_mask:0xf
	s_mov_b32 exec_lo, 0x10000
	s_mov_b32 exec_hi, 0x10000
	ds_write_b32 v132, v138 offset:224
	ds_write_b32 v132, v139 offset:228
	ds_write_b32 v132, v140 offset:232
	ds_write_b32 v132, v141 offset:236
	s_mov_b64 exec, -1
